# GEMM K-loops: loader delay s_sleep 2 + MFMA segment head/tail trimmed (s_setprio moved outside the barriers, duplicate lgkmcnt(0) removed); on top of v12
# baseline (speedup 1.0000x reference)
; #define PG8_STAGE(bufoff, gbase, voff) do { _Pragma("unroll") for (int _i = 0; _i < 2; ++_i) \
;         __builtin_amdgcn_global_load_lds((const unsigned*)((const char*)(gbase) + (voff)[_i]), (PG8_LAS unsigned*)(lds + (bufoff) + ldsw + _i * 8192), 16, 0, 0); } while (0)
; #define PG8_LDA(dst, b, h) do { _Pragma("unroll") for (int m = 0; m < 4; ++m) _Pragma("unroll") for (int k = 0; k < 2; ++k) dst[m][k] = *(const PG8_LAS bf16x8*)(lds + PG8_SA(b, h) + aoff + m * 2048 + k * 1024); } while (0)
; #define PG8_LDB(dst, b, h) do { _Pragma("unroll") for (int n = 0; n < 2; ++n) _Pragma("unroll") for (int k = 0; k < 2; ++k) dst[n][k] = *(const PG8_LAS bf16x8*)(lds + PG8_SB(b, h) + boff + n * 2048 + k * 1024); } while (0)
; template <class Epi, class Sched, bool ALIGN_EPI = false, bool SP2 = false>
; __device__ __forceinline__ void gemm_phase(PG8_LAS unsigned char* lds, const Gemm g, const Sched& S, const Epi& E) {
;     ...
;         for (int t = 0; t < nt; t += 2) {
;             const bool last = (t == nt - 2);
;             const char* a1 = cA + (size_t)(t + 1) * kstep;
;             const char* a2 = last ? nA : cA + (size_t)(t + 2) * kstep; const char* b2 = last ? nB : cB + (size_t)(t + 2) * kstep;
;             const char* a3 = a2 + kstep; const char* b3 = b2 + kstep;
;             if (last && has_next) S.a_ready(nxt);
;             if constexpr (SP2) {
;             PG8_LDB(B0, 0, 0); PG8_LDB(B1, 0, 1); PG8_SCHED; PG8_LDA(At, 0, 0); PG8_STAGE(PG8_SA(1, 1), a1 + hstep, voffA);
;             PG8_WAIT_V(8); PG8_WAIT_L(0); PG8_BAR; PG8_MMA(0, 0, At, B0); PG8_MMA(0, 1, At, B1); PG8_BAR; PG8_SCHED;
;             PG8_LDA(At, 0, 1); PG8_STAGE(PG8_SB(0, 0), b2, voffB); PG8_STAGE(PG8_SB(0, 1), b2 + hstep, voffB); PG8_STAGE(PG8_SA(0, 0), a2, voffA);
;             PG8_WAIT_V(8); PG8_WAIT_L(0); PG8_BAR; PG8_MMA(1, 0, At, B0); PG8_MMA(1, 1, At, B1); PG8_BAR; PG8_SCHED;
;             PG8_LDB(B0, 1, 0); PG8_LDB(B1, 1, 1); PG8_SCHED; PG8_LDA(At, 1, 0); PG8_STAGE(PG8_SA(0, 1), a2 + hstep, voffA);
;             PG8_WAIT_V(8); PG8_WAIT_L(0); PG8_BAR; PG8_MMA(0, 0, At, B0); PG8_MMA(0, 1, At, B1); PG8_BAR; PG8_SCHED;
;             PG8_LDA(At, 1, 1); PG8_STAGE(PG8_SB(1, 0), b3, voffB); PG8_STAGE(PG8_SB(1, 1), b3 + hstep, voffB); PG8_STAGE(PG8_SA(1, 0), a3, voffA);
;             PG8_WAIT_V(8); PG8_WAIT_L(0); PG8_BAR; PG8_MMA(1, 0, At, B0); PG8_MMA(1, 1, At, B1); PG8_BAR; PG8_SCHED;
.LBB0_93:
	ds_read_b128 v[146:149], v153
	ds_read_b128 v[156:159], v153 offset:1024
	ds_read_b128 v[160:163], v153 offset:2048
	ds_read_b128 v[164:167], v153 offset:3072
	ds_read_b128 v[168:171], v154
	ds_read_b128 v[172:175], v154 offset:1024
	ds_read_b128 v[176:179], v154 offset:2048
	ds_read_b128 v[184:187], v154 offset:3072
	s_add_u32 s48, s44, 0xfff80080
	s_addc_u32 s49, s45, -1
	s_cmp_eq_u32 s89, 28
	s_cselect_b32 s59, s25, s49
	s_cselect_b32 s58, s84, s48
	s_cselect_b32 s49, s13, s87
	s_cselect_b32 s48, s85, s86
	v_lshl_add_u64 v[180:181], s[44:45], 0, v[136:137]
	s_add_i32 m0, s35, 0xc000
	ds_read_b128 v[188:191], v155
	ds_read_b128 v[192:195], v155 offset:1024
	ds_read_b128 v[196:199], v155 offset:2048
	ds_read_b128 v[200:203], v155 offset:3072
	ds_read_b128 v[204:207], v155 offset:4096
	ds_read_b128 v[208:211], v155 offset:5120
	ds_read_b128 v[212:215], v155 offset:6144
	ds_read_b128 v[216:219], v155 offset:7168
	global_load_lds_dwordx4 v[180:181], off
	v_lshl_add_u64 v[180:181], s[44:45], 0, v[138:139]
	s_add_i32 m0, s35, 0xe000
	s_nop 0
	global_load_lds_dwordx4 v[180:181], off
	s_waitcnt vmcnt(8)
	s_waitcnt lgkmcnt(0)
	s_setprio 1
	s_barrier
	v_mfma_f32_16x16x32_bf16 v[124:127], v[146:149], v[188:191], v[124:127]
	v_mfma_f32_16x16x32_bf16 v[120:123], v[160:163], v[188:191], v[120:123]
	v_mfma_f32_16x16x32_bf16 v[108:111], v[146:149], v[196:199], v[108:111]
	v_mfma_f32_16x16x32_bf16 v[104:107], v[160:163], v[196:199], v[104:107]
	v_mfma_f32_16x16x32_bf16 v[92:95], v[146:149], v[204:207], v[92:95]
	v_mfma_f32_16x16x32_bf16 v[88:91], v[160:163], v[204:207], v[88:91]
	v_mfma_f32_16x16x32_bf16 v[76:79], v[146:149], v[212:215], v[76:79]
	v_mfma_f32_16x16x32_bf16 v[72:75], v[160:163], v[212:215], v[72:75]
	v_mfma_f32_16x16x32_bf16 v[124:127], v[156:159], v[192:195], v[124:127]
	v_mfma_f32_16x16x32_bf16 v[120:123], v[164:167], v[192:195], v[120:123]
	v_mfma_f32_16x16x32_bf16 v[108:111], v[156:159], v[200:203], v[108:111]
	v_mfma_f32_16x16x32_bf16 v[104:107], v[164:167], v[200:203], v[104:107]
	v_mfma_f32_16x16x32_bf16 v[92:95], v[156:159], v[208:211], v[92:95]
	v_mfma_f32_16x16x32_bf16 v[88:91], v[164:167], v[208:211], v[88:91]
	v_mfma_f32_16x16x32_bf16 v[76:79], v[156:159], v[216:219], v[76:79]
	v_mfma_f32_16x16x32_bf16 v[72:75], v[164:167], v[216:219], v[72:75]
	s_setprio 0
	s_setprio 1
	v_mfma_f32_16x16x32_bf16 v[116:119], v[168:171], v[188:191], v[116:119]
	v_mfma_f32_16x16x32_bf16 v[112:115], v[176:179], v[188:191], v[112:115]
	v_mfma_f32_16x16x32_bf16 v[100:103], v[168:171], v[196:199], v[100:103]
	v_mfma_f32_16x16x32_bf16 v[96:99], v[176:179], v[196:199], v[96:99]
	v_mfma_f32_16x16x32_bf16 v[84:87], v[168:171], v[204:207], v[84:87]
	v_mfma_f32_16x16x32_bf16 v[80:83], v[176:179], v[204:207], v[80:83]
	v_mfma_f32_16x16x32_bf16 v[68:71], v[168:171], v[212:215], v[68:71]
	v_mfma_f32_16x16x32_bf16 v[64:67], v[176:179], v[212:215], v[64:67]
	v_mfma_f32_16x16x32_bf16 v[116:119], v[172:175], v[192:195], v[116:119]
	v_mfma_f32_16x16x32_bf16 v[112:115], v[184:187], v[192:195], v[112:115]
	v_mfma_f32_16x16x32_bf16 v[100:103], v[172:175], v[200:203], v[100:103]
	v_mfma_f32_16x16x32_bf16 v[96:99], v[184:187], v[200:203], v[96:99]
	v_mfma_f32_16x16x32_bf16 v[84:87], v[172:175], v[208:211], v[84:87]
	v_mfma_f32_16x16x32_bf16 v[80:83], v[184:187], v[208:211], v[80:83]
	v_mfma_f32_16x16x32_bf16 v[68:71], v[172:175], v[216:219], v[68:71]
	v_mfma_f32_16x16x32_bf16 v[64:67], v[184:187], v[216:219], v[64:67]
	s_barrier
	s_setprio 0
	s_sleep 2
	s_add_i32 s90, s66, s29
	v_lshl_add_u64 v[180:181], s[48:49], 0, v[130:131]
	s_mov_b32 m0, s90
	ds_read_b128 v[188:191], v155 offset:16384
	ds_read_b128 v[192:195], v155 offset:17408
	ds_read_b128 v[196:199], v155 offset:18432
	ds_read_b128 v[200:203], v155 offset:19456
	ds_read_b128 v[204:207], v155 offset:20480
	ds_read_b128 v[208:211], v155 offset:21504
	ds_read_b128 v[212:215], v155 offset:22528
	ds_read_b128 v[216:219], v155 offset:23552
	global_load_lds_dwordx4 v[180:181], off
	s_add_i32 m0, s90, 0x2000
	s_add_u32 s92, s48, 0x80000
	v_lshl_add_u64 v[220:221], s[48:49], 0, v[134:135]
	s_addc_u32 s93, s49, 0
	s_add_i32 s90, s67, s29
	global_load_lds_dwordx4 v[220:221], off
	v_lshl_add_u64 v[222:223], s[92:93], 0, v[130:131]
	s_mov_b32 m0, s90
	v_lshl_add_u64 v[224:225], s[58:59], 0, v[132:133]
	global_load_lds_dwordx4 v[222:223], off
	v_lshl_add_u64 v[222:223], s[92:93], 0, v[134:135]
	s_add_i32 m0, s90, 0x2000
	s_nop 0
	global_load_lds_dwordx4 v[222:223], off
	v_lshl_add_u64 v[222:223], s[58:59], 0, v[128:129]
	s_mov_b32 m0, s35
	s_nop 0
	global_load_lds_dwordx4 v[222:223], off
	s_mov_b32 m0, s43
	s_nop 0
	global_load_lds_dwordx4 v[224:225], off
	s_waitcnt vmcnt(8)
	s_waitcnt lgkmcnt(0)
	s_setprio 1
	s_barrier
; #define PG8_STAGE(bufoff, gbase, voff) do { _Pragma("unroll") for (int _i = 0; _i < 2; ++_i) \
;         __builtin_amdgcn_global_load_lds((const unsigned*)((const char*)(gbase) + (voff)[_i]), (PG8_LAS unsigned*)(lds + (bufoff) + ldsw + _i * 8192), 16, 0, 0); } while (0)
; #define PG8_LDA(dst, b, h) do { _Pragma("unroll") for (int m = 0; m < 4; ++m) _Pragma("unroll") for (int k = 0; k < 2; ++k) dst[m][k] = *(const PG8_LAS bf16x8*)(lds + PG8_SA(b, h) + aoff + m * 2048 + k * 1024); } while (0)
; #define PG8_LDB(dst, b, h) do { _Pragma("unroll") for (int n = 0; n < 2; ++n) _Pragma("unroll") for (int k = 0; k < 2; ++k) dst[n][k] = *(const PG8_LAS bf16x8*)(lds + PG8_SB(b, h) + boff + n * 2048 + k * 1024); } while (0)
; #define PG8_MMA(ai, bj, At, Bt) do { __builtin_amdgcn_s_setprio(1); _Pragma("unroll") for (int m = 0; m < 4; ++m) _Pragma("unroll") for (int n = 0; n < 2; ++n) _Pragma("unroll") for (int k = 0; k < 2; ++k) \
;         acc[ai][bj][m][n] = __builtin_amdgcn_mfma_f32_16x16x32_bf16(Bt[n][k], At[m][k], acc[ai][bj][m][n], 0, 0, 0); __builtin_amdgcn_s_setprio(0); } while (0)
; #define PG8_BAR __builtin_amdgcn_s_barrier()
; template <class Epi, class Sched, bool ALIGN_EPI = false, bool SP2 = false>
; __device__ __forceinline__ void gemm_phase(PG8_LAS unsigned char* lds, const Gemm g, const Sched& S, const Epi& E) {
;     ...
;             if constexpr (SP2) {
;             PG8_LDB(B0, 0, 0); PG8_LDB(B1, 0, 1); PG8_SCHED; PG8_LDA(At, 0, 0); PG8_STAGE(PG8_SA(1, 1), a1 + hstep, voffA);
;             PG8_WAIT_V(8); PG8_WAIT_L(0); PG8_BAR; PG8_MMA(0, 0, At, B0); PG8_MMA(0, 1, At, B1); PG8_BAR; PG8_SCHED;
;             PG8_LDA(At, 0, 1); PG8_STAGE(PG8_SB(0, 0), b2, voffB); PG8_STAGE(PG8_SB(0, 1), b2 + hstep, voffB); PG8_STAGE(PG8_SA(0, 0), a2, voffA);
;             PG8_WAIT_V(8); PG8_WAIT_L(0); PG8_BAR; PG8_MMA(1, 0, At, B0); PG8_MMA(1, 1, At, B1); PG8_BAR; PG8_SCHED;
;             PG8_LDB(B0, 1, 0); PG8_LDB(B1, 1, 1); PG8_SCHED; PG8_LDA(At, 1, 0); PG8_STAGE(PG8_SA(0, 1), a2 + hstep, voffA);
;             PG8_WAIT_V(8); PG8_WAIT_L(0); PG8_BAR; PG8_MMA(0, 0, At, B0); PG8_MMA(0, 1, At, B1); PG8_BAR; PG8_SCHED;
;             PG8_LDA(At, 1, 1); PG8_STAGE(PG8_SB(1, 0), b3, voffB); PG8_STAGE(PG8_SB(1, 1), b3 + hstep, voffB); PG8_STAGE(PG8_SA(1, 0), a3, voffA);
;             PG8_WAIT_V(8); PG8_WAIT_L(0); PG8_BAR; PG8_MMA(1, 0, At, B0); PG8_MMA(1, 1, At, B1); PG8_BAR; PG8_SCHED;
	v_mfma_f32_16x16x32_bf16 v[60:63], v[146:149], v[188:191], v[60:63]
	v_mfma_f32_16x16x32_bf16 v[56:59], v[160:163], v[188:191], v[56:59]
	v_mfma_f32_16x16x32_bf16 v[44:47], v[146:149], v[196:199], v[44:47]
	v_mfma_f32_16x16x32_bf16 v[40:43], v[160:163], v[196:199], v[40:43]
	v_mfma_f32_16x16x32_bf16 v[28:31], v[146:149], v[204:207], v[28:31]
	v_mfma_f32_16x16x32_bf16 v[24:27], v[160:163], v[204:207], v[24:27]
	v_mfma_f32_16x16x32_bf16 v[12:15], v[146:149], v[212:215], v[12:15]
	v_mfma_f32_16x16x32_bf16 v[8:11], v[160:163], v[212:215], v[8:11]
	v_mfma_f32_16x16x32_bf16 v[60:63], v[156:159], v[192:195], v[60:63]
	v_mfma_f32_16x16x32_bf16 v[56:59], v[164:167], v[192:195], v[56:59]
	v_mfma_f32_16x16x32_bf16 v[44:47], v[156:159], v[200:203], v[44:47]
	v_mfma_f32_16x16x32_bf16 v[40:43], v[164:167], v[200:203], v[40:43]
	v_mfma_f32_16x16x32_bf16 v[28:31], v[156:159], v[208:211], v[28:31]
	v_mfma_f32_16x16x32_bf16 v[24:27], v[164:167], v[208:211], v[24:27]
	v_mfma_f32_16x16x32_bf16 v[12:15], v[156:159], v[216:219], v[12:15]
	v_mfma_f32_16x16x32_bf16 v[8:11], v[164:167], v[216:219], v[8:11]
	s_setprio 0
	s_setprio 1
	v_mfma_f32_16x16x32_bf16 v[52:55], v[168:171], v[188:191], v[52:55]
	v_mfma_f32_16x16x32_bf16 v[48:51], v[176:179], v[188:191], v[48:51]
	v_mfma_f32_16x16x32_bf16 v[36:39], v[168:171], v[196:199], v[36:39]
	v_mfma_f32_16x16x32_bf16 v[32:35], v[176:179], v[196:199], v[32:35]
	v_mfma_f32_16x16x32_bf16 v[20:23], v[168:171], v[204:207], v[20:23]
	v_mfma_f32_16x16x32_bf16 v[16:19], v[176:179], v[204:207], v[16:19]
	v_mfma_f32_16x16x32_bf16 v[4:7], v[168:171], v[212:215], v[4:7]
	v_mfma_f32_16x16x32_bf16 v[0:3], v[176:179], v[212:215], v[0:3]
	v_mfma_f32_16x16x32_bf16 v[52:55], v[172:175], v[192:195], v[52:55]
	v_mfma_f32_16x16x32_bf16 v[48:51], v[184:187], v[192:195], v[48:51]
	v_mfma_f32_16x16x32_bf16 v[36:39], v[172:175], v[200:203], v[36:39]
	v_mfma_f32_16x16x32_bf16 v[32:35], v[184:187], v[200:203], v[32:35]
	v_mfma_f32_16x16x32_bf16 v[20:23], v[172:175], v[208:211], v[20:23]
	v_mfma_f32_16x16x32_bf16 v[16:19], v[184:187], v[208:211], v[16:19]
	v_mfma_f32_16x16x32_bf16 v[4:7], v[172:175], v[216:219], v[4:7]
	v_mfma_f32_16x16x32_bf16 v[0:3], v[184:187], v[216:219], v[0:3]
	s_barrier
	s_setprio 0
	s_sleep 2
	s_add_i32 s90, 0, 0x18000
	s_add_i32 s92, 0, 0x1c000
	v_add_u32_e32 v164, s90, v151
	v_add_u32_e32 v184, s92, v151
	ds_read_b128 v[146:149], v164
	ds_read_b128 v[156:159], v164 offset:1024
	ds_read_b128 v[160:163], v164 offset:2048
	ds_read_b128 v[164:167], v164 offset:3072
	ds_read_b128 v[168:171], v184
	ds_read_b128 v[172:175], v184 offset:1024
	ds_read_b128 v[176:179], v184 offset:2048
	ds_read_b128 v[184:187], v184 offset:3072
	s_add_u32 s58, s58, 0x80000
	s_addc_u32 s59, s59, 0
	s_mov_b32 m0, s60
	v_lshl_add_u64 v[226:227], s[58:59], 0, v[128:129]
	ds_read_b128 v[188:191], v155 offset:32768
	ds_read_b128 v[192:195], v155 offset:33792
	ds_read_b128 v[196:199], v155 offset:34816
	ds_read_b128 v[200:203], v155 offset:35840
	ds_read_b128 v[204:207], v155 offset:36864
	ds_read_b128 v[208:211], v155 offset:37888
	ds_read_b128 v[212:215], v155 offset:38912
	ds_read_b128 v[216:219], v155 offset:39936
	global_load_lds_dwordx4 v[226:227], off
	v_lshl_add_u64 v[226:227], s[58:59], 0, v[132:133]
	s_mov_b32 m0, s61
	s_nop 0
	global_load_lds_dwordx4 v[226:227], off
	s_waitcnt vmcnt(8)
	s_waitcnt lgkmcnt(0)
	s_setprio 1
	s_barrier
	v_mfma_f32_16x16x32_bf16 v[124:127], v[146:149], v[188:191], v[124:127]
	v_mfma_f32_16x16x32_bf16 v[120:123], v[160:163], v[188:191], v[120:123]
	v_mfma_f32_16x16x32_bf16 v[108:111], v[146:149], v[196:199], v[108:111]
	v_mfma_f32_16x16x32_bf16 v[104:107], v[160:163], v[196:199], v[104:107]
	v_mfma_f32_16x16x32_bf16 v[92:95], v[146:149], v[204:207], v[92:95]
	v_mfma_f32_16x16x32_bf16 v[88:91], v[160:163], v[204:207], v[88:91]
	v_mfma_f32_16x16x32_bf16 v[76:79], v[146:149], v[212:215], v[76:79]
	v_mfma_f32_16x16x32_bf16 v[72:75], v[160:163], v[212:215], v[72:75]
	v_mfma_f32_16x16x32_bf16 v[124:127], v[156:159], v[192:195], v[124:127]
	v_mfma_f32_16x16x32_bf16 v[120:123], v[164:167], v[192:195], v[120:123]
	v_mfma_f32_16x16x32_bf16 v[108:111], v[156:159], v[200:203], v[108:111]
	v_mfma_f32_16x16x32_bf16 v[104:107], v[164:167], v[200:203], v[104:107]
	v_mfma_f32_16x16x32_bf16 v[92:95], v[156:159], v[208:211], v[92:95]
	v_mfma_f32_16x16x32_bf16 v[88:91], v[164:167], v[208:211], v[88:91]
	v_mfma_f32_16x16x32_bf16 v[76:79], v[156:159], v[216:219], v[76:79]
	v_mfma_f32_16x16x32_bf16 v[72:75], v[164:167], v[216:219], v[72:75]
	s_setprio 0
	s_setprio 1
	v_mfma_f32_16x16x32_bf16 v[116:119], v[168:171], v[188:191], v[116:119]
	v_mfma_f32_16x16x32_bf16 v[112:115], v[176:179], v[188:191], v[112:115]
	v_mfma_f32_16x16x32_bf16 v[100:103], v[168:171], v[196:199], v[100:103]
	v_mfma_f32_16x16x32_bf16 v[96:99], v[176:179], v[196:199], v[96:99]
	v_mfma_f32_16x16x32_bf16 v[84:87], v[168:171], v[204:207], v[84:87]
	v_mfma_f32_16x16x32_bf16 v[80:83], v[176:179], v[204:207], v[80:83]
	v_mfma_f32_16x16x32_bf16 v[68:71], v[168:171], v[212:215], v[68:71]
	v_mfma_f32_16x16x32_bf16 v[64:67], v[176:179], v[212:215], v[64:67]
	v_mfma_f32_16x16x32_bf16 v[116:119], v[172:175], v[192:195], v[116:119]
	v_mfma_f32_16x16x32_bf16 v[112:115], v[184:187], v[192:195], v[112:115]
	v_mfma_f32_16x16x32_bf16 v[100:103], v[172:175], v[200:203], v[100:103]
	v_mfma_f32_16x16x32_bf16 v[96:99], v[184:187], v[200:203], v[96:99]
	v_mfma_f32_16x16x32_bf16 v[84:87], v[172:175], v[208:211], v[84:87]
	v_mfma_f32_16x16x32_bf16 v[80:83], v[184:187], v[208:211], v[80:83]
	v_mfma_f32_16x16x32_bf16 v[68:71], v[172:175], v[216:219], v[68:71]
	v_mfma_f32_16x16x32_bf16 v[64:67], v[184:187], v[216:219], v[64:67]
	s_barrier
; #define PG8_STAGE(bufoff, gbase, voff) do { _Pragma("unroll") for (int _i = 0; _i < 2; ++_i) \
;         __builtin_amdgcn_global_load_lds((const unsigned*)((const char*)(gbase) + (voff)[_i]), (PG8_LAS unsigned*)(lds + (bufoff) + ldsw + _i * 8192), 16, 0, 0); } while (0)
; #define PG8_LDA(dst, b, h) do { _Pragma("unroll") for (int m = 0; m < 4; ++m) _Pragma("unroll") for (int k = 0; k < 2; ++k) dst[m][k] = *(const PG8_LAS bf16x8*)(lds + PG8_SA(b, h) + aoff + m * 2048 + k * 1024); } while (0)
; #define PG8_LDB(dst, b, h) do { _Pragma("unroll") for (int n = 0; n < 2; ++n) _Pragma("unroll") for (int k = 0; k < 2; ++k) dst[n][k] = *(const PG8_LAS bf16x8*)(lds + PG8_SB(b, h) + boff + n * 2048 + k * 1024); } while (0)
; #define PG8_MMA(ai, bj, At, Bt) do { __builtin_amdgcn_s_setprio(1); _Pragma("unroll") for (int m = 0; m < 4; ++m) _Pragma("unroll") for (int n = 0; n < 2; ++n) _Pragma("unroll") for (int k = 0; k < 2; ++k) \
;         acc[ai][bj][m][n] = __builtin_amdgcn_mfma_f32_16x16x32_bf16(Bt[n][k], At[m][k], acc[ai][bj][m][n], 0, 0, 0); __builtin_amdgcn_s_setprio(0); } while (0)
; template <class Epi, class Sched, bool ALIGN_EPI = false, bool SP2 = false>
; __device__ __forceinline__ void gemm_phase(PG8_LAS unsigned char* lds, const Gemm g, const Sched& S, const Epi& E) {
;     ...
;         for (int t = 0; t < nt; t += 2) {
;     ...
;             if constexpr (SP2) {
;             PG8_LDB(B0, 0, 0); PG8_LDB(B1, 0, 1); PG8_SCHED; PG8_LDA(At, 0, 0); PG8_STAGE(PG8_SA(1, 1), a1 + hstep, voffA);
;             PG8_WAIT_V(8); PG8_WAIT_L(0); PG8_BAR; PG8_MMA(0, 0, At, B0); PG8_MMA(0, 1, At, B1); PG8_BAR; PG8_SCHED;
;             PG8_LDA(At, 0, 1); PG8_STAGE(PG8_SB(0, 0), b2, voffB); PG8_STAGE(PG8_SB(0, 1), b2 + hstep, voffB); PG8_STAGE(PG8_SA(0, 0), a2, voffA);
;             PG8_WAIT_V(8); PG8_WAIT_L(0); PG8_BAR; PG8_MMA(1, 0, At, B0); PG8_MMA(1, 1, At, B1); PG8_BAR; PG8_SCHED;
;             PG8_LDB(B0, 1, 0); PG8_LDB(B1, 1, 1); PG8_SCHED; PG8_LDA(At, 1, 0); PG8_STAGE(PG8_SA(0, 1), a2 + hstep, voffA);
;             PG8_WAIT_V(8); PG8_WAIT_L(0); PG8_BAR; PG8_MMA(0, 0, At, B0); PG8_MMA(0, 1, At, B1); PG8_BAR; PG8_SCHED;
;             PG8_LDA(At, 1, 1); PG8_STAGE(PG8_SB(1, 0), b3, voffB); PG8_STAGE(PG8_SB(1, 1), b3 + hstep, voffB); PG8_STAGE(PG8_SA(1, 0), a3, voffA);
;             PG8_WAIT_V(8); PG8_WAIT_L(0); PG8_BAR; PG8_MMA(1, 0, At, B0); PG8_MMA(1, 1, At, B1); PG8_BAR; PG8_SCHED;
	s_setprio 0
	s_sleep 2
	s_add_i32 s58, s90, s29
	v_lshl_add_u64 v[180:181], v[180:181], 0, s[8:9]
	s_mov_b32 m0, s58
	ds_read_b128 v[188:191], v155 offset:49152
	ds_read_b128 v[192:195], v155 offset:50176
	ds_read_b128 v[196:199], v155 offset:51200
	ds_read_b128 v[200:203], v155 offset:52224
	ds_read_b128 v[204:207], v155 offset:53248
	ds_read_b128 v[208:211], v155 offset:54272
	ds_read_b128 v[212:215], v155 offset:55296
	ds_read_b128 v[216:219], v155 offset:56320
	global_load_lds_dwordx4 v[180:181], off
	s_add_i32 m0, s58, 0x2000
	s_add_u32 s48, s48, 0x80080
	v_lshl_add_u64 v[180:181], v[220:221], 0, s[8:9]
	s_addc_u32 s49, s49, 0
	s_add_i32 s58, s92, s29
	global_load_lds_dwordx4 v[180:181], off
	v_lshl_add_u64 v[180:181], s[48:49], 0, v[130:131]
	s_mov_b32 m0, s58
	s_nop 0
	global_load_lds_dwordx4 v[180:181], off
	v_lshl_add_u64 v[180:181], s[48:49], 0, v[134:135]
	s_add_i32 m0, s58, 0x2000
	s_nop 0
	global_load_lds_dwordx4 v[180:181], off
	v_lshl_add_u64 v[180:181], v[222:223], 0, s[8:9]
	s_mov_b32 m0, s64
	s_nop 0
	global_load_lds_dwordx4 v[180:181], off
	v_lshl_add_u64 v[180:181], v[224:225], 0, s[8:9]
	s_mov_b32 m0, s65
	s_nop 0
	global_load_lds_dwordx4 v[180:181], off
	s_waitcnt vmcnt(8)
	s_waitcnt lgkmcnt(0)
	s_setprio 1
	s_barrier
	v_mfma_f32_16x16x32_bf16 v[60:63], v[146:149], v[188:191], v[60:63]
	v_mfma_f32_16x16x32_bf16 v[56:59], v[160:163], v[188:191], v[56:59]
	v_mfma_f32_16x16x32_bf16 v[44:47], v[146:149], v[196:199], v[44:47]
	v_mfma_f32_16x16x32_bf16 v[40:43], v[160:163], v[196:199], v[40:43]
	v_mfma_f32_16x16x32_bf16 v[28:31], v[146:149], v[204:207], v[28:31]
	v_mfma_f32_16x16x32_bf16 v[24:27], v[160:163], v[204:207], v[24:27]
	v_mfma_f32_16x16x32_bf16 v[12:15], v[146:149], v[212:215], v[12:15]
	v_mfma_f32_16x16x32_bf16 v[8:11], v[160:163], v[212:215], v[8:11]
	v_mfma_f32_16x16x32_bf16 v[60:63], v[156:159], v[192:195], v[60:63]
	v_mfma_f32_16x16x32_bf16 v[56:59], v[164:167], v[192:195], v[56:59]
	v_mfma_f32_16x16x32_bf16 v[44:47], v[156:159], v[200:203], v[44:47]
	v_mfma_f32_16x16x32_bf16 v[40:43], v[164:167], v[200:203], v[40:43]
	v_mfma_f32_16x16x32_bf16 v[28:31], v[156:159], v[208:211], v[28:31]
	v_mfma_f32_16x16x32_bf16 v[24:27], v[164:167], v[208:211], v[24:27]
	v_mfma_f32_16x16x32_bf16 v[12:15], v[156:159], v[216:219], v[12:15]
	v_mfma_f32_16x16x32_bf16 v[8:11], v[164:167], v[216:219], v[8:11]
	s_setprio 0
	s_setprio 1
	v_mfma_f32_16x16x32_bf16 v[52:55], v[168:171], v[188:191], v[52:55]
	v_mfma_f32_16x16x32_bf16 v[48:51], v[176:179], v[188:191], v[48:51]
	v_mfma_f32_16x16x32_bf16 v[36:39], v[168:171], v[196:199], v[36:39]
	v_mfma_f32_16x16x32_bf16 v[32:35], v[176:179], v[196:199], v[32:35]
	v_mfma_f32_16x16x32_bf16 v[20:23], v[168:171], v[204:207], v[20:23]
	v_mfma_f32_16x16x32_bf16 v[16:19], v[176:179], v[204:207], v[16:19]
	v_mfma_f32_16x16x32_bf16 v[4:7], v[168:171], v[212:215], v[4:7]
	v_mfma_f32_16x16x32_bf16 v[0:3], v[176:179], v[212:215], v[0:3]
	v_mfma_f32_16x16x32_bf16 v[52:55], v[172:175], v[192:195], v[52:55]
	v_mfma_f32_16x16x32_bf16 v[48:51], v[184:187], v[192:195], v[48:51]
	v_mfma_f32_16x16x32_bf16 v[36:39], v[172:175], v[200:203], v[36:39]
	v_mfma_f32_16x16x32_bf16 v[32:35], v[184:187], v[200:203], v[32:35]
	v_mfma_f32_16x16x32_bf16 v[20:23], v[172:175], v[208:211], v[20:23]
	v_mfma_f32_16x16x32_bf16 v[16:19], v[184:187], v[208:211], v[16:19]
	v_mfma_f32_16x16x32_bf16 v[4:7], v[172:175], v[216:219], v[4:7]
	v_mfma_f32_16x16x32_bf16 v[0:3], v[184:187], v[216:219], v[0:3]
	s_barrier
	s_setprio 0
	s_sleep 2
	s_add_i32 s89, s89, 2
	s_add_u32 s44, s44, 0x100
	s_addc_u32 s45, s45, 0
	s_add_u32 s86, s86, 0x100
	s_addc_u32 s87, s87, 0
	s_cmp_gt_u32 s89, 29
	s_cbranch_scc0 .LBB0_93
	s_and_b64 vcc, exec, s[10:11]
	s_cbranch_vccz .LBB0_96
	s_barrier

; #define PG8_STAGE(bufoff, gbase, voff) do { _Pragma("unroll") for (int _i = 0; _i < 2; ++_i) \
;         __builtin_amdgcn_global_load_lds((const unsigned*)((const char*)(gbase) + (voff)[_i]), (PG8_LAS unsigned*)(lds + (bufoff) + ldsw + _i * 8192), 16, 0, 0); } while (0)
; #define PG8_LDA(dst, b, h) do { _Pragma("unroll") for (int m = 0; m < 4; ++m) _Pragma("unroll") for (int k = 0; k < 2; ++k) dst[m][k] = *(const PG8_LAS bf16x8*)(lds + PG8_SA(b, h) + aoff + m * 2048 + k * 1024); } while (0)
; #define PG8_LDB(dst, b, h) do { _Pragma("unroll") for (int n = 0; n < 2; ++n) _Pragma("unroll") for (int k = 0; k < 2; ++k) dst[n][k] = *(const PG8_LAS bf16x8*)(lds + PG8_SB(b, h) + boff + n * 2048 + k * 1024); } while (0)
; template <class Epi, class Sched, bool ALIGN_EPI = false, bool SP2 = false>
; __device__ __forceinline__ void gemm_phase(PG8_LAS unsigned char* lds, const Gemm g, const Sched& S, const Epi& E) {
;     ...
;         for (int t = 0; t < nt; t += 2) {
;             const bool last = (t == nt - 2);
;             const char* a1 = cA + (size_t)(t + 1) * kstep;
;             const char* a2 = last ? nA : cA + (size_t)(t + 2) * kstep; const char* b2 = last ? nB : cB + (size_t)(t + 2) * kstep;
;             const char* a3 = a2 + kstep; const char* b3 = b2 + kstep;
;             if (last && has_next) S.a_ready(nxt);
;             if constexpr (SP2) {
;             PG8_LDB(B0, 0, 0); PG8_LDB(B1, 0, 1); PG8_SCHED; PG8_LDA(At, 0, 0); PG8_STAGE(PG8_SA(1, 1), a1 + hstep, voffA);
;             PG8_WAIT_V(8); PG8_WAIT_L(0); PG8_BAR; PG8_MMA(0, 0, At, B0); PG8_MMA(0, 1, At, B1); PG8_BAR; PG8_SCHED;
;             PG8_LDA(At, 0, 1); PG8_STAGE(PG8_SB(0, 0), b2, voffB); PG8_STAGE(PG8_SB(0, 1), b2 + hstep, voffB); PG8_STAGE(PG8_SA(0, 0), a2, voffA);
;             PG8_WAIT_V(8); PG8_WAIT_L(0); PG8_BAR; PG8_MMA(1, 0, At, B0); PG8_MMA(1, 1, At, B1); PG8_BAR; PG8_SCHED;
;             PG8_LDB(B0, 1, 0); PG8_LDB(B1, 1, 1); PG8_SCHED; PG8_LDA(At, 1, 0); PG8_STAGE(PG8_SA(0, 1), a2 + hstep, voffA);
;             PG8_WAIT_V(8); PG8_WAIT_L(0); PG8_BAR; PG8_MMA(0, 0, At, B0); PG8_MMA(0, 1, At, B1); PG8_BAR; PG8_SCHED;
;             PG8_LDA(At, 1, 1); PG8_STAGE(PG8_SB(1, 0), b3, voffB); PG8_STAGE(PG8_SB(1, 1), b3 + hstep, voffB); PG8_STAGE(PG8_SA(1, 0), a3, voffA);
;             PG8_WAIT_V(8); PG8_WAIT_L(0); PG8_BAR; PG8_MMA(1, 0, At, B0); PG8_MMA(1, 1, At, B1); PG8_BAR; PG8_SCHED;
.LBB0_121:
	ds_read_b128 v[174:177], v166
	ds_read_b128 v[178:181], v166 offset:1024
	ds_read_b128 v[190:193], v166 offset:2048
	ds_read_b128 v[194:197], v166 offset:3072
	ds_read_b128 v[198:201], v167
	ds_read_b128 v[202:205], v167 offset:1024
	ds_read_b128 v[206:209], v167 offset:2048
	ds_read_b128 v[210:213], v167 offset:3072
	s_add_u32 s46, s10, 0x100
	s_addc_u32 s47, s11, 0
	s_add_u32 s58, s90, s10
	s_addc_u32 s59, s92, s11
	s_cmpk_eq_i32 s93, 0x54
	s_cselect_b32 s60, s38, s58
	s_cselect_b32 s58, 0, s46
	s_cselect_b32 s61, s39, s59
	s_cselect_b32 s59, 0, s47
	s_add_u32 s58, s26, s58
	s_addc_u32 s59, s27, s59
	v_lshl_add_u64 v[246:247], v[142:143], 0, s[10:11]
	s_add_i32 m0, s3, 0xc000
	ds_read_b128 v[214:217], v168
	ds_read_b128 v[218:221], v168 offset:1024
	ds_read_b128 v[222:225], v168 offset:2048
	ds_read_b128 v[226:229], v168 offset:3072
	ds_read_b128 v[230:233], v168 offset:4096
	ds_read_b128 v[234:237], v168 offset:5120
	ds_read_b128 v[238:241], v168 offset:6144
	ds_read_b128 v[242:245], v168 offset:7168
	global_load_lds_dwordx4 v[246:247], off
	v_lshl_add_u64 v[246:247], v[146:147], 0, s[10:11]
	s_add_i32 m0, s3, 0xe000
	s_nop 0
	global_load_lds_dwordx4 v[246:247], off
	s_waitcnt vmcnt(8)
	s_waitcnt lgkmcnt(0)
	s_setprio 1
	s_barrier
	v_mfma_f32_16x16x32_bf16 v[56:59], v[174:177], v[214:217], v[56:59]
	v_mfma_f32_16x16x32_bf16 v[60:63], v[190:193], v[214:217], v[60:63]
	v_mfma_f32_16x16x32_bf16 v[76:79], v[174:177], v[222:225], v[76:79]
	v_mfma_f32_16x16x32_bf16 v[80:83], v[190:193], v[222:225], v[80:83]
	v_mfma_f32_16x16x32_bf16 v[96:99], v[174:177], v[230:233], v[96:99]
	v_mfma_f32_16x16x32_bf16 v[100:103], v[190:193], v[230:233], v[100:103]
	v_mfma_f32_16x16x32_bf16 v[116:119], v[174:177], v[238:241], v[116:119]
	v_mfma_f32_16x16x32_bf16 v[120:123], v[190:193], v[238:241], v[120:123]
	v_mfma_f32_16x16x32_bf16 v[56:59], v[178:181], v[218:221], v[56:59]
	v_mfma_f32_16x16x32_bf16 v[60:63], v[194:197], v[218:221], v[60:63]
	v_mfma_f32_16x16x32_bf16 v[76:79], v[178:181], v[226:229], v[76:79]
	v_mfma_f32_16x16x32_bf16 v[80:83], v[194:197], v[226:229], v[80:83]
	v_mfma_f32_16x16x32_bf16 v[96:99], v[178:181], v[234:237], v[96:99]
	v_mfma_f32_16x16x32_bf16 v[100:103], v[194:197], v[234:237], v[100:103]
	v_mfma_f32_16x16x32_bf16 v[116:119], v[178:181], v[242:245], v[116:119]
	v_mfma_f32_16x16x32_bf16 v[120:123], v[194:197], v[242:245], v[120:123]
	s_setprio 0
	s_setprio 1
	v_mfma_f32_16x16x32_bf16 v[64:67], v[198:201], v[214:217], v[64:67]
	v_mfma_f32_16x16x32_bf16 v[68:71], v[206:209], v[214:217], v[68:71]
	v_mfma_f32_16x16x32_bf16 v[84:87], v[198:201], v[222:225], v[84:87]
	v_mfma_f32_16x16x32_bf16 v[92:95], v[206:209], v[222:225], v[92:95]
	v_mfma_f32_16x16x32_bf16 v[104:107], v[198:201], v[230:233], v[104:107]
	v_mfma_f32_16x16x32_bf16 v[108:111], v[206:209], v[230:233], v[108:111]
	v_mfma_f32_16x16x32_bf16 v[124:127], v[198:201], v[238:241], v[124:127]
	v_mfma_f32_16x16x32_bf16 v[112:115], v[206:209], v[238:241], v[112:115]
	v_mfma_f32_16x16x32_bf16 v[64:67], v[202:205], v[218:221], v[64:67]
	v_mfma_f32_16x16x32_bf16 v[68:71], v[210:213], v[218:221], v[68:71]
	v_mfma_f32_16x16x32_bf16 v[84:87], v[202:205], v[226:229], v[84:87]
	v_mfma_f32_16x16x32_bf16 v[92:95], v[210:213], v[226:229], v[92:95]
	v_mfma_f32_16x16x32_bf16 v[104:107], v[202:205], v[234:237], v[104:107]
	v_mfma_f32_16x16x32_bf16 v[108:111], v[210:213], v[234:237], v[108:111]
	v_mfma_f32_16x16x32_bf16 v[124:127], v[202:205], v[242:245], v[124:127]
	v_mfma_f32_16x16x32_bf16 v[112:115], v[210:213], v[242:245], v[112:115]
	s_barrier
	s_setprio 0
	s_sleep 2
	s_add_i32 s10, s79, s34
	v_lshl_add_u64 v[246:247], s[58:59], 0, v[128:129]
	s_mov_b32 m0, s10
	ds_read_b128 v[214:217], v168 offset:16384
	ds_read_b128 v[218:221], v168 offset:17408
	ds_read_b128 v[222:225], v168 offset:18432
	ds_read_b128 v[226:229], v168 offset:19456
	ds_read_b128 v[230:233], v168 offset:20480
	ds_read_b128 v[234:237], v168 offset:21504
	ds_read_b128 v[238:241], v168 offset:22528
	ds_read_b128 v[242:245], v168 offset:23552
	global_load_lds_dwordx4 v[246:247], off
	s_add_i32 m0, s10, 0x2000
	s_add_u32 s10, s58, 0x160000
	v_lshl_add_u64 v[248:249], s[58:59], 0, v[130:131]
	s_addc_u32 s11, s59, 0
	s_add_i32 s94, s84, s34
	global_load_lds_dwordx4 v[248:249], off
	v_lshl_add_u64 v[250:251], s[10:11], 0, v[128:129]
	s_mov_b32 m0, s94
	v_lshl_add_u64 v[252:253], s[60:61], 0, v[130:131]
	global_load_lds_dwordx4 v[250:251], off
	v_lshl_add_u64 v[250:251], s[10:11], 0, v[130:131]
	s_add_i32 m0, s94, 0x2000
	s_nop 0
	global_load_lds_dwordx4 v[250:251], off
	v_lshl_add_u64 v[250:251], s[60:61], 0, v[128:129]
	s_mov_b32 m0, s3
	s_nop 0
	global_load_lds_dwordx4 v[250:251], off
	s_mov_b32 m0, s28
	s_nop 0
	global_load_lds_dwordx4 v[252:253], off
	s_waitcnt vmcnt(8)
	s_waitcnt lgkmcnt(0)
	s_setprio 1
	s_barrier
; #define PG8_STAGE(bufoff, gbase, voff) do { _Pragma("unroll") for (int _i = 0; _i < 2; ++_i) \
;         __builtin_amdgcn_global_load_lds((const unsigned*)((const char*)(gbase) + (voff)[_i]), (PG8_LAS unsigned*)(lds + (bufoff) + ldsw + _i * 8192), 16, 0, 0); } while (0)
; #define PG8_LDA(dst, b, h) do { _Pragma("unroll") for (int m = 0; m < 4; ++m) _Pragma("unroll") for (int k = 0; k < 2; ++k) dst[m][k] = *(const PG8_LAS bf16x8*)(lds + PG8_SA(b, h) + aoff + m * 2048 + k * 1024); } while (0)
; #define PG8_LDB(dst, b, h) do { _Pragma("unroll") for (int n = 0; n < 2; ++n) _Pragma("unroll") for (int k = 0; k < 2; ++k) dst[n][k] = *(const PG8_LAS bf16x8*)(lds + PG8_SB(b, h) + boff + n * 2048 + k * 1024); } while (0)
; #define PG8_MMA(ai, bj, At, Bt) do { __builtin_amdgcn_s_setprio(1); _Pragma("unroll") for (int m = 0; m < 4; ++m) _Pragma("unroll") for (int n = 0; n < 2; ++n) _Pragma("unroll") for (int k = 0; k < 2; ++k) \
;         acc[ai][bj][m][n] = __builtin_amdgcn_mfma_f32_16x16x32_bf16(Bt[n][k], At[m][k], acc[ai][bj][m][n], 0, 0, 0); __builtin_amdgcn_s_setprio(0); } while (0)
; #define PG8_BAR __builtin_amdgcn_s_barrier()
; template <class Epi, class Sched, bool ALIGN_EPI = false, bool SP2 = false>
; __device__ __forceinline__ void gemm_phase(PG8_LAS unsigned char* lds, const Gemm g, const Sched& S, const Epi& E) {
;     ...
;             if constexpr (SP2) {
;             PG8_LDB(B0, 0, 0); PG8_LDB(B1, 0, 1); PG8_SCHED; PG8_LDA(At, 0, 0); PG8_STAGE(PG8_SA(1, 1), a1 + hstep, voffA);
;             PG8_WAIT_V(8); PG8_WAIT_L(0); PG8_BAR; PG8_MMA(0, 0, At, B0); PG8_MMA(0, 1, At, B1); PG8_BAR; PG8_SCHED;
;             PG8_LDA(At, 0, 1); PG8_STAGE(PG8_SB(0, 0), b2, voffB); PG8_STAGE(PG8_SB(0, 1), b2 + hstep, voffB); PG8_STAGE(PG8_SA(0, 0), a2, voffA);
;             PG8_WAIT_V(8); PG8_WAIT_L(0); PG8_BAR; PG8_MMA(1, 0, At, B0); PG8_MMA(1, 1, At, B1); PG8_BAR; PG8_SCHED;
;             PG8_LDB(B0, 1, 0); PG8_LDB(B1, 1, 1); PG8_SCHED; PG8_LDA(At, 1, 0); PG8_STAGE(PG8_SA(0, 1), a2 + hstep, voffA);
;             PG8_WAIT_V(8); PG8_WAIT_L(0); PG8_BAR; PG8_MMA(0, 0, At, B0); PG8_MMA(0, 1, At, B1); PG8_BAR; PG8_SCHED;
;             PG8_LDA(At, 1, 1); PG8_STAGE(PG8_SB(1, 0), b3, voffB); PG8_STAGE(PG8_SB(1, 1), b3 + hstep, voffB); PG8_STAGE(PG8_SA(1, 0), a3, voffA);
;             PG8_WAIT_V(8); PG8_WAIT_L(0); PG8_BAR; PG8_MMA(1, 0, At, B0); PG8_MMA(1, 1, At, B1); PG8_BAR; PG8_SCHED;
	v_mfma_f32_16x16x32_bf16 v[88:91], v[174:177], v[214:217], v[88:91]
	v_mfma_f32_16x16x32_bf16 v[72:75], v[190:193], v[214:217], v[72:75]
	v_mfma_f32_16x16x32_bf16 v[44:47], v[174:177], v[222:225], v[44:47]
	v_mfma_f32_16x16x32_bf16 v[40:43], v[190:193], v[222:225], v[40:43]
	v_mfma_f32_16x16x32_bf16 v[28:31], v[174:177], v[230:233], v[28:31]
	v_mfma_f32_16x16x32_bf16 v[24:27], v[190:193], v[230:233], v[24:27]
	v_mfma_f32_16x16x32_bf16 v[12:15], v[174:177], v[238:241], v[12:15]
	v_mfma_f32_16x16x32_bf16 v[8:11], v[190:193], v[238:241], v[8:11]
	v_mfma_f32_16x16x32_bf16 v[88:91], v[178:181], v[218:221], v[88:91]
	v_mfma_f32_16x16x32_bf16 v[72:75], v[194:197], v[218:221], v[72:75]
	v_mfma_f32_16x16x32_bf16 v[44:47], v[178:181], v[226:229], v[44:47]
	v_mfma_f32_16x16x32_bf16 v[40:43], v[194:197], v[226:229], v[40:43]
	v_mfma_f32_16x16x32_bf16 v[28:31], v[178:181], v[234:237], v[28:31]
	v_mfma_f32_16x16x32_bf16 v[24:27], v[194:197], v[234:237], v[24:27]
	v_mfma_f32_16x16x32_bf16 v[12:15], v[178:181], v[242:245], v[12:15]
	v_mfma_f32_16x16x32_bf16 v[8:11], v[194:197], v[242:245], v[8:11]
	s_setprio 0
	s_setprio 1
	v_mfma_f32_16x16x32_bf16 v[52:55], v[198:201], v[214:217], v[52:55]
	v_mfma_f32_16x16x32_bf16 v[48:51], v[206:209], v[214:217], v[48:51]
	v_mfma_f32_16x16x32_bf16 v[36:39], v[198:201], v[222:225], v[36:39]
	v_mfma_f32_16x16x32_bf16 v[32:35], v[206:209], v[222:225], v[32:35]
	v_mfma_f32_16x16x32_bf16 v[20:23], v[198:201], v[230:233], v[20:23]
	v_mfma_f32_16x16x32_bf16 v[16:19], v[206:209], v[230:233], v[16:19]
	v_mfma_f32_16x16x32_bf16 v[4:7], v[198:201], v[238:241], v[4:7]
	v_mfma_f32_16x16x32_bf16 v[0:3], v[206:209], v[238:241], v[0:3]
	v_mfma_f32_16x16x32_bf16 v[52:55], v[202:205], v[218:221], v[52:55]
	v_mfma_f32_16x16x32_bf16 v[48:51], v[210:213], v[218:221], v[48:51]
	v_mfma_f32_16x16x32_bf16 v[36:39], v[202:205], v[226:229], v[36:39]
	v_mfma_f32_16x16x32_bf16 v[32:35], v[210:213], v[226:229], v[32:35]
	v_mfma_f32_16x16x32_bf16 v[20:23], v[202:205], v[234:237], v[20:23]
	v_mfma_f32_16x16x32_bf16 v[16:19], v[210:213], v[234:237], v[16:19]
	v_mfma_f32_16x16x32_bf16 v[4:7], v[202:205], v[242:245], v[4:7]
	v_mfma_f32_16x16x32_bf16 v[0:3], v[210:213], v[242:245], v[0:3]
	s_barrier
	s_setprio 0
	s_sleep 2
	s_add_i32 s94, 0, 0x18000
	v_add_u32_e32 v173, s94, v148
	s_add_i32 s95, 0, 0x1c000
	ds_read_b128 v[174:177], v173
	ds_read_b128 v[178:181], v173 offset:1024
	ds_read_b128 v[190:193], v173 offset:2048
	ds_read_b128 v[194:197], v173 offset:3072
	v_add_u32_e32 v173, s95, v148
	ds_read_b128 v[198:201], v173
	ds_read_b128 v[202:205], v173 offset:1024
	ds_read_b128 v[206:209], v173 offset:2048
	ds_read_b128 v[210:213], v173 offset:3072
	s_add_u32 s10, s60, 0x160000
	s_addc_u32 s11, s61, 0
	s_mov_b32 m0, s35
	v_lshl_add_u64 v[188:189], s[10:11], 0, v[128:129]
	ds_read_b128 v[214:217], v168 offset:32768
	ds_read_b128 v[218:221], v168 offset:33792
	ds_read_b128 v[222:225], v168 offset:34816
	ds_read_b128 v[226:229], v168 offset:35840
	ds_read_b128 v[230:233], v168 offset:36864
	ds_read_b128 v[234:237], v168 offset:37888
	ds_read_b128 v[238:241], v168 offset:38912
	ds_read_b128 v[242:245], v168 offset:39936
	global_load_lds_dwordx4 v[188:189], off
	v_lshl_add_u64 v[188:189], s[10:11], 0, v[130:131]
	s_mov_b32 m0, s62
	s_nop 0
	global_load_lds_dwordx4 v[188:189], off
	s_waitcnt vmcnt(8)
	s_waitcnt lgkmcnt(0)
	s_setprio 1
	s_barrier
	v_mfma_f32_16x16x32_bf16 v[56:59], v[174:177], v[214:217], v[56:59]
	v_mfma_f32_16x16x32_bf16 v[60:63], v[190:193], v[214:217], v[60:63]
	v_mfma_f32_16x16x32_bf16 v[76:79], v[174:177], v[222:225], v[76:79]
	v_mfma_f32_16x16x32_bf16 v[80:83], v[190:193], v[222:225], v[80:83]
	v_mfma_f32_16x16x32_bf16 v[96:99], v[174:177], v[230:233], v[96:99]
	v_mfma_f32_16x16x32_bf16 v[100:103], v[190:193], v[230:233], v[100:103]
	v_mfma_f32_16x16x32_bf16 v[116:119], v[174:177], v[238:241], v[116:119]
	v_mfma_f32_16x16x32_bf16 v[120:123], v[190:193], v[238:241], v[120:123]
	v_mfma_f32_16x16x32_bf16 v[56:59], v[178:181], v[218:221], v[56:59]
	v_mfma_f32_16x16x32_bf16 v[60:63], v[194:197], v[218:221], v[60:63]
	v_mfma_f32_16x16x32_bf16 v[76:79], v[178:181], v[226:229], v[76:79]
	v_mfma_f32_16x16x32_bf16 v[80:83], v[194:197], v[226:229], v[80:83]
	v_mfma_f32_16x16x32_bf16 v[96:99], v[178:181], v[234:237], v[96:99]
	v_mfma_f32_16x16x32_bf16 v[100:103], v[194:197], v[234:237], v[100:103]
	v_mfma_f32_16x16x32_bf16 v[116:119], v[178:181], v[242:245], v[116:119]
	v_mfma_f32_16x16x32_bf16 v[120:123], v[194:197], v[242:245], v[120:123]
	s_setprio 0
	s_setprio 1
	v_mfma_f32_16x16x32_bf16 v[64:67], v[198:201], v[214:217], v[64:67]
	v_mfma_f32_16x16x32_bf16 v[68:71], v[206:209], v[214:217], v[68:71]
	v_mfma_f32_16x16x32_bf16 v[84:87], v[198:201], v[222:225], v[84:87]
	v_mfma_f32_16x16x32_bf16 v[92:95], v[206:209], v[222:225], v[92:95]
	v_mfma_f32_16x16x32_bf16 v[104:107], v[198:201], v[230:233], v[104:107]
	v_mfma_f32_16x16x32_bf16 v[108:111], v[206:209], v[230:233], v[108:111]
	v_mfma_f32_16x16x32_bf16 v[124:127], v[198:201], v[238:241], v[124:127]
	v_mfma_f32_16x16x32_bf16 v[112:115], v[206:209], v[238:241], v[112:115]
	v_mfma_f32_16x16x32_bf16 v[64:67], v[202:205], v[218:221], v[64:67]
	v_mfma_f32_16x16x32_bf16 v[68:71], v[210:213], v[218:221], v[68:71]
	v_mfma_f32_16x16x32_bf16 v[84:87], v[202:205], v[226:229], v[84:87]
	v_mfma_f32_16x16x32_bf16 v[92:95], v[210:213], v[226:229], v[92:95]
	v_mfma_f32_16x16x32_bf16 v[104:107], v[202:205], v[234:237], v[104:107]
	v_mfma_f32_16x16x32_bf16 v[108:111], v[210:213], v[234:237], v[108:111]
	v_mfma_f32_16x16x32_bf16 v[124:127], v[202:205], v[242:245], v[124:127]
	v_mfma_f32_16x16x32_bf16 v[112:115], v[210:213], v[242:245], v[112:115]
	s_barrier
; #define PG8_STAGE(bufoff, gbase, voff) do { _Pragma("unroll") for (int _i = 0; _i < 2; ++_i) \
;         __builtin_amdgcn_global_load_lds((const unsigned*)((const char*)(gbase) + (voff)[_i]), (PG8_LAS unsigned*)(lds + (bufoff) + ldsw + _i * 8192), 16, 0, 0); } while (0)
; #define PG8_LDA(dst, b, h) do { _Pragma("unroll") for (int m = 0; m < 4; ++m) _Pragma("unroll") for (int k = 0; k < 2; ++k) dst[m][k] = *(const PG8_LAS bf16x8*)(lds + PG8_SA(b, h) + aoff + m * 2048 + k * 1024); } while (0)
; #define PG8_LDB(dst, b, h) do { _Pragma("unroll") for (int n = 0; n < 2; ++n) _Pragma("unroll") for (int k = 0; k < 2; ++k) dst[n][k] = *(const PG8_LAS bf16x8*)(lds + PG8_SB(b, h) + boff + n * 2048 + k * 1024); } while (0)
; #define PG8_MMA(ai, bj, At, Bt) do { __builtin_amdgcn_s_setprio(1); _Pragma("unroll") for (int m = 0; m < 4; ++m) _Pragma("unroll") for (int n = 0; n < 2; ++n) _Pragma("unroll") for (int k = 0; k < 2; ++k) \
;         acc[ai][bj][m][n] = __builtin_amdgcn_mfma_f32_16x16x32_bf16(Bt[n][k], At[m][k], acc[ai][bj][m][n], 0, 0, 0); __builtin_amdgcn_s_setprio(0); } while (0)
; template <class Epi, class Sched, bool ALIGN_EPI = false, bool SP2 = false>
; __device__ __forceinline__ void gemm_phase(PG8_LAS unsigned char* lds, const Gemm g, const Sched& S, const Epi& E) {
;     ...
;         for (int t = 0; t < nt; t += 2) {
;     ...
;             if constexpr (SP2) {
;             PG8_LDB(B0, 0, 0); PG8_LDB(B1, 0, 1); PG8_SCHED; PG8_LDA(At, 0, 0); PG8_STAGE(PG8_SA(1, 1), a1 + hstep, voffA);
;             PG8_WAIT_V(8); PG8_WAIT_L(0); PG8_BAR; PG8_MMA(0, 0, At, B0); PG8_MMA(0, 1, At, B1); PG8_BAR; PG8_SCHED;
;             PG8_LDA(At, 0, 1); PG8_STAGE(PG8_SB(0, 0), b2, voffB); PG8_STAGE(PG8_SB(0, 1), b2 + hstep, voffB); PG8_STAGE(PG8_SA(0, 0), a2, voffA);
;             PG8_WAIT_V(8); PG8_WAIT_L(0); PG8_BAR; PG8_MMA(1, 0, At, B0); PG8_MMA(1, 1, At, B1); PG8_BAR; PG8_SCHED;
;             PG8_LDB(B0, 1, 0); PG8_LDB(B1, 1, 1); PG8_SCHED; PG8_LDA(At, 1, 0); PG8_STAGE(PG8_SA(0, 1), a2 + hstep, voffA);
;             PG8_WAIT_V(8); PG8_WAIT_L(0); PG8_BAR; PG8_MMA(0, 0, At, B0); PG8_MMA(0, 1, At, B1); PG8_BAR; PG8_SCHED;
;             PG8_LDA(At, 1, 1); PG8_STAGE(PG8_SB(1, 0), b3, voffB); PG8_STAGE(PG8_SB(1, 1), b3 + hstep, voffB); PG8_STAGE(PG8_SA(1, 0), a3, voffA);
;             PG8_WAIT_V(8); PG8_WAIT_L(0); PG8_BAR; PG8_MMA(1, 0, At, B0); PG8_MMA(1, 1, At, B1); PG8_BAR; PG8_SCHED;
	s_setprio 0
	s_sleep 2
	s_add_i32 s10, s94, s34
	v_lshl_add_u64 v[188:189], v[246:247], 0, s[44:45]
	s_mov_b32 m0, s10
	ds_read_b128 v[214:217], v168 offset:49152
	ds_read_b128 v[218:221], v168 offset:50176
	ds_read_b128 v[222:225], v168 offset:51200
	ds_read_b128 v[226:229], v168 offset:52224
	ds_read_b128 v[230:233], v168 offset:53248
	ds_read_b128 v[234:237], v168 offset:54272
	ds_read_b128 v[238:241], v168 offset:55296
	ds_read_b128 v[242:245], v168 offset:56320
	global_load_lds_dwordx4 v[188:189], off
	s_add_i32 m0, s10, 0x2000
	s_add_u32 s10, s58, 0x160080
	v_lshl_add_u64 v[188:189], v[248:249], 0, s[44:45]
	s_addc_u32 s11, s59, 0
	s_add_i32 s58, s95, s34
	global_load_lds_dwordx4 v[188:189], off
	v_lshl_add_u64 v[188:189], s[10:11], 0, v[128:129]
	s_mov_b32 m0, s58
	s_nop 0
	global_load_lds_dwordx4 v[188:189], off
	v_lshl_add_u64 v[188:189], s[10:11], 0, v[130:131]
	s_add_i32 m0, s58, 0x2000
	s_nop 0
	global_load_lds_dwordx4 v[188:189], off
	v_lshl_add_u64 v[188:189], v[250:251], 0, s[44:45]
	s_mov_b32 m0, s65
	s_nop 0
	global_load_lds_dwordx4 v[188:189], off
	v_lshl_add_u64 v[188:189], v[252:253], 0, s[44:45]
	s_mov_b32 m0, s66
	s_nop 0
	global_load_lds_dwordx4 v[188:189], off
	s_waitcnt vmcnt(8)
	s_waitcnt lgkmcnt(0)
	s_setprio 1
	s_barrier
	v_mfma_f32_16x16x32_bf16 v[88:91], v[174:177], v[214:217], v[88:91]
	v_mfma_f32_16x16x32_bf16 v[72:75], v[190:193], v[214:217], v[72:75]
	v_mfma_f32_16x16x32_bf16 v[44:47], v[174:177], v[222:225], v[44:47]
	v_mfma_f32_16x16x32_bf16 v[40:43], v[190:193], v[222:225], v[40:43]
	v_mfma_f32_16x16x32_bf16 v[28:31], v[174:177], v[230:233], v[28:31]
	v_mfma_f32_16x16x32_bf16 v[24:27], v[190:193], v[230:233], v[24:27]
	v_mfma_f32_16x16x32_bf16 v[12:15], v[174:177], v[238:241], v[12:15]
	v_mfma_f32_16x16x32_bf16 v[8:11], v[190:193], v[238:241], v[8:11]
	v_mfma_f32_16x16x32_bf16 v[88:91], v[178:181], v[218:221], v[88:91]
	v_mfma_f32_16x16x32_bf16 v[72:75], v[194:197], v[218:221], v[72:75]
	v_mfma_f32_16x16x32_bf16 v[44:47], v[178:181], v[226:229], v[44:47]
	v_mfma_f32_16x16x32_bf16 v[40:43], v[194:197], v[226:229], v[40:43]
	v_mfma_f32_16x16x32_bf16 v[28:31], v[178:181], v[234:237], v[28:31]
	v_mfma_f32_16x16x32_bf16 v[24:27], v[194:197], v[234:237], v[24:27]
	v_mfma_f32_16x16x32_bf16 v[12:15], v[178:181], v[242:245], v[12:15]
	v_mfma_f32_16x16x32_bf16 v[8:11], v[194:197], v[242:245], v[8:11]
	s_setprio 0
	s_setprio 1
	v_mfma_f32_16x16x32_bf16 v[52:55], v[198:201], v[214:217], v[52:55]
	v_mfma_f32_16x16x32_bf16 v[48:51], v[206:209], v[214:217], v[48:51]
	v_mfma_f32_16x16x32_bf16 v[36:39], v[198:201], v[222:225], v[36:39]
	v_mfma_f32_16x16x32_bf16 v[32:35], v[206:209], v[222:225], v[32:35]
	v_mfma_f32_16x16x32_bf16 v[20:23], v[198:201], v[230:233], v[20:23]
	v_mfma_f32_16x16x32_bf16 v[16:19], v[206:209], v[230:233], v[16:19]
	v_mfma_f32_16x16x32_bf16 v[4:7], v[198:201], v[238:241], v[4:7]
	v_mfma_f32_16x16x32_bf16 v[0:3], v[206:209], v[238:241], v[0:3]
	v_mfma_f32_16x16x32_bf16 v[52:55], v[202:205], v[218:221], v[52:55]
	v_mfma_f32_16x16x32_bf16 v[48:51], v[210:213], v[218:221], v[48:51]
	v_mfma_f32_16x16x32_bf16 v[36:39], v[202:205], v[226:229], v[36:39]
	v_mfma_f32_16x16x32_bf16 v[32:35], v[210:213], v[226:229], v[32:35]
	v_mfma_f32_16x16x32_bf16 v[20:23], v[202:205], v[234:237], v[20:23]
	v_mfma_f32_16x16x32_bf16 v[16:19], v[210:213], v[234:237], v[16:19]
	v_mfma_f32_16x16x32_bf16 v[4:7], v[202:205], v[242:245], v[4:7]
	v_mfma_f32_16x16x32_bf16 v[0:3], v[210:213], v[242:245], v[0:3]
	s_barrier
	s_setprio 0
	s_sleep 2
	s_add_i32 s93, s93, 2
	s_cmpk_gt_u32 s93, 0x55
	s_mov_b64 s[10:11], s[46:47]
	s_cbranch_scc0 .LBB0_121
	s_and_b64 vcc, exec, s[48:49]
	s_cbranch_vccz .LBB0_124
	s_barrier

; #define PG8_STAGE(bufoff, gbase, voff) do { _Pragma("unroll") for (int _i = 0; _i < 2; ++_i) \
;         __builtin_amdgcn_global_load_lds((const unsigned*)((const char*)(gbase) + (voff)[_i]), (PG8_LAS unsigned*)(lds + (bufoff) + ldsw + _i * 8192), 16, 0, 0); } while (0)
; #define PG8_LDA(dst, b, h) do { _Pragma("unroll") for (int m = 0; m < 4; ++m) _Pragma("unroll") for (int k = 0; k < 2; ++k) dst[m][k] = *(const PG8_LAS bf16x8*)(lds + PG8_SA(b, h) + aoff + m * 2048 + k * 1024); } while (0)
; #define PG8_LDB(dst, b, h) do { _Pragma("unroll") for (int n = 0; n < 2; ++n) _Pragma("unroll") for (int k = 0; k < 2; ++k) dst[n][k] = *(const PG8_LAS bf16x8*)(lds + PG8_SB(b, h) + boff + n * 2048 + k * 1024); } while (0)
; #define PG8_MMA(ai, bj, At, Bt) do { __builtin_amdgcn_s_setprio(1); _Pragma("unroll") for (int m = 0; m < 4; ++m) _Pragma("unroll") for (int n = 0; n < 2; ++n) _Pragma("unroll") for (int k = 0; k < 2; ++k) \
;         acc[ai][bj][m][n] = __builtin_amdgcn_mfma_f32_16x16x32_bf16(Bt[n][k], At[m][k], acc[ai][bj][m][n], 0, 0, 0); __builtin_amdgcn_s_setprio(0); } while (0)
; #define PG8_WAIT_V(n) asm volatile("s_waitcnt vmcnt(" #n ")" ::: "memory")
; #define PG8_WAIT_L(n) asm volatile("s_waitcnt lgkmcnt(" #n ")" ::: "memory")
; #define PG8_BAR __builtin_amdgcn_s_barrier()
; #define PG8_SCHED __builtin_amdgcn_sched_barrier(0)
; template <class Epi, class Sched, bool ALIGN_EPI = false, bool SP2 = false>
; __device__ __forceinline__ void gemm_phase(PG8_LAS unsigned char* lds, const Gemm g, const Sched& S, const Epi& E) {
;     ...
;         for (int t = 0; t < nt; t += 2) {
;             const bool last = (t == nt - 2);
;             const char* a1 = cA + (size_t)(t + 1) * kstep;
;             const char* a2 = last ? nA : cA + (size_t)(t + 2) * kstep; const char* b2 = last ? nB : cB + (size_t)(t + 2) * kstep;
;             const char* a3 = a2 + kstep; const char* b3 = b2 + kstep;
;             if (last && has_next) S.a_ready(nxt);
;             if constexpr (SP2) {
;             PG8_LDB(B0, 0, 0); PG8_LDB(B1, 0, 1); PG8_SCHED; PG8_LDA(At, 0, 0); PG8_STAGE(PG8_SA(1, 1), a1 + hstep, voffA);
;             PG8_WAIT_V(8); PG8_WAIT_L(0); PG8_BAR; PG8_MMA(0, 0, At, B0); PG8_MMA(0, 1, At, B1); PG8_BAR; PG8_SCHED;
;             PG8_LDA(At, 0, 1); PG8_STAGE(PG8_SB(0, 0), b2, voffB); PG8_STAGE(PG8_SB(0, 1), b2 + hstep, voffB); PG8_STAGE(PG8_SA(0, 0), a2, voffA);
.LBB0_181:
	ds_read_b128 v[0:3], v147
	ds_read_b128 v[4:7], v147 offset:1024
	ds_read_b128 v[8:11], v147 offset:2048
	ds_read_b128 v[12:15], v147 offset:3072
	ds_read_b128 v[16:19], v148
	ds_read_b128 v[20:23], v148 offset:1024
	ds_read_b128 v[24:27], v148 offset:2048
	ds_read_b128 v[28:31], v148 offset:3072
	s_ashr_i32 s41, s40, 31
	s_lshl_b64 s[42:43], s[40:41], 17
	s_add_u32 s42, s28, s42
	s_addc_u32 s43, s29, s43
	s_and_b64 s[44:45], s[0:1], exec
	s_cselect_b32 s63, s43, s49
	s_cselect_b32 s62, s42, s48
	s_ashr_i32 s39, s38, 31
	s_lshl_b64 s[44:45], s[38:39], 17
	s_add_u32 s44, s82, s44
	s_addc_u32 s45, s83, s45
	s_and_b64 s[58:59], s[0:1], exec
	s_cselect_b32 s59, s45, s61
	s_cselect_b32 s58, s44, s60
	s_add_u32 s86, s48, 0x10080
	s_addc_u32 s87, s49, 0
	s_add_i32 s92, s35, 0xc000
	v_lshl_add_u64 v[64:65], s[86:87], 0, v[130:131]
	s_mov_b32 m0, s92
	s_add_i32 s39, s35, 0xe000
	ds_read_b128 v[32:35], v149
	ds_read_b128 v[36:39], v149 offset:1024
	ds_read_b128 v[40:43], v149 offset:2048
	ds_read_b128 v[44:47], v149 offset:3072
	ds_read_b128 v[48:51], v149 offset:4096
	ds_read_b128 v[52:55], v149 offset:5120
	ds_read_b128 v[56:59], v149 offset:6144
	ds_read_b128 v[60:63], v149 offset:7168
	global_load_lds_dwordx4 v[64:65], off
	v_lshl_add_u64 v[64:65], s[86:87], 0, v[128:129]
	s_mov_b32 m0, s39
	s_nop 0
	global_load_lds_dwordx4 v[64:65], off
	s_waitcnt vmcnt(8)
	s_waitcnt lgkmcnt(0)
	s_setprio 1
	s_barrier
	v_mfma_f32_16x16x32_bf16 v[64:67], v[0:3], v[32:35], 0
	v_mfma_f32_16x16x32_bf16 v[68:71], v[8:11], v[32:35], 0
	v_mfma_f32_16x16x32_bf16 v[72:75], v[0:3], v[40:43], 0
	v_mfma_f32_16x16x32_bf16 v[76:79], v[8:11], v[40:43], 0
	v_mfma_f32_16x16x32_bf16 v[80:83], v[0:3], v[48:51], 0
	v_mfma_f32_16x16x32_bf16 v[84:87], v[8:11], v[48:51], 0
	v_mfma_f32_16x16x32_bf16 v[88:91], v[0:3], v[56:59], 0
	v_mfma_f32_16x16x32_bf16 v[92:95], v[8:11], v[56:59], 0
	v_mfma_f32_16x16x32_bf16 v[64:67], v[4:7], v[36:39], v[64:67]
	v_mfma_f32_16x16x32_bf16 v[68:71], v[12:15], v[36:39], v[68:71]
	v_mfma_f32_16x16x32_bf16 v[72:75], v[4:7], v[44:47], v[72:75]
	v_mfma_f32_16x16x32_bf16 v[76:79], v[12:15], v[44:47], v[76:79]
	v_mfma_f32_16x16x32_bf16 v[80:83], v[4:7], v[52:55], v[80:83]
	v_mfma_f32_16x16x32_bf16 v[84:87], v[12:15], v[52:55], v[84:87]
	v_mfma_f32_16x16x32_bf16 v[88:91], v[4:7], v[60:63], v[88:91]
	v_mfma_f32_16x16x32_bf16 v[92:95], v[12:15], v[60:63], v[92:95]
	s_setprio 0
	s_setprio 1
	v_mfma_f32_16x16x32_bf16 v[96:99], v[16:19], v[32:35], 0
	v_mfma_f32_16x16x32_bf16 v[32:35], v[24:27], v[32:35], 0
	v_mfma_f32_16x16x32_bf16 v[96:99], v[20:23], v[36:39], v[96:99]
	v_mfma_f32_16x16x32_bf16 v[32:35], v[28:31], v[36:39], v[32:35]
	v_mfma_f32_16x16x32_bf16 v[36:39], v[16:19], v[40:43], 0
	v_mfma_f32_16x16x32_bf16 v[40:43], v[24:27], v[40:43], 0
	v_mfma_f32_16x16x32_bf16 v[36:39], v[20:23], v[44:47], v[36:39]
	v_mfma_f32_16x16x32_bf16 v[40:43], v[28:31], v[44:47], v[40:43]
	v_mfma_f32_16x16x32_bf16 v[44:47], v[16:19], v[48:51], 0
	v_mfma_f32_16x16x32_bf16 v[48:51], v[24:27], v[48:51], 0
	v_mfma_f32_16x16x32_bf16 v[44:47], v[20:23], v[52:55], v[44:47]
	v_mfma_f32_16x16x32_bf16 v[48:51], v[28:31], v[52:55], v[48:51]
	v_mfma_f32_16x16x32_bf16 v[52:55], v[16:19], v[56:59], 0
	v_mfma_f32_16x16x32_bf16 v[56:59], v[24:27], v[56:59], 0
	v_mfma_f32_16x16x32_bf16 v[52:55], v[20:23], v[60:63], v[52:55]
	v_mfma_f32_16x16x32_bf16 v[56:59], v[28:31], v[60:63], v[56:59]
	s_barrier
	s_setprio 0
	s_sleep 2
	s_add_i32 s89, s79, s3
	v_lshl_add_u64 v[140:141], s[60:61], 0, v[130:131]
	s_add_i32 s41, s89, 0x2000
	v_lshl_add_u64 v[136:137], v[140:141], 0, s[12:13]
	s_mov_b32 m0, s89
	v_lshl_add_u64 v[180:181], s[60:61], 0, v[128:129]
	s_add_u32 s96, s60, 0x10100
	ds_read_b128 v[60:63], v149 offset:16384
	ds_read_b128 v[100:103], v149 offset:17408
	ds_read_b128 v[104:107], v149 offset:18432
	ds_read_b128 v[108:111], v149 offset:19456
	ds_read_b128 v[112:115], v149 offset:20480
	ds_read_b128 v[116:119], v149 offset:21504
	ds_read_b128 v[120:123], v149 offset:22528
	ds_read_b128 v[124:127], v149 offset:23552
	global_load_lds_dwordx4 v[136:137], off
	v_lshl_add_u64 v[136:137], v[180:181], 0, s[12:13]
	s_mov_b32 m0, s41
	s_addc_u32 s97, s61, 0
	s_add_i32 s86, s84, s3
	global_load_lds_dwordx4 v[136:137], off
	v_lshl_add_u64 v[136:137], s[96:97], 0, v[130:131]
	s_mov_b32 m0, s86
	s_add_i32 s87, s86, 0x2000
	global_load_lds_dwordx4 v[136:137], off
	v_lshl_add_u64 v[136:137], s[96:97], 0, v[128:129]
	s_mov_b32 m0, s87
	v_lshl_add_u64 v[188:189], s[48:49], 0, v[130:131]
	global_load_lds_dwordx4 v[136:137], off
	v_lshl_add_u64 v[136:137], v[188:189], 0, s[12:13]
	s_mov_b32 m0, s35
	v_lshl_add_u64 v[222:223], s[48:49], 0, v[128:129]
	global_load_lds_dwordx4 v[136:137], off
	v_lshl_add_u64 v[136:137], v[222:223], 0, s[12:13]
	s_mov_b32 m0, s47
	s_nop 0
	global_load_lds_dwordx4 v[136:137], off
	s_waitcnt vmcnt(8)
	s_waitcnt lgkmcnt(0)
	s_setprio 1
	s_barrier
; #define PG8_STAGE(bufoff, gbase, voff) do { _Pragma("unroll") for (int _i = 0; _i < 2; ++_i) \
;         __builtin_amdgcn_global_load_lds((const unsigned*)((const char*)(gbase) + (voff)[_i]), (PG8_LAS unsigned*)(lds + (bufoff) + ldsw + _i * 8192), 16, 0, 0); } while (0)
; #define PG8_LDA(dst, b, h) do { _Pragma("unroll") for (int m = 0; m < 4; ++m) _Pragma("unroll") for (int k = 0; k < 2; ++k) dst[m][k] = *(const PG8_LAS bf16x8*)(lds + PG8_SA(b, h) + aoff + m * 2048 + k * 1024); } while (0)
; #define PG8_LDB(dst, b, h) do { _Pragma("unroll") for (int n = 0; n < 2; ++n) _Pragma("unroll") for (int k = 0; k < 2; ++k) dst[n][k] = *(const PG8_LAS bf16x8*)(lds + PG8_SB(b, h) + boff + n * 2048 + k * 1024); } while (0)
; #define PG8_MMA(ai, bj, At, Bt) do { __builtin_amdgcn_s_setprio(1); _Pragma("unroll") for (int m = 0; m < 4; ++m) _Pragma("unroll") for (int n = 0; n < 2; ++n) _Pragma("unroll") for (int k = 0; k < 2; ++k) \
;         acc[ai][bj][m][n] = __builtin_amdgcn_mfma_f32_16x16x32_bf16(Bt[n][k], At[m][k], acc[ai][bj][m][n], 0, 0, 0); __builtin_amdgcn_s_setprio(0); } while (0)
; #define PG8_WAIT_V(n) asm volatile("s_waitcnt vmcnt(" #n ")" ::: "memory")
; #define PG8_WAIT_L(n) asm volatile("s_waitcnt lgkmcnt(" #n ")" ::: "memory")
; #define PG8_BAR __builtin_amdgcn_s_barrier()
; template <class Epi, class Sched, bool ALIGN_EPI = false, bool SP2 = false>
; __device__ __forceinline__ void gemm_phase(PG8_LAS unsigned char* lds, const Gemm g, const Sched& S, const Epi& E) {
;     ...
;             PG8_WAIT_V(8); PG8_WAIT_L(0); PG8_BAR; PG8_MMA(0, 0, At, B0); PG8_MMA(0, 1, At, B1); PG8_BAR; PG8_SCHED;
;             PG8_LDA(At, 0, 1); PG8_STAGE(PG8_SB(0, 0), b2, voffB); PG8_STAGE(PG8_SB(0, 1), b2 + hstep, voffB); PG8_STAGE(PG8_SA(0, 0), a2, voffA);
;             PG8_WAIT_V(8); PG8_WAIT_L(0); PG8_BAR; PG8_MMA(1, 0, At, B0); PG8_MMA(1, 1, At, B1); PG8_BAR; PG8_SCHED;
;             PG8_LDB(B0, 1, 0); PG8_LDB(B1, 1, 1); PG8_SCHED; PG8_LDA(At, 1, 0); PG8_STAGE(PG8_SA(0, 1), a2 + hstep, voffA);
;             PG8_WAIT_V(8); PG8_WAIT_L(0); PG8_BAR; PG8_MMA(0, 0, At, B0); PG8_MMA(0, 1, At, B1); PG8_BAR; PG8_SCHED;
;             PG8_LDA(At, 1, 1); PG8_STAGE(PG8_SB(1, 0), b3, voffB); PG8_STAGE(PG8_SB(1, 1), b3 + hstep, voffB); PG8_STAGE(PG8_SA(1, 0), a3, voffA);
;             PG8_WAIT_V(8); PG8_WAIT_L(0); PG8_BAR; PG8_MMA(1, 0, At, B0); PG8_MMA(1, 1, At, B1); PG8_BAR; PG8_SCHED;
	v_mfma_f32_16x16x32_bf16 v[136:139], v[0:3], v[60:63], 0
	v_mfma_f32_16x16x32_bf16 v[156:159], v[0:3], v[104:107], 0
	v_mfma_f32_16x16x32_bf16 v[164:167], v[0:3], v[112:115], 0
	v_mfma_f32_16x16x32_bf16 v[0:3], v[0:3], v[120:123], 0
	v_mfma_f32_16x16x32_bf16 v[136:139], v[4:7], v[100:103], v[136:139]
	v_mfma_f32_16x16x32_bf16 v[156:159], v[4:7], v[108:111], v[156:159]
	v_mfma_f32_16x16x32_bf16 v[164:167], v[4:7], v[116:119], v[164:167]
	v_mfma_f32_16x16x32_bf16 v[0:3], v[4:7], v[124:127], v[0:3]
	v_mfma_f32_16x16x32_bf16 v[4:7], v[8:11], v[120:123], 0
	v_mfma_f32_16x16x32_bf16 v[152:155], v[8:11], v[60:63], 0
	v_mfma_f32_16x16x32_bf16 v[160:163], v[8:11], v[104:107], 0
	v_mfma_f32_16x16x32_bf16 v[168:171], v[8:11], v[112:115], 0
	v_mfma_f32_16x16x32_bf16 v[4:7], v[12:15], v[124:127], v[4:7]
	v_mfma_f32_16x16x32_bf16 v[152:155], v[12:15], v[100:103], v[152:155]
	v_mfma_f32_16x16x32_bf16 v[160:163], v[12:15], v[108:111], v[160:163]
	v_mfma_f32_16x16x32_bf16 v[168:171], v[12:15], v[116:119], v[168:171]
	s_setprio 0
	s_setprio 1
	v_mfma_f32_16x16x32_bf16 v[8:11], v[16:19], v[60:63], 0
	v_mfma_f32_16x16x32_bf16 v[12:15], v[24:27], v[60:63], 0
	v_mfma_f32_16x16x32_bf16 v[8:11], v[20:23], v[100:103], v[8:11]
	v_mfma_f32_16x16x32_bf16 v[12:15], v[28:31], v[100:103], v[12:15]
	v_mfma_f32_16x16x32_bf16 v[60:63], v[16:19], v[104:107], 0
	v_mfma_f32_16x16x32_bf16 v[100:103], v[24:27], v[104:107], 0
	v_mfma_f32_16x16x32_bf16 v[104:107], v[16:19], v[112:115], 0
	v_mfma_f32_16x16x32_bf16 v[16:19], v[16:19], v[120:123], 0
	v_mfma_f32_16x16x32_bf16 v[60:63], v[20:23], v[108:111], v[60:63]
	v_mfma_f32_16x16x32_bf16 v[100:103], v[28:31], v[108:111], v[100:103]
	v_mfma_f32_16x16x32_bf16 v[104:107], v[20:23], v[116:119], v[104:107]
	v_mfma_f32_16x16x32_bf16 v[108:111], v[24:27], v[112:115], 0
	v_mfma_f32_16x16x32_bf16 v[16:19], v[20:23], v[124:127], v[16:19]
	v_mfma_f32_16x16x32_bf16 v[20:23], v[24:27], v[120:123], 0
	v_mfma_f32_16x16x32_bf16 v[108:111], v[28:31], v[116:119], v[108:111]
	v_mfma_f32_16x16x32_bf16 v[20:23], v[28:31], v[124:127], v[20:23]
	s_barrier
	s_setprio 0
	s_sleep 2
	s_add_i32 s93, 0, 0x18000
	s_add_i32 s94, 0, 0x1c000
	v_add_u32_e32 v226, s93, v143
	v_add_u32_e32 v227, s94, v143
	ds_read_b128 v[24:27], v226
	ds_read_b128 v[28:31], v226 offset:1024
	ds_read_b128 v[112:115], v226 offset:2048
	ds_read_b128 v[116:119], v226 offset:3072
	ds_read_b128 v[120:123], v227
	ds_read_b128 v[124:127], v227 offset:1024
	ds_read_b128 v[172:175], v227 offset:2048
	ds_read_b128 v[176:179], v227 offset:3072
	s_add_u32 s96, s48, 0x10100
	s_addc_u32 s97, s49, 0
	s_mov_b32 m0, s64
	v_lshl_add_u64 v[224:225], s[96:97], 0, v[130:131]
	ds_read_b128 v[190:193], v149 offset:32768
	ds_read_b128 v[194:197], v149 offset:33792
	ds_read_b128 v[198:201], v149 offset:34816
	ds_read_b128 v[202:205], v149 offset:35840
	ds_read_b128 v[206:209], v149 offset:36864
	ds_read_b128 v[210:213], v149 offset:37888
	ds_read_b128 v[214:217], v149 offset:38912
	ds_read_b128 v[218:221], v149 offset:39936
	global_load_lds_dwordx4 v[224:225], off
	v_lshl_add_u64 v[224:225], s[96:97], 0, v[128:129]
	s_mov_b32 m0, s65
	s_nop 0
	global_load_lds_dwordx4 v[224:225], off
	s_waitcnt vmcnt(8)
	s_waitcnt lgkmcnt(0)
	s_setprio 1
	s_barrier
	v_mfma_f32_16x16x32_bf16 v[64:67], v[24:27], v[190:193], v[64:67]
	v_mfma_f32_16x16x32_bf16 v[68:71], v[112:115], v[190:193], v[68:71]
	v_mfma_f32_16x16x32_bf16 v[72:75], v[24:27], v[198:201], v[72:75]
	v_mfma_f32_16x16x32_bf16 v[76:79], v[112:115], v[198:201], v[76:79]
	v_mfma_f32_16x16x32_bf16 v[80:83], v[24:27], v[206:209], v[80:83]
	v_mfma_f32_16x16x32_bf16 v[84:87], v[112:115], v[206:209], v[84:87]
	v_mfma_f32_16x16x32_bf16 v[88:91], v[24:27], v[214:217], v[88:91]
	v_mfma_f32_16x16x32_bf16 v[92:95], v[112:115], v[214:217], v[92:95]
	v_mfma_f32_16x16x32_bf16 v[64:67], v[28:31], v[194:197], v[64:67]
	v_mfma_f32_16x16x32_bf16 v[68:71], v[116:119], v[194:197], v[68:71]
	v_mfma_f32_16x16x32_bf16 v[72:75], v[28:31], v[202:205], v[72:75]
	v_mfma_f32_16x16x32_bf16 v[76:79], v[116:119], v[202:205], v[76:79]
	v_mfma_f32_16x16x32_bf16 v[80:83], v[28:31], v[210:213], v[80:83]
	v_mfma_f32_16x16x32_bf16 v[84:87], v[116:119], v[210:213], v[84:87]
	v_mfma_f32_16x16x32_bf16 v[88:91], v[28:31], v[218:221], v[88:91]
	v_mfma_f32_16x16x32_bf16 v[92:95], v[116:119], v[218:221], v[92:95]
	s_setprio 0
	s_setprio 1
	v_mfma_f32_16x16x32_bf16 v[96:99], v[120:123], v[190:193], v[96:99]
	v_mfma_f32_16x16x32_bf16 v[32:35], v[172:175], v[190:193], v[32:35]
	v_mfma_f32_16x16x32_bf16 v[36:39], v[120:123], v[198:201], v[36:39]
	v_mfma_f32_16x16x32_bf16 v[40:43], v[172:175], v[198:201], v[40:43]
	v_mfma_f32_16x16x32_bf16 v[44:47], v[120:123], v[206:209], v[44:47]
	v_mfma_f32_16x16x32_bf16 v[48:51], v[172:175], v[206:209], v[48:51]
	v_mfma_f32_16x16x32_bf16 v[52:55], v[120:123], v[214:217], v[52:55]
	v_mfma_f32_16x16x32_bf16 v[56:59], v[172:175], v[214:217], v[56:59]
	v_mfma_f32_16x16x32_bf16 v[96:99], v[124:127], v[194:197], v[96:99]
	v_mfma_f32_16x16x32_bf16 v[32:35], v[176:179], v[194:197], v[32:35]
	v_mfma_f32_16x16x32_bf16 v[36:39], v[124:127], v[202:205], v[36:39]
	v_mfma_f32_16x16x32_bf16 v[40:43], v[176:179], v[202:205], v[40:43]
	v_mfma_f32_16x16x32_bf16 v[44:47], v[124:127], v[210:213], v[44:47]
	v_mfma_f32_16x16x32_bf16 v[48:51], v[176:179], v[210:213], v[48:51]
	v_mfma_f32_16x16x32_bf16 v[52:55], v[124:127], v[218:221], v[52:55]
	v_mfma_f32_16x16x32_bf16 v[56:59], v[176:179], v[218:221], v[56:59]
	s_barrier
; #define PG8_STAGE(bufoff, gbase, voff) do { _Pragma("unroll") for (int _i = 0; _i < 2; ++_i) \
;         __builtin_amdgcn_global_load_lds((const unsigned*)((const char*)(gbase) + (voff)[_i]), (PG8_LAS unsigned*)(lds + (bufoff) + ldsw + _i * 8192), 16, 0, 0); } while (0)
; #define PG8_LDA(dst, b, h) do { _Pragma("unroll") for (int m = 0; m < 4; ++m) _Pragma("unroll") for (int k = 0; k < 2; ++k) dst[m][k] = *(const PG8_LAS bf16x8*)(lds + PG8_SA(b, h) + aoff + m * 2048 + k * 1024); } while (0)
; #define PG8_LDB(dst, b, h) do { _Pragma("unroll") for (int n = 0; n < 2; ++n) _Pragma("unroll") for (int k = 0; k < 2; ++k) dst[n][k] = *(const PG8_LAS bf16x8*)(lds + PG8_SB(b, h) + boff + n * 2048 + k * 1024); } while (0)
; #define PG8_MMA(ai, bj, At, Bt) do { __builtin_amdgcn_s_setprio(1); _Pragma("unroll") for (int m = 0; m < 4; ++m) _Pragma("unroll") for (int n = 0; n < 2; ++n) _Pragma("unroll") for (int k = 0; k < 2; ++k) \
;         acc[ai][bj][m][n] = __builtin_amdgcn_mfma_f32_16x16x32_bf16(Bt[n][k], At[m][k], acc[ai][bj][m][n], 0, 0, 0); __builtin_amdgcn_s_setprio(0); } while (0)
; #define PG8_WAIT_V(n) asm volatile("s_waitcnt vmcnt(" #n ")" ::: "memory")
; #define PG8_WAIT_L(n) asm volatile("s_waitcnt lgkmcnt(" #n ")" ::: "memory")
; #define PG8_BAR __builtin_amdgcn_s_barrier()
; #define PG8_SCHED __builtin_amdgcn_sched_barrier(0)
; template <class Epi, class Sched, bool ALIGN_EPI = false, bool SP2 = false>
; __device__ __forceinline__ void gemm_phase(PG8_LAS unsigned char* lds, const Gemm g, const Sched& S, const Epi& E) {
;     ...
;             PG8_LDB(B0, 0, 0); PG8_LDB(B1, 0, 1); PG8_SCHED; PG8_LDA(At, 0, 0); PG8_STAGE(PG8_SA(1, 1), a1 + hstep, voffA);
;             PG8_WAIT_V(8); PG8_WAIT_L(0); PG8_BAR; PG8_MMA(0, 0, At, B0); PG8_MMA(0, 1, At, B1); PG8_BAR; PG8_SCHED;
;     ...
;             PG8_LDA(At, 1, 1); PG8_STAGE(PG8_SB(1, 0), b3, voffB); PG8_STAGE(PG8_SB(1, 1), b3 + hstep, voffB); PG8_STAGE(PG8_SA(1, 0), a3, voffA);
;             PG8_WAIT_V(8); PG8_WAIT_L(0); PG8_BAR; PG8_MMA(1, 0, At, B0); PG8_MMA(1, 1, At, B1); PG8_BAR; PG8_SCHED;
	s_setprio 0
	s_sleep 2
	s_add_i32 s93, s93, s3
	s_add_i32 s90, s93, 0x2000
	v_lshl_add_u64 v[140:141], v[140:141], 0, s[36:37]
	s_mov_b32 m0, s93
	s_add_u32 s96, s60, 0x10180
	ds_read_b128 v[190:193], v149 offset:49152
	ds_read_b128 v[194:197], v149 offset:50176
	ds_read_b128 v[198:201], v149 offset:51200
	ds_read_b128 v[202:205], v149 offset:52224
	ds_read_b128 v[206:209], v149 offset:53248
	ds_read_b128 v[210:213], v149 offset:54272
	ds_read_b128 v[214:217], v149 offset:55296
	ds_read_b128 v[218:221], v149 offset:56320
	global_load_lds_dwordx4 v[140:141], off
	v_lshl_add_u64 v[140:141], v[180:181], 0, s[36:37]
	s_mov_b32 m0, s90
	s_addc_u32 s97, s61, 0
	s_add_i32 s60, s94, s3
	global_load_lds_dwordx4 v[140:141], off
	v_lshl_add_u64 v[140:141], s[96:97], 0, v[130:131]
	s_mov_b32 m0, s60
	s_add_i32 s61, s60, 0x2000
	global_load_lds_dwordx4 v[140:141], off
	v_lshl_add_u64 v[140:141], s[96:97], 0, v[128:129]
	s_mov_b32 m0, s61
	s_nop 0
	global_load_lds_dwordx4 v[140:141], off
	v_lshl_add_u64 v[140:141], v[188:189], 0, s[36:37]
	s_mov_b32 m0, s66
	s_nop 0
	global_load_lds_dwordx4 v[140:141], off
	v_lshl_add_u64 v[140:141], v[222:223], 0, s[36:37]
	s_mov_b32 m0, s67
	s_nop 0
	global_load_lds_dwordx4 v[140:141], off
	s_waitcnt vmcnt(8)
	s_waitcnt lgkmcnt(0)
	s_setprio 1
	s_barrier
	v_mfma_f32_16x16x32_bf16 v[0:3], v[24:27], v[214:217], v[0:3]
	v_mfma_f32_16x16x32_bf16 v[4:7], v[112:115], v[214:217], v[4:7]
	v_mfma_f32_16x16x32_bf16 v[136:139], v[24:27], v[190:193], v[136:139]
	v_mfma_f32_16x16x32_bf16 v[152:155], v[112:115], v[190:193], v[152:155]
	v_mfma_f32_16x16x32_bf16 v[156:159], v[24:27], v[198:201], v[156:159]
	v_mfma_f32_16x16x32_bf16 v[160:163], v[112:115], v[198:201], v[160:163]
	v_mfma_f32_16x16x32_bf16 v[164:167], v[24:27], v[206:209], v[164:167]
	v_mfma_f32_16x16x32_bf16 v[168:171], v[112:115], v[206:209], v[168:171]
	v_mfma_f32_16x16x32_bf16 v[0:3], v[28:31], v[218:221], v[0:3]
	v_mfma_f32_16x16x32_bf16 v[4:7], v[116:119], v[218:221], v[4:7]
	v_mfma_f32_16x16x32_bf16 v[136:139], v[28:31], v[194:197], v[136:139]
	v_mfma_f32_16x16x32_bf16 v[152:155], v[116:119], v[194:197], v[152:155]
	v_mfma_f32_16x16x32_bf16 v[156:159], v[28:31], v[202:205], v[156:159]
	v_mfma_f32_16x16x32_bf16 v[160:163], v[116:119], v[202:205], v[160:163]
	v_mfma_f32_16x16x32_bf16 v[164:167], v[28:31], v[210:213], v[164:167]
	v_mfma_f32_16x16x32_bf16 v[168:171], v[116:119], v[210:213], v[168:171]
	s_setprio 0
	s_setprio 1
	v_mfma_f32_16x16x32_bf16 v[8:11], v[120:123], v[190:193], v[8:11]
	v_mfma_f32_16x16x32_bf16 v[12:15], v[172:175], v[190:193], v[12:15]
	v_mfma_f32_16x16x32_bf16 v[24:27], v[120:123], v[198:201], v[60:63]
	v_mfma_f32_16x16x32_bf16 v[28:31], v[172:175], v[198:201], v[100:103]
	v_mfma_f32_16x16x32_bf16 v[60:63], v[120:123], v[206:209], v[104:107]
	v_mfma_f32_16x16x32_bf16 v[100:103], v[172:175], v[206:209], v[108:111]
	v_mfma_f32_16x16x32_bf16 v[16:19], v[120:123], v[214:217], v[16:19]
	v_mfma_f32_16x16x32_bf16 v[20:23], v[172:175], v[214:217], v[20:23]
	v_mfma_f32_16x16x32_bf16 v[8:11], v[124:127], v[194:197], v[8:11]
	v_mfma_f32_16x16x32_bf16 v[12:15], v[176:179], v[194:197], v[12:15]
	v_mfma_f32_16x16x32_bf16 v[24:27], v[124:127], v[202:205], v[24:27]
	v_mfma_f32_16x16x32_bf16 v[28:31], v[176:179], v[202:205], v[28:31]
	v_mfma_f32_16x16x32_bf16 v[60:63], v[124:127], v[210:213], v[60:63]
	v_mfma_f32_16x16x32_bf16 v[100:103], v[176:179], v[210:213], v[100:103]
	v_mfma_f32_16x16x32_bf16 v[16:19], v[124:127], v[218:221], v[16:19]
	v_mfma_f32_16x16x32_bf16 v[20:23], v[176:179], v[218:221], v[20:23]
	s_barrier
	s_setprio 0
	s_sleep 2
	ds_read_b128 v[104:107], v147
	ds_read_b128 v[108:111], v147 offset:1024
	ds_read_b128 v[112:115], v147 offset:2048
	ds_read_b128 v[116:119], v147 offset:3072
	ds_read_b128 v[120:123], v148
	ds_read_b128 v[124:127], v148 offset:1024
	ds_read_b128 v[172:175], v148 offset:2048
	ds_read_b128 v[176:179], v148 offset:3072
	s_add_u32 s48, s48, 0x10180
	s_addc_u32 s49, s49, 0
	s_mov_b32 m0, s92
	v_lshl_add_u64 v[140:141], s[48:49], 0, v[130:131]
	ds_read_b128 v[190:193], v149
	ds_read_b128 v[194:197], v149 offset:1024
	ds_read_b128 v[198:201], v149 offset:2048
	ds_read_b128 v[202:205], v149 offset:3072
	ds_read_b128 v[206:209], v149 offset:4096
	ds_read_b128 v[210:213], v149 offset:5120
	ds_read_b128 v[214:217], v149 offset:6144
	ds_read_b128 v[218:221], v149 offset:7168
	global_load_lds_dwordx4 v[140:141], off
	v_lshl_add_u64 v[140:141], s[48:49], 0, v[128:129]
	s_mov_b32 m0, s39
	s_nop 0
	global_load_lds_dwordx4 v[140:141], off
	s_waitcnt vmcnt(8)
	s_waitcnt lgkmcnt(0)
	s_setprio 1
	s_barrier
; #define PG8_STAGE(bufoff, gbase, voff) do { _Pragma("unroll") for (int _i = 0; _i < 2; ++_i) \
;         __builtin_amdgcn_global_load_lds((const unsigned*)((const char*)(gbase) + (voff)[_i]), (PG8_LAS unsigned*)(lds + (bufoff) + ldsw + _i * 8192), 16, 0, 0); } while (0)
; #define PG8_LDA(dst, b, h) do { _Pragma("unroll") for (int m = 0; m < 4; ++m) _Pragma("unroll") for (int k = 0; k < 2; ++k) dst[m][k] = *(const PG8_LAS bf16x8*)(lds + PG8_SA(b, h) + aoff + m * 2048 + k * 1024); } while (0)
; #define PG8_LDB(dst, b, h) do { _Pragma("unroll") for (int n = 0; n < 2; ++n) _Pragma("unroll") for (int k = 0; k < 2; ++k) dst[n][k] = *(const PG8_LAS bf16x8*)(lds + PG8_SB(b, h) + boff + n * 2048 + k * 1024); } while (0)
; #define PG8_MMA(ai, bj, At, Bt) do { __builtin_amdgcn_s_setprio(1); _Pragma("unroll") for (int m = 0; m < 4; ++m) _Pragma("unroll") for (int n = 0; n < 2; ++n) _Pragma("unroll") for (int k = 0; k < 2; ++k) \
;         acc[ai][bj][m][n] = __builtin_amdgcn_mfma_f32_16x16x32_bf16(Bt[n][k], At[m][k], acc[ai][bj][m][n], 0, 0, 0); __builtin_amdgcn_s_setprio(0); } while (0)
; #define PG8_WAIT_V(n) asm volatile("s_waitcnt vmcnt(" #n ")" ::: "memory")
; #define PG8_WAIT_L(n) asm volatile("s_waitcnt lgkmcnt(" #n ")" ::: "memory")
; #define PG8_BAR __builtin_amdgcn_s_barrier()
; #define PG8_SCHED __builtin_amdgcn_sched_barrier(0)
; template <class Epi, class Sched, bool ALIGN_EPI = false, bool SP2 = false>
; __device__ __forceinline__ void gemm_phase(PG8_LAS unsigned char* lds, const Gemm g, const Sched& S, const Epi& E) {
;     ...
;             PG8_LDB(B0, 0, 0); PG8_LDB(B1, 0, 1); PG8_SCHED; PG8_LDA(At, 0, 0); PG8_STAGE(PG8_SA(1, 1), a1 + hstep, voffA);
;             PG8_WAIT_V(8); PG8_WAIT_L(0); PG8_BAR; PG8_MMA(0, 0, At, B0); PG8_MMA(0, 1, At, B1); PG8_BAR; PG8_SCHED;
;             PG8_LDA(At, 0, 1); PG8_STAGE(PG8_SB(0, 0), b2, voffB); PG8_STAGE(PG8_SB(0, 1), b2 + hstep, voffB); PG8_STAGE(PG8_SA(0, 0), a2, voffA);
;             PG8_WAIT_V(8); PG8_WAIT_L(0); PG8_BAR; PG8_MMA(1, 0, At, B0); PG8_MMA(1, 1, At, B1); PG8_BAR; PG8_SCHED;
;             PG8_LDB(B0, 1, 0); PG8_LDB(B1, 1, 1); PG8_SCHED; PG8_LDA(At, 1, 0); PG8_STAGE(PG8_SA(0, 1), a2 + hstep, voffA);
;             PG8_WAIT_V(8); PG8_WAIT_L(0); PG8_BAR; PG8_MMA(0, 0, At, B0); PG8_MMA(0, 1, At, B1); PG8_BAR; PG8_SCHED;
	v_mfma_f32_16x16x32_bf16 v[64:67], v[104:107], v[190:193], v[64:67]
	v_mfma_f32_16x16x32_bf16 v[68:71], v[112:115], v[190:193], v[68:71]
	v_mfma_f32_16x16x32_bf16 v[72:75], v[104:107], v[198:201], v[72:75]
	v_mfma_f32_16x16x32_bf16 v[76:79], v[112:115], v[198:201], v[76:79]
	v_mfma_f32_16x16x32_bf16 v[80:83], v[104:107], v[206:209], v[80:83]
	v_mfma_f32_16x16x32_bf16 v[84:87], v[112:115], v[206:209], v[84:87]
	v_mfma_f32_16x16x32_bf16 v[88:91], v[104:107], v[214:217], v[88:91]
	v_mfma_f32_16x16x32_bf16 v[92:95], v[112:115], v[214:217], v[92:95]
	v_mfma_f32_16x16x32_bf16 v[64:67], v[108:111], v[194:197], v[64:67]
	v_mfma_f32_16x16x32_bf16 v[68:71], v[116:119], v[194:197], v[68:71]
	v_mfma_f32_16x16x32_bf16 v[72:75], v[108:111], v[202:205], v[72:75]
	v_mfma_f32_16x16x32_bf16 v[76:79], v[116:119], v[202:205], v[76:79]
	v_mfma_f32_16x16x32_bf16 v[80:83], v[108:111], v[210:213], v[80:83]
	v_mfma_f32_16x16x32_bf16 v[84:87], v[116:119], v[210:213], v[84:87]
	v_mfma_f32_16x16x32_bf16 v[88:91], v[108:111], v[218:221], v[88:91]
	v_mfma_f32_16x16x32_bf16 v[92:95], v[116:119], v[218:221], v[92:95]
	s_setprio 0
	s_setprio 1
	v_mfma_f32_16x16x32_bf16 v[32:35], v[172:175], v[190:193], v[32:35]
	v_mfma_f32_16x16x32_bf16 v[36:39], v[120:123], v[198:201], v[36:39]
	v_mfma_f32_16x16x32_bf16 v[40:43], v[172:175], v[198:201], v[40:43]
	v_mfma_f32_16x16x32_bf16 v[44:47], v[120:123], v[206:209], v[44:47]
	v_mfma_f32_16x16x32_bf16 v[48:51], v[172:175], v[206:209], v[48:51]
	v_mfma_f32_16x16x32_bf16 v[52:55], v[120:123], v[214:217], v[52:55]
	v_mfma_f32_16x16x32_bf16 v[56:59], v[172:175], v[214:217], v[56:59]
	v_mfma_f32_16x16x32_bf16 v[96:99], v[120:123], v[190:193], v[96:99]
	v_mfma_f32_16x16x32_bf16 v[32:35], v[176:179], v[194:197], v[32:35]
	v_mfma_f32_16x16x32_bf16 v[36:39], v[124:127], v[202:205], v[36:39]
	v_mfma_f32_16x16x32_bf16 v[40:43], v[176:179], v[202:205], v[40:43]
	v_mfma_f32_16x16x32_bf16 v[44:47], v[124:127], v[210:213], v[44:47]
	v_mfma_f32_16x16x32_bf16 v[48:51], v[176:179], v[210:213], v[48:51]
	v_mfma_f32_16x16x32_bf16 v[52:55], v[124:127], v[218:221], v[52:55]
	v_mfma_f32_16x16x32_bf16 v[56:59], v[176:179], v[218:221], v[56:59]
	v_mfma_f32_16x16x32_bf16 v[222:225], v[124:127], v[194:197], v[96:99]
	s_barrier
	s_setprio 0
	s_sleep 2
	s_mov_b32 m0, s89
	v_lshl_add_u64 v[140:141], s[58:59], 0, v[130:131]
	s_add_u32 s48, s58, 0x10000
	ds_read_b128 v[96:99], v149 offset:16384
	ds_read_b128 v[190:193], v149 offset:17408
	ds_read_b128 v[194:197], v149 offset:18432
	ds_read_b128 v[198:201], v149 offset:19456
	ds_read_b128 v[202:205], v149 offset:20480
	ds_read_b128 v[206:209], v149 offset:21504
	ds_read_b128 v[210:213], v149 offset:22528
	ds_read_b128 v[214:217], v149 offset:23552
	global_load_lds_dwordx4 v[140:141], off
	v_lshl_add_u64 v[180:181], s[58:59], 0, v[128:129]
	s_mov_b32 m0, s41
	s_addc_u32 s49, s59, 0
	global_load_lds_dwordx4 v[180:181], off
	v_lshl_add_u64 v[188:189], s[48:49], 0, v[130:131]
	s_mov_b32 m0, s86
	v_lshl_add_u64 v[250:251], s[62:63], 0, v[128:129]
	global_load_lds_dwordx4 v[188:189], off
	v_lshl_add_u64 v[188:189], s[48:49], 0, v[128:129]
	s_mov_b32 m0, s87
	s_nop 0
	global_load_lds_dwordx4 v[188:189], off
	v_lshl_add_u64 v[188:189], s[62:63], 0, v[130:131]
	s_mov_b32 m0, s35
	s_nop 0
	global_load_lds_dwordx4 v[188:189], off
	s_mov_b32 m0, s47
	s_nop 0
	global_load_lds_dwordx4 v[250:251], off
	s_waitcnt vmcnt(8)
	s_waitcnt lgkmcnt(0)
	s_setprio 1
	s_barrier
	v_mfma_f32_16x16x32_bf16 v[0:3], v[104:107], v[210:213], v[0:3]
	v_mfma_f32_16x16x32_bf16 v[4:7], v[112:115], v[210:213], v[4:7]
	v_mfma_f32_16x16x32_bf16 v[136:139], v[104:107], v[96:99], v[136:139]
	v_mfma_f32_16x16x32_bf16 v[152:155], v[112:115], v[96:99], v[152:155]
	v_mfma_f32_16x16x32_bf16 v[156:159], v[104:107], v[194:197], v[156:159]
	v_mfma_f32_16x16x32_bf16 v[160:163], v[112:115], v[194:197], v[160:163]
	v_mfma_f32_16x16x32_bf16 v[164:167], v[104:107], v[202:205], v[164:167]
	v_mfma_f32_16x16x32_bf16 v[168:171], v[112:115], v[202:205], v[168:171]
	v_mfma_f32_16x16x32_bf16 v[0:3], v[108:111], v[214:217], v[0:3]
	v_mfma_f32_16x16x32_bf16 v[4:7], v[116:119], v[214:217], v[4:7]
	v_mfma_f32_16x16x32_bf16 v[136:139], v[108:111], v[190:193], v[136:139]
	v_mfma_f32_16x16x32_bf16 v[152:155], v[116:119], v[190:193], v[152:155]
	v_mfma_f32_16x16x32_bf16 v[156:159], v[108:111], v[198:201], v[156:159]
	v_mfma_f32_16x16x32_bf16 v[160:163], v[116:119], v[198:201], v[160:163]
	v_mfma_f32_16x16x32_bf16 v[164:167], v[108:111], v[206:209], v[164:167]
	v_mfma_f32_16x16x32_bf16 v[168:171], v[116:119], v[206:209], v[168:171]
	s_setprio 0
	s_setprio 1
	v_mfma_f32_16x16x32_bf16 v[8:11], v[120:123], v[96:99], v[8:11]
	v_mfma_f32_16x16x32_bf16 v[12:15], v[172:175], v[96:99], v[12:15]
	v_mfma_f32_16x16x32_bf16 v[24:27], v[120:123], v[194:197], v[24:27]
	v_mfma_f32_16x16x32_bf16 v[28:31], v[172:175], v[194:197], v[28:31]
	v_mfma_f32_16x16x32_bf16 v[60:63], v[120:123], v[202:205], v[60:63]
	v_mfma_f32_16x16x32_bf16 v[16:19], v[120:123], v[210:213], v[16:19]
	v_mfma_f32_16x16x32_bf16 v[8:11], v[124:127], v[190:193], v[8:11]
	v_mfma_f32_16x16x32_bf16 v[12:15], v[176:179], v[190:193], v[12:15]
	v_mfma_f32_16x16x32_bf16 v[24:27], v[124:127], v[198:201], v[24:27]
	v_mfma_f32_16x16x32_bf16 v[28:31], v[176:179], v[198:201], v[28:31]
	v_mfma_f32_16x16x32_bf16 v[190:193], v[124:127], v[206:209], v[60:63]
	v_mfma_f32_16x16x32_bf16 v[60:63], v[172:175], v[202:205], v[100:103]
	v_mfma_f32_16x16x32_bf16 v[198:201], v[124:127], v[214:217], v[16:19]
	v_mfma_f32_16x16x32_bf16 v[16:19], v[172:175], v[210:213], v[20:23]
	v_mfma_f32_16x16x32_bf16 v[194:197], v[176:179], v[206:209], v[60:63]
	v_mfma_f32_16x16x32_bf16 v[172:175], v[176:179], v[214:217], v[16:19]
	s_barrier
; #define PG8_STAGE(bufoff, gbase, voff) do { _Pragma("unroll") for (int _i = 0; _i < 2; ++_i) \
;         __builtin_amdgcn_global_load_lds((const unsigned*)((const char*)(gbase) + (voff)[_i]), (PG8_LAS unsigned*)(lds + (bufoff) + ldsw + _i * 8192), 16, 0, 0); } while (0)
; #define PG8_LDA(dst, b, h) do { _Pragma("unroll") for (int m = 0; m < 4; ++m) _Pragma("unroll") for (int k = 0; k < 2; ++k) dst[m][k] = *(const PG8_LAS bf16x8*)(lds + PG8_SA(b, h) + aoff + m * 2048 + k * 1024); } while (0)
; #define PG8_LDB(dst, b, h) do { _Pragma("unroll") for (int n = 0; n < 2; ++n) _Pragma("unroll") for (int k = 0; k < 2; ++k) dst[n][k] = *(const PG8_LAS bf16x8*)(lds + PG8_SB(b, h) + boff + n * 2048 + k * 1024); } while (0)
; #define PG8_MMA(ai, bj, At, Bt) do { __builtin_amdgcn_s_setprio(1); _Pragma("unroll") for (int m = 0; m < 4; ++m) _Pragma("unroll") for (int n = 0; n < 2; ++n) _Pragma("unroll") for (int k = 0; k < 2; ++k) \
;         acc[ai][bj][m][n] = __builtin_amdgcn_mfma_f32_16x16x32_bf16(Bt[n][k], At[m][k], acc[ai][bj][m][n], 0, 0, 0); __builtin_amdgcn_s_setprio(0); } while (0)
; #define PG8_WAIT_V(n) asm volatile("s_waitcnt vmcnt(" #n ")" ::: "memory")
; #define PG8_WAIT_L(n) asm volatile("s_waitcnt lgkmcnt(" #n ")" ::: "memory")
; #define PG8_BAR __builtin_amdgcn_s_barrier()
; #define PG8_SCHED __builtin_amdgcn_sched_barrier(0)
; template <class Epi, class Sched, bool ALIGN_EPI = false, bool SP2 = false>
; __device__ __forceinline__ void gemm_phase(PG8_LAS unsigned char* lds, const Gemm g, const Sched& S, const Epi& E) {
;     ...
;             PG8_LDB(B0, 1, 0); PG8_LDB(B1, 1, 1); PG8_SCHED; PG8_LDA(At, 1, 0); PG8_STAGE(PG8_SA(0, 1), a2 + hstep, voffA);
;             PG8_WAIT_V(8); PG8_WAIT_L(0); PG8_BAR; PG8_MMA(0, 0, At, B0); PG8_MMA(0, 1, At, B1); PG8_BAR; PG8_SCHED;
;             PG8_LDA(At, 1, 1); PG8_STAGE(PG8_SB(1, 0), b3, voffB); PG8_STAGE(PG8_SB(1, 1), b3 + hstep, voffB); PG8_STAGE(PG8_SA(1, 0), a3, voffA);
;             PG8_WAIT_V(8); PG8_WAIT_L(0); PG8_BAR; PG8_MMA(1, 0, At, B0); PG8_MMA(1, 1, At, B1); PG8_BAR; PG8_SCHED;
;     ...
;         if constexpr (ALIGN_EPI) { if (wr == 0) PG8_BAR; }
;         if constexpr (!Epi::AFTER_DRAIN) { E(acc, cur, wr, wc, fr, fq); S.done(cur); }
;         if (!has_next) break;
	s_setprio 0
	s_sleep 2
	s_nop 1
	ds_read_b128 v[60:63], v226
	ds_read_b128 v[176:179], v226 offset:1024
	ds_read_b128 v[202:205], v226 offset:2048
	ds_read_b128 v[206:209], v226 offset:3072
	ds_read_b128 v[210:213], v227
	ds_read_b128 v[214:217], v227 offset:1024
	ds_read_b128 v[218:221], v227 offset:2048
	ds_read_b128 v[226:229], v227 offset:3072
	s_add_u32 s48, s62, 0x10000
	s_addc_u32 s49, s63, 0
	s_mov_b32 m0, s64
	v_lshl_add_u64 v[96:97], s[48:49], 0, v[130:131]
	ds_read_b128 v[16:19], v149 offset:32768
	ds_read_b128 v[20:23], v149 offset:33792
	ds_read_b128 v[104:107], v149 offset:34816
	ds_read_b128 v[230:233], v149 offset:35840
	ds_read_b128 v[234:237], v149 offset:36864
	ds_read_b128 v[238:241], v149 offset:37888
	ds_read_b128 v[242:245], v149 offset:38912
	ds_read_b128 v[246:249], v149 offset:39936
	global_load_lds_dwordx4 v[96:97], off
	v_lshl_add_u64 v[96:97], s[48:49], 0, v[128:129]
	s_mov_b32 m0, s65
	s_nop 0
	global_load_lds_dwordx4 v[96:97], off
	s_waitcnt vmcnt(8)
	s_waitcnt lgkmcnt(0)
	s_setprio 1
	s_barrier
	v_mfma_f32_16x16x32_bf16 v[64:67], v[60:63], v[16:19], v[64:67]
	v_mfma_f32_16x16x32_bf16 v[112:115], v[176:179], v[20:23], v[64:67]
	v_mfma_f32_16x16x32_bf16 v[64:67], v[202:205], v[16:19], v[68:71]
	v_mfma_f32_16x16x32_bf16 v[116:119], v[206:209], v[20:23], v[64:67]
	v_mfma_f32_16x16x32_bf16 v[64:67], v[60:63], v[104:107], v[72:75]
	v_mfma_f32_16x16x32_bf16 v[96:99], v[176:179], v[230:233], v[64:67]
	v_mfma_f32_16x16x32_bf16 v[64:67], v[202:205], v[104:107], v[76:79]
	v_mfma_f32_16x16x32_bf16 v[100:103], v[206:209], v[230:233], v[64:67]
	v_mfma_f32_16x16x32_bf16 v[64:67], v[60:63], v[234:237], v[80:83]
	v_mfma_f32_16x16x32_bf16 v[80:83], v[176:179], v[238:241], v[64:67]
	v_mfma_f32_16x16x32_bf16 v[64:67], v[202:205], v[234:237], v[84:87]
	v_mfma_f32_16x16x32_bf16 v[84:87], v[206:209], v[238:241], v[64:67]
	v_mfma_f32_16x16x32_bf16 v[64:67], v[60:63], v[242:245], v[88:91]
	v_mfma_f32_16x16x32_bf16 v[68:71], v[202:205], v[242:245], v[92:95]
	v_mfma_f32_16x16x32_bf16 v[64:67], v[176:179], v[246:249], v[64:67]
	v_mfma_f32_16x16x32_bf16 v[68:71], v[206:209], v[246:249], v[68:71]
	s_setprio 0
	s_setprio 1
	v_mfma_f32_16x16x32_bf16 v[72:75], v[210:213], v[16:19], v[222:225]
	v_mfma_f32_16x16x32_bf16 v[16:19], v[218:221], v[16:19], v[32:35]
	v_mfma_f32_16x16x32_bf16 v[120:123], v[226:229], v[20:23], v[16:19]
	v_mfma_f32_16x16x32_bf16 v[16:19], v[210:213], v[104:107], v[36:39]
	v_mfma_f32_16x16x32_bf16 v[108:111], v[214:217], v[230:233], v[16:19]
	v_mfma_f32_16x16x32_bf16 v[16:19], v[218:221], v[104:107], v[40:43]
	v_mfma_f32_16x16x32_bf16 v[104:107], v[226:229], v[230:233], v[16:19]
	v_mfma_f32_16x16x32_bf16 v[16:19], v[210:213], v[234:237], v[44:47]
	v_mfma_f32_16x16x32_bf16 v[92:95], v[214:217], v[238:241], v[16:19]
	v_mfma_f32_16x16x32_bf16 v[16:19], v[218:221], v[234:237], v[48:51]
	v_mfma_f32_16x16x32_bf16 v[88:91], v[226:229], v[238:241], v[16:19]
	v_mfma_f32_16x16x32_bf16 v[16:19], v[210:213], v[242:245], v[52:55]
	v_mfma_f32_16x16x32_bf16 v[76:79], v[214:217], v[246:249], v[16:19]
	v_mfma_f32_16x16x32_bf16 v[16:19], v[218:221], v[242:245], v[56:59]
	v_mfma_f32_16x16x32_bf16 v[124:127], v[214:217], v[20:23], v[72:75]
	v_mfma_f32_16x16x32_bf16 v[72:75], v[226:229], v[246:249], v[16:19]
	s_barrier
	s_setprio 0
	s_sleep 2
	s_mov_b32 m0, s93
	s_nop 2
	v_lshl_add_u64 v[16:17], v[140:141], 0, s[6:7]
	s_add_u32 s48, s58, 0x10080
	ds_read_b128 v[40:43], v149 offset:49152
	ds_read_b128 v[44:47], v149 offset:50176
	ds_read_b128 v[222:225], v149 offset:51200
	ds_read_b128 v[230:233], v149 offset:52224
	ds_read_b128 v[234:237], v149 offset:53248
	ds_read_b128 v[238:241], v149 offset:54272
	ds_read_b128 v[242:245], v149 offset:55296
	ds_read_b128 v[246:249], v149 offset:56320
	global_load_lds_dwordx4 v[16:17], off
	v_lshl_add_u64 v[16:17], v[180:181], 0, s[6:7]
	s_mov_b32 m0, s90
	s_addc_u32 s49, s59, 0
	global_load_lds_dwordx4 v[16:17], off
	v_lshl_add_u64 v[16:17], s[48:49], 0, v[130:131]
	s_mov_b32 m0, s60
	s_nop 0
	global_load_lds_dwordx4 v[16:17], off
	v_lshl_add_u64 v[16:17], s[48:49], 0, v[128:129]
	s_mov_b32 m0, s61
	s_nop 0
	global_load_lds_dwordx4 v[16:17], off
	v_lshl_add_u64 v[16:17], v[188:189], 0, s[6:7]
	s_mov_b32 m0, s66
	s_nop 0
	global_load_lds_dwordx4 v[16:17], off
	v_lshl_add_u64 v[16:17], v[250:251], 0, s[6:7]
	s_mov_b32 m0, s67
	s_nop 0
	global_load_lds_dwordx4 v[16:17], off
	s_waitcnt vmcnt(8)
	s_waitcnt lgkmcnt(0)
	s_setprio 1
	s_barrier
	v_mfma_f32_16x16x32_bf16 v[16:19], v[60:63], v[40:43], v[136:139]
	v_mfma_f32_16x16x32_bf16 v[48:51], v[176:179], v[44:47], v[16:19]
	v_mfma_f32_16x16x32_bf16 v[16:19], v[202:205], v[40:43], v[152:155]
	v_mfma_f32_16x16x32_bf16 v[52:55], v[206:209], v[44:47], v[16:19]
	v_mfma_f32_16x16x32_bf16 v[16:19], v[60:63], v[222:225], v[156:159]
	v_mfma_f32_16x16x32_bf16 v[32:35], v[176:179], v[230:233], v[16:19]
	v_mfma_f32_16x16x32_bf16 v[16:19], v[202:205], v[222:225], v[160:163]
	v_mfma_f32_16x16x32_bf16 v[36:39], v[206:209], v[230:233], v[16:19]
	v_mfma_f32_16x16x32_bf16 v[16:19], v[60:63], v[234:237], v[164:167]
	v_mfma_f32_16x16x32_bf16 v[20:23], v[202:205], v[234:237], v[168:171]
	v_mfma_f32_16x16x32_bf16 v[0:3], v[60:63], v[242:245], v[0:3]
	v_mfma_f32_16x16x32_bf16 v[4:7], v[202:205], v[242:245], v[4:7]
	v_mfma_f32_16x16x32_bf16 v[16:19], v[176:179], v[238:241], v[16:19]
	v_mfma_f32_16x16x32_bf16 v[20:23], v[206:209], v[238:241], v[20:23]
	v_mfma_f32_16x16x32_bf16 v[0:3], v[176:179], v[246:249], v[0:3]
	v_mfma_f32_16x16x32_bf16 v[4:7], v[206:209], v[246:249], v[4:7]
	s_setprio 0
	s_setprio 1
	v_mfma_f32_16x16x32_bf16 v[8:11], v[210:213], v[40:43], v[8:11]
	v_mfma_f32_16x16x32_bf16 v[60:63], v[214:217], v[44:47], v[8:11]
	v_mfma_f32_16x16x32_bf16 v[8:11], v[218:221], v[40:43], v[12:15]
	v_mfma_f32_16x16x32_bf16 v[56:59], v[226:229], v[44:47], v[8:11]
	v_mfma_f32_16x16x32_bf16 v[8:11], v[210:213], v[222:225], v[24:27]
	v_mfma_f32_16x16x32_bf16 v[44:47], v[214:217], v[230:233], v[8:11]
	v_mfma_f32_16x16x32_bf16 v[8:11], v[218:221], v[222:225], v[28:31]
	v_mfma_f32_16x16x32_bf16 v[40:43], v[226:229], v[230:233], v[8:11]
	v_mfma_f32_16x16x32_bf16 v[8:11], v[210:213], v[234:237], v[190:193]
	v_mfma_f32_16x16x32_bf16 v[28:31], v[214:217], v[238:241], v[8:11]
	v_mfma_f32_16x16x32_bf16 v[8:11], v[218:221], v[234:237], v[194:197]
	v_mfma_f32_16x16x32_bf16 v[24:27], v[226:229], v[238:241], v[8:11]
	v_mfma_f32_16x16x32_bf16 v[8:11], v[210:213], v[242:245], v[198:201]
	v_mfma_f32_16x16x32_bf16 v[12:15], v[218:221], v[242:245], v[172:175]
	v_mfma_f32_16x16x32_bf16 v[8:11], v[214:217], v[246:249], v[8:11]
	v_mfma_f32_16x16x32_bf16 v[12:15], v[226:229], v[246:249], v[12:15]
	s_barrier
	s_setprio 0
	s_sleep 2
	s_andn2_b64 vcc, exec, s[8:9]
	s_cbranch_vccnz .LBB0_183
	s_barrier

; #define PG8_STAGE(bufoff, gbase, voff) do { _Pragma("unroll") for (int _i = 0; _i < 2; ++_i) \
;         __builtin_amdgcn_global_load_lds((const unsigned*)((const char*)(gbase) + (voff)[_i]), (PG8_LAS unsigned*)(lds + (bufoff) + ldsw + _i * 8192), 16, 0, 0); } while (0)
; #define PG8_LDA(dst, b, h) do { _Pragma("unroll") for (int m = 0; m < 4; ++m) _Pragma("unroll") for (int k = 0; k < 2; ++k) dst[m][k] = *(const PG8_LAS bf16x8*)(lds + PG8_SA(b, h) + aoff + m * 2048 + k * 1024); } while (0)
; #define PG8_LDB(dst, b, h) do { _Pragma("unroll") for (int n = 0; n < 2; ++n) _Pragma("unroll") for (int k = 0; k < 2; ++k) dst[n][k] = *(const PG8_LAS bf16x8*)(lds + PG8_SB(b, h) + boff + n * 2048 + k * 1024); } while (0)
; #define PG8_MMA(ai, bj, At, Bt) do { __builtin_amdgcn_s_setprio(1); _Pragma("unroll") for (int m = 0; m < 4; ++m) _Pragma("unroll") for (int n = 0; n < 2; ++n) _Pragma("unroll") for (int k = 0; k < 2; ++k) \
;         acc[ai][bj][m][n] = __builtin_amdgcn_mfma_f32_16x16x32_bf16(Bt[n][k], At[m][k], acc[ai][bj][m][n], 0, 0, 0); __builtin_amdgcn_s_setprio(0); } while (0)
; #define PG8_WAIT_V(n) asm volatile("s_waitcnt vmcnt(" #n ")" ::: "memory")
; #define PG8_WAIT_L(n) asm volatile("s_waitcnt lgkmcnt(" #n ")" ::: "memory")
; template <class Epi, class Sched, bool ALIGN_EPI = false, bool SP2 = false>
; __device__ __forceinline__ void gemm_phase(PG8_LAS unsigned char* lds, const Gemm g, const Sched& S, const Epi& E) {
;     ...
;             const bool last = (t == nt - 2);
;             const char* a1 = cA + (size_t)(t + 1) * kstep;
;             const char* a2 = last ? nA : cA + (size_t)(t + 2) * kstep; const char* b2 = last ? nB : cB + (size_t)(t + 2) * kstep;
;             const char* a3 = a2 + kstep; const char* b3 = b2 + kstep;
;             if (last && has_next) S.a_ready(nxt);
;             if constexpr (SP2) {
;             PG8_LDB(B0, 0, 0); PG8_LDB(B1, 0, 1); PG8_SCHED; PG8_LDA(At, 0, 0); PG8_STAGE(PG8_SA(1, 1), a1 + hstep, voffA);
;             PG8_WAIT_V(8); PG8_WAIT_L(0); PG8_BAR; PG8_MMA(0, 0, At, B0); PG8_MMA(0, 1, At, B1); PG8_BAR; PG8_SCHED;
;             PG8_LDA(At, 0, 1); PG8_STAGE(PG8_SB(0, 0), b2, voffB); PG8_STAGE(PG8_SB(0, 1), b2 + hstep, voffB); PG8_STAGE(PG8_SA(0, 0), a2, voffA);
;             PG8_WAIT_V(8); PG8_WAIT_L(0); PG8_BAR; PG8_MMA(1, 0, At, B0); PG8_MMA(1, 1, At, B1); PG8_BAR; PG8_SCHED;
.LBB0_199:
	ds_read_b128 v[146:149], v162
	ds_read_b128 v[172:175], v162 offset:1024
	ds_read_b128 v[176:179], v162 offset:2048
	ds_read_b128 v[190:193], v162 offset:3072
	ds_read_b128 v[194:197], v163
	ds_read_b128 v[198:201], v163 offset:1024
	ds_read_b128 v[202:205], v163 offset:2048
	ds_read_b128 v[206:209], v163 offset:3072
	s_add_u32 s60, s58, 0xfff80080
	s_addc_u32 s61, s59, -1
	s_cmp_eq_u32 s94, 28
	s_cselect_b32 s63, s9, s61
	s_cselect_b32 s62, s43, s60
	s_cselect_b32 s61, s41, s93
	s_cselect_b32 s60, s90, s92
	v_lshl_add_u64 v[150:151], s[58:59], 0, v[136:137]
	s_add_i32 m0, s28, 0xc000
	ds_read_b128 v[210:213], v164
	ds_read_b128 v[214:217], v164 offset:1024
	ds_read_b128 v[218:221], v164 offset:2048
	ds_read_b128 v[222:225], v164 offset:3072
	ds_read_b128 v[226:229], v164 offset:4096
	ds_read_b128 v[230:233], v164 offset:5120
	ds_read_b128 v[234:237], v164 offset:6144
	ds_read_b128 v[238:241], v164 offset:7168
	global_load_lds_dwordx4 v[150:151], off
	v_lshl_add_u64 v[150:151], s[58:59], 0, v[138:139]
	s_add_i32 m0, s28, 0xe000
	s_nop 0
	global_load_lds_dwordx4 v[150:151], off
	s_waitcnt vmcnt(8)
	s_waitcnt lgkmcnt(0)
	s_setprio 1
	s_barrier
	v_mfma_f32_16x16x32_bf16 v[124:127], v[146:149], v[210:213], v[124:127]
	v_mfma_f32_16x16x32_bf16 v[120:123], v[176:179], v[210:213], v[120:123]
	v_mfma_f32_16x16x32_bf16 v[108:111], v[146:149], v[218:221], v[108:111]
	v_mfma_f32_16x16x32_bf16 v[104:107], v[176:179], v[218:221], v[104:107]
	v_mfma_f32_16x16x32_bf16 v[92:95], v[146:149], v[226:229], v[92:95]
	v_mfma_f32_16x16x32_bf16 v[88:91], v[176:179], v[226:229], v[88:91]
	v_mfma_f32_16x16x32_bf16 v[76:79], v[146:149], v[234:237], v[76:79]
	v_mfma_f32_16x16x32_bf16 v[72:75], v[176:179], v[234:237], v[72:75]
	v_mfma_f32_16x16x32_bf16 v[124:127], v[172:175], v[214:217], v[124:127]
	v_mfma_f32_16x16x32_bf16 v[120:123], v[190:193], v[214:217], v[120:123]
	v_mfma_f32_16x16x32_bf16 v[108:111], v[172:175], v[222:225], v[108:111]
	v_mfma_f32_16x16x32_bf16 v[104:107], v[190:193], v[222:225], v[104:107]
	v_mfma_f32_16x16x32_bf16 v[92:95], v[172:175], v[230:233], v[92:95]
	v_mfma_f32_16x16x32_bf16 v[88:91], v[190:193], v[230:233], v[88:91]
	v_mfma_f32_16x16x32_bf16 v[76:79], v[172:175], v[238:241], v[76:79]
	v_mfma_f32_16x16x32_bf16 v[72:75], v[190:193], v[238:241], v[72:75]
	s_setprio 0
	s_setprio 1
	v_mfma_f32_16x16x32_bf16 v[116:119], v[194:197], v[210:213], v[116:119]
	v_mfma_f32_16x16x32_bf16 v[112:115], v[202:205], v[210:213], v[112:115]
	v_mfma_f32_16x16x32_bf16 v[100:103], v[194:197], v[218:221], v[100:103]
	v_mfma_f32_16x16x32_bf16 v[96:99], v[202:205], v[218:221], v[96:99]
	v_mfma_f32_16x16x32_bf16 v[84:87], v[194:197], v[226:229], v[84:87]
	v_mfma_f32_16x16x32_bf16 v[80:83], v[202:205], v[226:229], v[80:83]
	v_mfma_f32_16x16x32_bf16 v[68:71], v[194:197], v[234:237], v[68:71]
	v_mfma_f32_16x16x32_bf16 v[64:67], v[202:205], v[234:237], v[64:67]
	v_mfma_f32_16x16x32_bf16 v[116:119], v[198:201], v[214:217], v[116:119]
	v_mfma_f32_16x16x32_bf16 v[112:115], v[206:209], v[214:217], v[112:115]
	v_mfma_f32_16x16x32_bf16 v[100:103], v[198:201], v[222:225], v[100:103]
	v_mfma_f32_16x16x32_bf16 v[96:99], v[206:209], v[222:225], v[96:99]
	v_mfma_f32_16x16x32_bf16 v[84:87], v[198:201], v[230:233], v[84:87]
	v_mfma_f32_16x16x32_bf16 v[80:83], v[206:209], v[230:233], v[80:83]
	v_mfma_f32_16x16x32_bf16 v[68:71], v[198:201], v[238:241], v[68:71]
	v_mfma_f32_16x16x32_bf16 v[64:67], v[206:209], v[238:241], v[64:67]
	s_barrier
	s_setprio 0
	s_sleep 2
	s_add_i32 s95, s84, s3
	v_lshl_add_u64 v[150:151], s[60:61], 0, v[130:131]
	s_mov_b32 m0, s95
	ds_read_b128 v[210:213], v164 offset:16384
	ds_read_b128 v[214:217], v164 offset:17408
	ds_read_b128 v[218:221], v164 offset:18432
	ds_read_b128 v[222:225], v164 offset:19456
	ds_read_b128 v[226:229], v164 offset:20480
	ds_read_b128 v[230:233], v164 offset:21504
	ds_read_b128 v[234:237], v164 offset:22528
	ds_read_b128 v[238:241], v164 offset:23552
	global_load_lds_dwordx4 v[150:151], off
	s_add_i32 m0, s95, 0x2000
	s_add_u32 s96, s60, 0x80000
	v_lshl_add_u64 v[180:181], s[60:61], 0, v[134:135]
	s_addc_u32 s97, s61, 0
	s_add_i32 s95, s85, s3
	global_load_lds_dwordx4 v[180:181], off
	v_lshl_add_u64 v[188:189], s[96:97], 0, v[130:131]
	s_mov_b32 m0, s95
	v_lshl_add_u64 v[242:243], s[62:63], 0, v[132:133]
	global_load_lds_dwordx4 v[188:189], off
	v_lshl_add_u64 v[188:189], s[96:97], 0, v[134:135]
	s_add_i32 m0, s95, 0x2000
	s_nop 0
	global_load_lds_dwordx4 v[188:189], off
	v_lshl_add_u64 v[188:189], s[62:63], 0, v[128:129]
	s_mov_b32 m0, s28
	s_nop 0
	global_load_lds_dwordx4 v[188:189], off
	s_mov_b32 m0, s29
	s_nop 0
	global_load_lds_dwordx4 v[242:243], off
	s_waitcnt vmcnt(8)
	s_waitcnt lgkmcnt(0)
	s_setprio 1
	s_barrier
; #define PG8_STAGE(bufoff, gbase, voff) do { _Pragma("unroll") for (int _i = 0; _i < 2; ++_i) \
;         __builtin_amdgcn_global_load_lds((const unsigned*)((const char*)(gbase) + (voff)[_i]), (PG8_LAS unsigned*)(lds + (bufoff) + ldsw + _i * 8192), 16, 0, 0); } while (0)
; #define PG8_LDA(dst, b, h) do { _Pragma("unroll") for (int m = 0; m < 4; ++m) _Pragma("unroll") for (int k = 0; k < 2; ++k) dst[m][k] = *(const PG8_LAS bf16x8*)(lds + PG8_SA(b, h) + aoff + m * 2048 + k * 1024); } while (0)
; #define PG8_LDB(dst, b, h) do { _Pragma("unroll") for (int n = 0; n < 2; ++n) _Pragma("unroll") for (int k = 0; k < 2; ++k) dst[n][k] = *(const PG8_LAS bf16x8*)(lds + PG8_SB(b, h) + boff + n * 2048 + k * 1024); } while (0)
; #define PG8_MMA(ai, bj, At, Bt) do { __builtin_amdgcn_s_setprio(1); _Pragma("unroll") for (int m = 0; m < 4; ++m) _Pragma("unroll") for (int n = 0; n < 2; ++n) _Pragma("unroll") for (int k = 0; k < 2; ++k) \
;         acc[ai][bj][m][n] = __builtin_amdgcn_mfma_f32_16x16x32_bf16(Bt[n][k], At[m][k], acc[ai][bj][m][n], 0, 0, 0); __builtin_amdgcn_s_setprio(0); } while (0)
; #define PG8_WAIT_V(n) asm volatile("s_waitcnt vmcnt(" #n ")" ::: "memory")
; #define PG8_WAIT_L(n) asm volatile("s_waitcnt lgkmcnt(" #n ")" ::: "memory")
; #define PG8_BAR __builtin_amdgcn_s_barrier()
; #define PG8_SCHED __builtin_amdgcn_sched_barrier(0)
; template <class Epi, class Sched, bool ALIGN_EPI = false, bool SP2 = false>
; __device__ __forceinline__ void gemm_phase(PG8_LAS unsigned char* lds, const Gemm g, const Sched& S, const Epi& E) {
;     ...
;             PG8_WAIT_V(8); PG8_WAIT_L(0); PG8_BAR; PG8_MMA(1, 0, At, B0); PG8_MMA(1, 1, At, B1); PG8_BAR; PG8_SCHED;
;             PG8_LDB(B0, 1, 0); PG8_LDB(B1, 1, 1); PG8_SCHED; PG8_LDA(At, 1, 0); PG8_STAGE(PG8_SA(0, 1), a2 + hstep, voffA);
;             PG8_WAIT_V(8); PG8_WAIT_L(0); PG8_BAR; PG8_MMA(0, 0, At, B0); PG8_MMA(0, 1, At, B1); PG8_BAR; PG8_SCHED;
;             PG8_LDA(At, 1, 1); PG8_STAGE(PG8_SB(1, 0), b3, voffB); PG8_STAGE(PG8_SB(1, 1), b3 + hstep, voffB); PG8_STAGE(PG8_SA(1, 0), a3, voffA);
;             PG8_WAIT_V(8); PG8_WAIT_L(0); PG8_BAR; PG8_MMA(1, 0, At, B0); PG8_MMA(1, 1, At, B1); PG8_BAR; PG8_SCHED;
	v_mfma_f32_16x16x32_bf16 v[60:63], v[146:149], v[210:213], v[60:63]
	v_mfma_f32_16x16x32_bf16 v[56:59], v[176:179], v[210:213], v[56:59]
	v_mfma_f32_16x16x32_bf16 v[44:47], v[146:149], v[218:221], v[44:47]
	v_mfma_f32_16x16x32_bf16 v[40:43], v[176:179], v[218:221], v[40:43]
	v_mfma_f32_16x16x32_bf16 v[28:31], v[146:149], v[226:229], v[28:31]
	v_mfma_f32_16x16x32_bf16 v[24:27], v[176:179], v[226:229], v[24:27]
	v_mfma_f32_16x16x32_bf16 v[12:15], v[146:149], v[234:237], v[12:15]
	v_mfma_f32_16x16x32_bf16 v[8:11], v[176:179], v[234:237], v[8:11]
	v_mfma_f32_16x16x32_bf16 v[60:63], v[172:175], v[214:217], v[60:63]
	v_mfma_f32_16x16x32_bf16 v[56:59], v[190:193], v[214:217], v[56:59]
	v_mfma_f32_16x16x32_bf16 v[44:47], v[172:175], v[222:225], v[44:47]
	v_mfma_f32_16x16x32_bf16 v[40:43], v[190:193], v[222:225], v[40:43]
	v_mfma_f32_16x16x32_bf16 v[28:31], v[172:175], v[230:233], v[28:31]
	v_mfma_f32_16x16x32_bf16 v[24:27], v[190:193], v[230:233], v[24:27]
	v_mfma_f32_16x16x32_bf16 v[12:15], v[172:175], v[238:241], v[12:15]
	v_mfma_f32_16x16x32_bf16 v[8:11], v[190:193], v[238:241], v[8:11]
	s_setprio 0
	s_setprio 1
	v_mfma_f32_16x16x32_bf16 v[52:55], v[194:197], v[210:213], v[52:55]
	v_mfma_f32_16x16x32_bf16 v[48:51], v[202:205], v[210:213], v[48:51]
	v_mfma_f32_16x16x32_bf16 v[36:39], v[194:197], v[218:221], v[36:39]
	v_mfma_f32_16x16x32_bf16 v[32:35], v[202:205], v[218:221], v[32:35]
	v_mfma_f32_16x16x32_bf16 v[20:23], v[194:197], v[226:229], v[20:23]
	v_mfma_f32_16x16x32_bf16 v[16:19], v[202:205], v[226:229], v[16:19]
	v_mfma_f32_16x16x32_bf16 v[4:7], v[194:197], v[234:237], v[4:7]
	v_mfma_f32_16x16x32_bf16 v[0:3], v[202:205], v[234:237], v[0:3]
	v_mfma_f32_16x16x32_bf16 v[52:55], v[198:201], v[214:217], v[52:55]
	v_mfma_f32_16x16x32_bf16 v[48:51], v[206:209], v[214:217], v[48:51]
	v_mfma_f32_16x16x32_bf16 v[36:39], v[198:201], v[222:225], v[36:39]
	v_mfma_f32_16x16x32_bf16 v[32:35], v[206:209], v[222:225], v[32:35]
	v_mfma_f32_16x16x32_bf16 v[20:23], v[198:201], v[230:233], v[20:23]
	v_mfma_f32_16x16x32_bf16 v[16:19], v[206:209], v[230:233], v[16:19]
	v_mfma_f32_16x16x32_bf16 v[4:7], v[198:201], v[238:241], v[4:7]
	v_mfma_f32_16x16x32_bf16 v[0:3], v[206:209], v[238:241], v[0:3]
	s_barrier
	s_setprio 0
	s_sleep 2
	s_add_i32 s95, 0, 0x18000
	v_add_u32_e32 v171, s95, v160
	s_add_i32 s96, 0, 0x1c000
	ds_read_b128 v[146:149], v171
	ds_read_b128 v[172:175], v171 offset:1024
	ds_read_b128 v[176:179], v171 offset:2048
	ds_read_b128 v[190:193], v171 offset:3072
	v_add_u32_e32 v171, s96, v160
	ds_read_b128 v[194:197], v171
	ds_read_b128 v[198:201], v171 offset:1024
	ds_read_b128 v[202:205], v171 offset:2048
	ds_read_b128 v[206:209], v171 offset:3072
	s_add_u32 s62, s62, 0x80000
	s_addc_u32 s63, s63, 0
	s_mov_b32 m0, s34
	v_lshl_add_u64 v[244:245], s[62:63], 0, v[128:129]
	ds_read_b128 v[210:213], v164 offset:32768
	ds_read_b128 v[214:217], v164 offset:33792
	ds_read_b128 v[218:221], v164 offset:34816
	ds_read_b128 v[222:225], v164 offset:35840
	ds_read_b128 v[226:229], v164 offset:36864
	ds_read_b128 v[230:233], v164 offset:37888
	ds_read_b128 v[234:237], v164 offset:38912
	ds_read_b128 v[238:241], v164 offset:39936
	global_load_lds_dwordx4 v[244:245], off
	v_lshl_add_u64 v[244:245], s[62:63], 0, v[132:133]
	s_mov_b32 m0, s35
	s_nop 0
	global_load_lds_dwordx4 v[244:245], off
	s_waitcnt vmcnt(8)
	s_waitcnt lgkmcnt(0)
	s_setprio 1
	s_barrier
	v_mfma_f32_16x16x32_bf16 v[124:127], v[146:149], v[210:213], v[124:127]
	v_mfma_f32_16x16x32_bf16 v[120:123], v[176:179], v[210:213], v[120:123]
	v_mfma_f32_16x16x32_bf16 v[108:111], v[146:149], v[218:221], v[108:111]
	v_mfma_f32_16x16x32_bf16 v[104:107], v[176:179], v[218:221], v[104:107]
	v_mfma_f32_16x16x32_bf16 v[92:95], v[146:149], v[226:229], v[92:95]
	v_mfma_f32_16x16x32_bf16 v[88:91], v[176:179], v[226:229], v[88:91]
	v_mfma_f32_16x16x32_bf16 v[76:79], v[146:149], v[234:237], v[76:79]
	v_mfma_f32_16x16x32_bf16 v[72:75], v[176:179], v[234:237], v[72:75]
	v_mfma_f32_16x16x32_bf16 v[124:127], v[172:175], v[214:217], v[124:127]
	v_mfma_f32_16x16x32_bf16 v[120:123], v[190:193], v[214:217], v[120:123]
	v_mfma_f32_16x16x32_bf16 v[108:111], v[172:175], v[222:225], v[108:111]
	v_mfma_f32_16x16x32_bf16 v[104:107], v[190:193], v[222:225], v[104:107]
	v_mfma_f32_16x16x32_bf16 v[92:95], v[172:175], v[230:233], v[92:95]
	v_mfma_f32_16x16x32_bf16 v[88:91], v[190:193], v[230:233], v[88:91]
	v_mfma_f32_16x16x32_bf16 v[76:79], v[172:175], v[238:241], v[76:79]
	v_mfma_f32_16x16x32_bf16 v[72:75], v[190:193], v[238:241], v[72:75]
	s_setprio 0
	s_setprio 1
	v_mfma_f32_16x16x32_bf16 v[116:119], v[194:197], v[210:213], v[116:119]
	v_mfma_f32_16x16x32_bf16 v[112:115], v[202:205], v[210:213], v[112:115]
	v_mfma_f32_16x16x32_bf16 v[100:103], v[194:197], v[218:221], v[100:103]
	v_mfma_f32_16x16x32_bf16 v[96:99], v[202:205], v[218:221], v[96:99]
	v_mfma_f32_16x16x32_bf16 v[84:87], v[194:197], v[226:229], v[84:87]
	v_mfma_f32_16x16x32_bf16 v[80:83], v[202:205], v[226:229], v[80:83]
	v_mfma_f32_16x16x32_bf16 v[68:71], v[194:197], v[234:237], v[68:71]
	v_mfma_f32_16x16x32_bf16 v[64:67], v[202:205], v[234:237], v[64:67]
	v_mfma_f32_16x16x32_bf16 v[116:119], v[198:201], v[214:217], v[116:119]
	v_mfma_f32_16x16x32_bf16 v[112:115], v[206:209], v[214:217], v[112:115]
	v_mfma_f32_16x16x32_bf16 v[100:103], v[198:201], v[222:225], v[100:103]
	v_mfma_f32_16x16x32_bf16 v[96:99], v[206:209], v[222:225], v[96:99]
	v_mfma_f32_16x16x32_bf16 v[84:87], v[198:201], v[230:233], v[84:87]
	v_mfma_f32_16x16x32_bf16 v[80:83], v[206:209], v[230:233], v[80:83]
	v_mfma_f32_16x16x32_bf16 v[68:71], v[198:201], v[238:241], v[68:71]
	v_mfma_f32_16x16x32_bf16 v[64:67], v[206:209], v[238:241], v[64:67]
	s_barrier
; #define PG8_STAGE(bufoff, gbase, voff) do { _Pragma("unroll") for (int _i = 0; _i < 2; ++_i) \
;         __builtin_amdgcn_global_load_lds((const unsigned*)((const char*)(gbase) + (voff)[_i]), (PG8_LAS unsigned*)(lds + (bufoff) + ldsw + _i * 8192), 16, 0, 0); } while (0)
; #define PG8_LDA(dst, b, h) do { _Pragma("unroll") for (int m = 0; m < 4; ++m) _Pragma("unroll") for (int k = 0; k < 2; ++k) dst[m][k] = *(const PG8_LAS bf16x8*)(lds + PG8_SA(b, h) + aoff + m * 2048 + k * 1024); } while (0)
; #define PG8_MMA(ai, bj, At, Bt) do { __builtin_amdgcn_s_setprio(1); _Pragma("unroll") for (int m = 0; m < 4; ++m) _Pragma("unroll") for (int n = 0; n < 2; ++n) _Pragma("unroll") for (int k = 0; k < 2; ++k) \
;         acc[ai][bj][m][n] = __builtin_amdgcn_mfma_f32_16x16x32_bf16(Bt[n][k], At[m][k], acc[ai][bj][m][n], 0, 0, 0); __builtin_amdgcn_s_setprio(0); } while (0)
; #define PG8_WAIT_V(n) asm volatile("s_waitcnt vmcnt(" #n ")" ::: "memory")
; #define PG8_WAIT_L(n) asm volatile("s_waitcnt lgkmcnt(" #n ")" ::: "memory")
; #define PG8_BAR __builtin_amdgcn_s_barrier()
; #define PG8_SCHED __builtin_amdgcn_sched_barrier(0)
; template <class Epi, class Sched, bool ALIGN_EPI = false, bool SP2 = false>
; __device__ __forceinline__ void gemm_phase(PG8_LAS unsigned char* lds, const Gemm g, const Sched& S, const Epi& E) {
;     ...
;         for (int t = 0; t < nt; t += 2) {
;     ...
;             PG8_LDA(At, 1, 1); PG8_STAGE(PG8_SB(1, 0), b3, voffB); PG8_STAGE(PG8_SB(1, 1), b3 + hstep, voffB); PG8_STAGE(PG8_SA(1, 0), a3, voffA);
;             PG8_WAIT_V(8); PG8_WAIT_L(0); PG8_BAR; PG8_MMA(1, 0, At, B0); PG8_MMA(1, 1, At, B1); PG8_BAR; PG8_SCHED;
	s_setprio 0
	s_sleep 2
	s_add_i32 s62, s95, s3
	v_lshl_add_u64 v[150:151], v[150:151], 0, s[36:37]
	s_mov_b32 m0, s62
	ds_read_b128 v[210:213], v164 offset:49152
	ds_read_b128 v[214:217], v164 offset:50176
	ds_read_b128 v[218:221], v164 offset:51200
	ds_read_b128 v[222:225], v164 offset:52224
	ds_read_b128 v[226:229], v164 offset:53248
	ds_read_b128 v[230:233], v164 offset:54272
	ds_read_b128 v[234:237], v164 offset:55296
	ds_read_b128 v[238:241], v164 offset:56320
	global_load_lds_dwordx4 v[150:151], off
	s_add_i32 m0, s62, 0x2000
	s_add_u32 s60, s60, 0x80080
	v_lshl_add_u64 v[150:151], v[180:181], 0, s[36:37]
	s_addc_u32 s61, s61, 0
	s_add_i32 s62, s96, s3
	global_load_lds_dwordx4 v[150:151], off
	v_lshl_add_u64 v[150:151], s[60:61], 0, v[130:131]
	s_mov_b32 m0, s62
	s_nop 0
	global_load_lds_dwordx4 v[150:151], off
	v_lshl_add_u64 v[150:151], s[60:61], 0, v[134:135]
	s_add_i32 m0, s62, 0x2000
	s_nop 0
	global_load_lds_dwordx4 v[150:151], off
	v_lshl_add_u64 v[150:151], v[188:189], 0, s[36:37]
	s_mov_b32 m0, s65
	s_nop 0
	global_load_lds_dwordx4 v[150:151], off
	v_lshl_add_u64 v[150:151], v[242:243], 0, s[36:37]
	s_mov_b32 m0, s66
	s_nop 0
	global_load_lds_dwordx4 v[150:151], off
	s_waitcnt vmcnt(8)
	s_waitcnt lgkmcnt(0)
	s_setprio 1
	s_barrier
	v_mfma_f32_16x16x32_bf16 v[60:63], v[146:149], v[210:213], v[60:63]
	v_mfma_f32_16x16x32_bf16 v[56:59], v[176:179], v[210:213], v[56:59]
	v_mfma_f32_16x16x32_bf16 v[44:47], v[146:149], v[218:221], v[44:47]
	v_mfma_f32_16x16x32_bf16 v[40:43], v[176:179], v[218:221], v[40:43]
	v_mfma_f32_16x16x32_bf16 v[28:31], v[146:149], v[226:229], v[28:31]
	v_mfma_f32_16x16x32_bf16 v[24:27], v[176:179], v[226:229], v[24:27]
	v_mfma_f32_16x16x32_bf16 v[12:15], v[146:149], v[234:237], v[12:15]
	v_mfma_f32_16x16x32_bf16 v[8:11], v[176:179], v[234:237], v[8:11]
	v_mfma_f32_16x16x32_bf16 v[60:63], v[172:175], v[214:217], v[60:63]
	v_mfma_f32_16x16x32_bf16 v[56:59], v[190:193], v[214:217], v[56:59]
	v_mfma_f32_16x16x32_bf16 v[44:47], v[172:175], v[222:225], v[44:47]
	v_mfma_f32_16x16x32_bf16 v[40:43], v[190:193], v[222:225], v[40:43]
	v_mfma_f32_16x16x32_bf16 v[28:31], v[172:175], v[230:233], v[28:31]
	v_mfma_f32_16x16x32_bf16 v[24:27], v[190:193], v[230:233], v[24:27]
	v_mfma_f32_16x16x32_bf16 v[12:15], v[172:175], v[238:241], v[12:15]
	v_mfma_f32_16x16x32_bf16 v[8:11], v[190:193], v[238:241], v[8:11]
	s_setprio 0
	s_setprio 1
	v_mfma_f32_16x16x32_bf16 v[52:55], v[194:197], v[210:213], v[52:55]
	v_mfma_f32_16x16x32_bf16 v[48:51], v[202:205], v[210:213], v[48:51]
	v_mfma_f32_16x16x32_bf16 v[36:39], v[194:197], v[218:221], v[36:39]
	v_mfma_f32_16x16x32_bf16 v[32:35], v[202:205], v[218:221], v[32:35]
	v_mfma_f32_16x16x32_bf16 v[20:23], v[194:197], v[226:229], v[20:23]
	v_mfma_f32_16x16x32_bf16 v[16:19], v[202:205], v[226:229], v[16:19]
	v_mfma_f32_16x16x32_bf16 v[4:7], v[194:197], v[234:237], v[4:7]
	v_mfma_f32_16x16x32_bf16 v[0:3], v[202:205], v[234:237], v[0:3]
	v_mfma_f32_16x16x32_bf16 v[52:55], v[198:201], v[214:217], v[52:55]
	v_mfma_f32_16x16x32_bf16 v[48:51], v[206:209], v[214:217], v[48:51]
	v_mfma_f32_16x16x32_bf16 v[36:39], v[198:201], v[222:225], v[36:39]
	v_mfma_f32_16x16x32_bf16 v[32:35], v[206:209], v[222:225], v[32:35]
	v_mfma_f32_16x16x32_bf16 v[20:23], v[198:201], v[230:233], v[20:23]
	v_mfma_f32_16x16x32_bf16 v[16:19], v[206:209], v[230:233], v[16:19]
	v_mfma_f32_16x16x32_bf16 v[4:7], v[198:201], v[238:241], v[4:7]
	v_mfma_f32_16x16x32_bf16 v[0:3], v[206:209], v[238:241], v[0:3]
	s_barrier
	s_setprio 0
	s_sleep 2
	s_add_i32 s94, s94, 2
	s_add_u32 s58, s58, 0x100
	s_addc_u32 s59, s59, 0
	s_add_u32 s92, s92, 0x100
	s_addc_u32 s93, s93, 0
	s_cmp_gt_u32 s94, 29
	s_cbranch_scc0 .LBB0_199
	s_and_b64 vcc, exec, s[38:39]
	s_cbranch_vccz .LBB0_202
	s_barrier

; #define PG8_STAGE(bufoff, gbase, voff) do { _Pragma("unroll") for (int _i = 0; _i < 2; ++_i) \
;         __builtin_amdgcn_global_load_lds((const unsigned*)((const char*)(gbase) + (voff)[_i]), (PG8_LAS unsigned*)(lds + (bufoff) + ldsw + _i * 8192), 16, 0, 0); } while (0)
; #define PG8_LDA(dst, b, h) do { _Pragma("unroll") for (int m = 0; m < 4; ++m) _Pragma("unroll") for (int k = 0; k < 2; ++k) dst[m][k] = *(const PG8_LAS bf16x8*)(lds + PG8_SA(b, h) + aoff + m * 2048 + k * 1024); } while (0)
; #define PG8_LDB(dst, b, h) do { _Pragma("unroll") for (int n = 0; n < 2; ++n) _Pragma("unroll") for (int k = 0; k < 2; ++k) dst[n][k] = *(const PG8_LAS bf16x8*)(lds + PG8_SB(b, h) + boff + n * 2048 + k * 1024); } while (0)
; #define PG8_MMA(ai, bj, At, Bt) do { __builtin_amdgcn_s_setprio(1); _Pragma("unroll") for (int m = 0; m < 4; ++m) _Pragma("unroll") for (int n = 0; n < 2; ++n) _Pragma("unroll") for (int k = 0; k < 2; ++k) \
;         acc[ai][bj][m][n] = __builtin_amdgcn_mfma_f32_16x16x32_bf16(Bt[n][k], At[m][k], acc[ai][bj][m][n], 0, 0, 0); __builtin_amdgcn_s_setprio(0); } while (0)
; #define PG8_WAIT_V(n) asm volatile("s_waitcnt vmcnt(" #n ")" ::: "memory")
; #define PG8_WAIT_L(n) asm volatile("s_waitcnt lgkmcnt(" #n ")" ::: "memory")
; template <class Epi, class Sched, bool ALIGN_EPI = false, bool SP2 = false>
; __device__ __forceinline__ void gemm_phase(PG8_LAS unsigned char* lds, const Gemm g, const Sched& S, const Epi& E) {
;     ...
;             const bool last = (t == nt - 2);
;             const char* a1 = cA + (size_t)(t + 1) * kstep;
;             const char* a2 = last ? nA : cA + (size_t)(t + 2) * kstep; const char* b2 = last ? nB : cB + (size_t)(t + 2) * kstep;
;             const char* a3 = a2 + kstep; const char* b3 = b2 + kstep;
;             if (last && has_next) S.a_ready(nxt);
;             if constexpr (SP2) {
;             PG8_LDB(B0, 0, 0); PG8_LDB(B1, 0, 1); PG8_SCHED; PG8_LDA(At, 0, 0); PG8_STAGE(PG8_SA(1, 1), a1 + hstep, voffA);
;             PG8_WAIT_V(8); PG8_WAIT_L(0); PG8_BAR; PG8_MMA(0, 0, At, B0); PG8_MMA(0, 1, At, B1); PG8_BAR; PG8_SCHED;
;             PG8_LDA(At, 0, 1); PG8_STAGE(PG8_SB(0, 0), b2, voffB); PG8_STAGE(PG8_SB(0, 1), b2 + hstep, voffB); PG8_STAGE(PG8_SA(0, 0), a2, voffA);
;             PG8_WAIT_V(8); PG8_WAIT_L(0); PG8_BAR; PG8_MMA(1, 0, At, B0); PG8_MMA(1, 1, At, B1); PG8_BAR; PG8_SCHED;
.LBB0_251:
	ds_read_b128 v[146:149], v152
	ds_read_b128 v[156:159], v152 offset:1024
	ds_read_b128 v[160:163], v152 offset:2048
	ds_read_b128 v[164:167], v152 offset:3072
	ds_read_b128 v[168:171], v154
	ds_read_b128 v[172:175], v154 offset:1024
	ds_read_b128 v[176:179], v154 offset:2048
	ds_read_b128 v[190:193], v154 offset:3072
	s_add_u32 s46, s44, 0xfff80080
	s_addc_u32 s47, s45, -1
	s_cmp_eq_u32 s82, 28
	s_cselect_b32 s49, s37, s47
	s_cselect_b32 s48, s77, s46
	s_cselect_b32 s47, s13, s81
	s_cselect_b32 s46, s79, s80
	v_lshl_add_u64 v[180:181], s[44:45], 0, v[136:137]
	s_add_i32 m0, s35, 0xc000
	ds_read_b128 v[194:197], v155
	ds_read_b128 v[198:201], v155 offset:1024
	ds_read_b128 v[202:205], v155 offset:2048
	ds_read_b128 v[206:209], v155 offset:3072
	ds_read_b128 v[210:213], v155 offset:4096
	ds_read_b128 v[214:217], v155 offset:5120
	ds_read_b128 v[218:221], v155 offset:6144
	ds_read_b128 v[222:225], v155 offset:7168
	global_load_lds_dwordx4 v[180:181], off
	v_lshl_add_u64 v[180:181], s[44:45], 0, v[138:139]
	s_add_i32 m0, s35, 0xe000
	s_nop 0
	global_load_lds_dwordx4 v[180:181], off
	s_waitcnt vmcnt(8)
	s_waitcnt lgkmcnt(0)
	s_setprio 1
	s_barrier
	v_mfma_f32_16x16x32_bf16 v[124:127], v[146:149], v[194:197], v[124:127]
	v_mfma_f32_16x16x32_bf16 v[120:123], v[160:163], v[194:197], v[120:123]
	v_mfma_f32_16x16x32_bf16 v[116:119], v[146:149], v[202:205], v[116:119]
	v_mfma_f32_16x16x32_bf16 v[108:111], v[160:163], v[202:205], v[108:111]
	v_mfma_f32_16x16x32_bf16 v[100:103], v[146:149], v[210:213], v[100:103]
	v_mfma_f32_16x16x32_bf16 v[92:95], v[160:163], v[210:213], v[92:95]
	v_mfma_f32_16x16x32_bf16 v[84:87], v[146:149], v[218:221], v[84:87]
	v_mfma_f32_16x16x32_bf16 v[76:79], v[160:163], v[218:221], v[76:79]
	v_mfma_f32_16x16x32_bf16 v[124:127], v[156:159], v[198:201], v[124:127]
	v_mfma_f32_16x16x32_bf16 v[120:123], v[164:167], v[198:201], v[120:123]
	v_mfma_f32_16x16x32_bf16 v[116:119], v[156:159], v[206:209], v[116:119]
	v_mfma_f32_16x16x32_bf16 v[108:111], v[164:167], v[206:209], v[108:111]
	v_mfma_f32_16x16x32_bf16 v[100:103], v[156:159], v[214:217], v[100:103]
	v_mfma_f32_16x16x32_bf16 v[92:95], v[164:167], v[214:217], v[92:95]
	v_mfma_f32_16x16x32_bf16 v[84:87], v[156:159], v[222:225], v[84:87]
	v_mfma_f32_16x16x32_bf16 v[76:79], v[164:167], v[222:225], v[76:79]
	s_setprio 0
	s_setprio 1
	v_mfma_f32_16x16x32_bf16 v[112:115], v[168:171], v[194:197], v[112:115]
	v_mfma_f32_16x16x32_bf16 v[104:107], v[176:179], v[194:197], v[104:107]
	v_mfma_f32_16x16x32_bf16 v[96:99], v[168:171], v[202:205], v[96:99]
	v_mfma_f32_16x16x32_bf16 v[88:91], v[176:179], v[202:205], v[88:91]
	v_mfma_f32_16x16x32_bf16 v[80:83], v[168:171], v[210:213], v[80:83]
	v_mfma_f32_16x16x32_bf16 v[72:75], v[176:179], v[210:213], v[72:75]
	v_mfma_f32_16x16x32_bf16 v[68:71], v[168:171], v[218:221], v[68:71]
	v_mfma_f32_16x16x32_bf16 v[64:67], v[176:179], v[218:221], v[64:67]
	v_mfma_f32_16x16x32_bf16 v[112:115], v[172:175], v[198:201], v[112:115]
	v_mfma_f32_16x16x32_bf16 v[104:107], v[190:193], v[198:201], v[104:107]
	v_mfma_f32_16x16x32_bf16 v[96:99], v[172:175], v[206:209], v[96:99]
	v_mfma_f32_16x16x32_bf16 v[88:91], v[190:193], v[206:209], v[88:91]
	v_mfma_f32_16x16x32_bf16 v[80:83], v[172:175], v[214:217], v[80:83]
	v_mfma_f32_16x16x32_bf16 v[72:75], v[190:193], v[214:217], v[72:75]
	v_mfma_f32_16x16x32_bf16 v[68:71], v[172:175], v[222:225], v[68:71]
	v_mfma_f32_16x16x32_bf16 v[64:67], v[190:193], v[222:225], v[64:67]
	s_barrier
	s_setprio 0
	s_sleep 2
	s_add_i32 s83, s65, s29
	v_lshl_add_u64 v[180:181], s[46:47], 0, v[130:131]
	s_mov_b32 m0, s83
	ds_read_b128 v[194:197], v155 offset:16384
	ds_read_b128 v[198:201], v155 offset:17408
	ds_read_b128 v[202:205], v155 offset:18432
	ds_read_b128 v[206:209], v155 offset:19456
	ds_read_b128 v[210:213], v155 offset:20480
	ds_read_b128 v[214:217], v155 offset:21504
	ds_read_b128 v[218:221], v155 offset:22528
	ds_read_b128 v[222:225], v155 offset:23552
	global_load_lds_dwordx4 v[180:181], off
	s_add_i32 m0, s83, 0x2000
	s_add_u32 s84, s46, 0x80000
	v_lshl_add_u64 v[188:189], s[46:47], 0, v[134:135]
	s_addc_u32 s85, s47, 0
	s_add_i32 s83, s66, s29
	global_load_lds_dwordx4 v[188:189], off
	v_lshl_add_u64 v[226:227], s[84:85], 0, v[130:131]
	s_mov_b32 m0, s83
	v_lshl_add_u64 v[228:229], s[48:49], 0, v[132:133]
	global_load_lds_dwordx4 v[226:227], off
	v_lshl_add_u64 v[226:227], s[84:85], 0, v[134:135]
	s_add_i32 m0, s83, 0x2000
	s_nop 0
	global_load_lds_dwordx4 v[226:227], off
	v_lshl_add_u64 v[226:227], s[48:49], 0, v[128:129]
	s_mov_b32 m0, s35
	s_nop 0
	global_load_lds_dwordx4 v[226:227], off
	s_mov_b32 m0, s43
	s_nop 0
	global_load_lds_dwordx4 v[228:229], off
	s_waitcnt vmcnt(8)
	s_waitcnt lgkmcnt(0)
	s_setprio 1
	s_barrier
; #define PG8_STAGE(bufoff, gbase, voff) do { _Pragma("unroll") for (int _i = 0; _i < 2; ++_i) \
;         __builtin_amdgcn_global_load_lds((const unsigned*)((const char*)(gbase) + (voff)[_i]), (PG8_LAS unsigned*)(lds + (bufoff) + ldsw + _i * 8192), 16, 0, 0); } while (0)
; #define PG8_LDA(dst, b, h) do { _Pragma("unroll") for (int m = 0; m < 4; ++m) _Pragma("unroll") for (int k = 0; k < 2; ++k) dst[m][k] = *(const PG8_LAS bf16x8*)(lds + PG8_SA(b, h) + aoff + m * 2048 + k * 1024); } while (0)
; #define PG8_LDB(dst, b, h) do { _Pragma("unroll") for (int n = 0; n < 2; ++n) _Pragma("unroll") for (int k = 0; k < 2; ++k) dst[n][k] = *(const PG8_LAS bf16x8*)(lds + PG8_SB(b, h) + boff + n * 2048 + k * 1024); } while (0)
; #define PG8_MMA(ai, bj, At, Bt) do { __builtin_amdgcn_s_setprio(1); _Pragma("unroll") for (int m = 0; m < 4; ++m) _Pragma("unroll") for (int n = 0; n < 2; ++n) _Pragma("unroll") for (int k = 0; k < 2; ++k) \
;         acc[ai][bj][m][n] = __builtin_amdgcn_mfma_f32_16x16x32_bf16(Bt[n][k], At[m][k], acc[ai][bj][m][n], 0, 0, 0); __builtin_amdgcn_s_setprio(0); } while (0)
; #define PG8_WAIT_V(n) asm volatile("s_waitcnt vmcnt(" #n ")" ::: "memory")
; #define PG8_WAIT_L(n) asm volatile("s_waitcnt lgkmcnt(" #n ")" ::: "memory")
; #define PG8_BAR __builtin_amdgcn_s_barrier()
; #define PG8_SCHED __builtin_amdgcn_sched_barrier(0)
; template <class Epi, class Sched, bool ALIGN_EPI = false, bool SP2 = false>
; __device__ __forceinline__ void gemm_phase(PG8_LAS unsigned char* lds, const Gemm g, const Sched& S, const Epi& E) {
;     ...
;             PG8_WAIT_V(8); PG8_WAIT_L(0); PG8_BAR; PG8_MMA(1, 0, At, B0); PG8_MMA(1, 1, At, B1); PG8_BAR; PG8_SCHED;
;             PG8_LDB(B0, 1, 0); PG8_LDB(B1, 1, 1); PG8_SCHED; PG8_LDA(At, 1, 0); PG8_STAGE(PG8_SA(0, 1), a2 + hstep, voffA);
;             PG8_WAIT_V(8); PG8_WAIT_L(0); PG8_BAR; PG8_MMA(0, 0, At, B0); PG8_MMA(0, 1, At, B1); PG8_BAR; PG8_SCHED;
;             PG8_LDA(At, 1, 1); PG8_STAGE(PG8_SB(1, 0), b3, voffB); PG8_STAGE(PG8_SB(1, 1), b3 + hstep, voffB); PG8_STAGE(PG8_SA(1, 0), a3, voffA);
;             PG8_WAIT_V(8); PG8_WAIT_L(0); PG8_BAR; PG8_MMA(1, 0, At, B0); PG8_MMA(1, 1, At, B1); PG8_BAR; PG8_SCHED;
	v_mfma_f32_16x16x32_bf16 v[60:63], v[146:149], v[194:197], v[60:63]
	v_mfma_f32_16x16x32_bf16 v[56:59], v[160:163], v[194:197], v[56:59]
	v_mfma_f32_16x16x32_bf16 v[52:55], v[146:149], v[202:205], v[52:55]
	v_mfma_f32_16x16x32_bf16 v[44:47], v[160:163], v[202:205], v[44:47]
	v_mfma_f32_16x16x32_bf16 v[36:39], v[146:149], v[210:213], v[36:39]
	v_mfma_f32_16x16x32_bf16 v[28:31], v[160:163], v[210:213], v[28:31]
	v_mfma_f32_16x16x32_bf16 v[20:23], v[146:149], v[218:221], v[20:23]
	v_mfma_f32_16x16x32_bf16 v[12:15], v[160:163], v[218:221], v[12:15]
	v_mfma_f32_16x16x32_bf16 v[60:63], v[156:159], v[198:201], v[60:63]
	v_mfma_f32_16x16x32_bf16 v[56:59], v[164:167], v[198:201], v[56:59]
	v_mfma_f32_16x16x32_bf16 v[52:55], v[156:159], v[206:209], v[52:55]
	v_mfma_f32_16x16x32_bf16 v[44:47], v[164:167], v[206:209], v[44:47]
	v_mfma_f32_16x16x32_bf16 v[36:39], v[156:159], v[214:217], v[36:39]
	v_mfma_f32_16x16x32_bf16 v[28:31], v[164:167], v[214:217], v[28:31]
	v_mfma_f32_16x16x32_bf16 v[20:23], v[156:159], v[222:225], v[20:23]
	v_mfma_f32_16x16x32_bf16 v[12:15], v[164:167], v[222:225], v[12:15]
	s_setprio 0
	s_setprio 1
	v_mfma_f32_16x16x32_bf16 v[48:51], v[168:171], v[194:197], v[48:51]
	v_mfma_f32_16x16x32_bf16 v[40:43], v[176:179], v[194:197], v[40:43]
	v_mfma_f32_16x16x32_bf16 v[32:35], v[168:171], v[202:205], v[32:35]
	v_mfma_f32_16x16x32_bf16 v[24:27], v[176:179], v[202:205], v[24:27]
	v_mfma_f32_16x16x32_bf16 v[16:19], v[168:171], v[210:213], v[16:19]
	v_mfma_f32_16x16x32_bf16 v[8:11], v[176:179], v[210:213], v[8:11]
	v_mfma_f32_16x16x32_bf16 v[4:7], v[168:171], v[218:221], v[4:7]
	v_mfma_f32_16x16x32_bf16 v[0:3], v[176:179], v[218:221], v[0:3]
	v_mfma_f32_16x16x32_bf16 v[48:51], v[172:175], v[198:201], v[48:51]
	v_mfma_f32_16x16x32_bf16 v[40:43], v[190:193], v[198:201], v[40:43]
	v_mfma_f32_16x16x32_bf16 v[32:35], v[172:175], v[206:209], v[32:35]
	v_mfma_f32_16x16x32_bf16 v[24:27], v[190:193], v[206:209], v[24:27]
	v_mfma_f32_16x16x32_bf16 v[16:19], v[172:175], v[214:217], v[16:19]
	v_mfma_f32_16x16x32_bf16 v[8:11], v[190:193], v[214:217], v[8:11]
	v_mfma_f32_16x16x32_bf16 v[4:7], v[172:175], v[222:225], v[4:7]
	v_mfma_f32_16x16x32_bf16 v[0:3], v[190:193], v[222:225], v[0:3]
	s_barrier
	s_setprio 0
	s_sleep 2
	s_add_i32 s83, 0, 0x18000
	s_add_i32 s84, 0, 0x1c000
	v_add_u32_e32 v164, s83, v151
	v_add_u32_e32 v190, s84, v151
	ds_read_b128 v[146:149], v164
	ds_read_b128 v[156:159], v164 offset:1024
	ds_read_b128 v[160:163], v164 offset:2048
	ds_read_b128 v[164:167], v164 offset:3072
	ds_read_b128 v[168:171], v190
	ds_read_b128 v[172:175], v190 offset:1024
	ds_read_b128 v[176:179], v190 offset:2048
	ds_read_b128 v[190:193], v190 offset:3072
	s_add_u32 s48, s48, 0x80000
	s_addc_u32 s49, s49, 0
	s_mov_b32 m0, s58
	v_lshl_add_u64 v[230:231], s[48:49], 0, v[128:129]
	ds_read_b128 v[194:197], v155 offset:32768
	ds_read_b128 v[198:201], v155 offset:33792
	ds_read_b128 v[202:205], v155 offset:34816
	ds_read_b128 v[206:209], v155 offset:35840
	ds_read_b128 v[210:213], v155 offset:36864
	ds_read_b128 v[214:217], v155 offset:37888
	ds_read_b128 v[218:221], v155 offset:38912
	ds_read_b128 v[222:225], v155 offset:39936
	global_load_lds_dwordx4 v[230:231], off
	v_lshl_add_u64 v[230:231], s[48:49], 0, v[132:133]
	s_mov_b32 m0, s59
	s_nop 0
	global_load_lds_dwordx4 v[230:231], off
	s_waitcnt vmcnt(8)
	s_waitcnt lgkmcnt(0)
	s_setprio 1
	s_barrier
	v_mfma_f32_16x16x32_bf16 v[124:127], v[146:149], v[194:197], v[124:127]
	v_mfma_f32_16x16x32_bf16 v[120:123], v[160:163], v[194:197], v[120:123]
	v_mfma_f32_16x16x32_bf16 v[116:119], v[146:149], v[202:205], v[116:119]
	v_mfma_f32_16x16x32_bf16 v[108:111], v[160:163], v[202:205], v[108:111]
	v_mfma_f32_16x16x32_bf16 v[100:103], v[146:149], v[210:213], v[100:103]
	v_mfma_f32_16x16x32_bf16 v[92:95], v[160:163], v[210:213], v[92:95]
	v_mfma_f32_16x16x32_bf16 v[84:87], v[146:149], v[218:221], v[84:87]
	v_mfma_f32_16x16x32_bf16 v[76:79], v[160:163], v[218:221], v[76:79]
	v_mfma_f32_16x16x32_bf16 v[124:127], v[156:159], v[198:201], v[124:127]
	v_mfma_f32_16x16x32_bf16 v[120:123], v[164:167], v[198:201], v[120:123]
	v_mfma_f32_16x16x32_bf16 v[116:119], v[156:159], v[206:209], v[116:119]
	v_mfma_f32_16x16x32_bf16 v[108:111], v[164:167], v[206:209], v[108:111]
	v_mfma_f32_16x16x32_bf16 v[100:103], v[156:159], v[214:217], v[100:103]
	v_mfma_f32_16x16x32_bf16 v[92:95], v[164:167], v[214:217], v[92:95]
	v_mfma_f32_16x16x32_bf16 v[84:87], v[156:159], v[222:225], v[84:87]
	v_mfma_f32_16x16x32_bf16 v[76:79], v[164:167], v[222:225], v[76:79]
	s_setprio 0
	s_setprio 1
	v_mfma_f32_16x16x32_bf16 v[112:115], v[168:171], v[194:197], v[112:115]
	v_mfma_f32_16x16x32_bf16 v[104:107], v[176:179], v[194:197], v[104:107]
	v_mfma_f32_16x16x32_bf16 v[96:99], v[168:171], v[202:205], v[96:99]
	v_mfma_f32_16x16x32_bf16 v[88:91], v[176:179], v[202:205], v[88:91]
	v_mfma_f32_16x16x32_bf16 v[80:83], v[168:171], v[210:213], v[80:83]
	v_mfma_f32_16x16x32_bf16 v[72:75], v[176:179], v[210:213], v[72:75]
	v_mfma_f32_16x16x32_bf16 v[68:71], v[168:171], v[218:221], v[68:71]
	v_mfma_f32_16x16x32_bf16 v[64:67], v[176:179], v[218:221], v[64:67]
	v_mfma_f32_16x16x32_bf16 v[112:115], v[172:175], v[198:201], v[112:115]
	v_mfma_f32_16x16x32_bf16 v[104:107], v[190:193], v[198:201], v[104:107]
	v_mfma_f32_16x16x32_bf16 v[96:99], v[172:175], v[206:209], v[96:99]
	v_mfma_f32_16x16x32_bf16 v[88:91], v[190:193], v[206:209], v[88:91]
	v_mfma_f32_16x16x32_bf16 v[80:83], v[172:175], v[214:217], v[80:83]
	v_mfma_f32_16x16x32_bf16 v[72:75], v[190:193], v[214:217], v[72:75]
	v_mfma_f32_16x16x32_bf16 v[68:71], v[172:175], v[222:225], v[68:71]
	v_mfma_f32_16x16x32_bf16 v[64:67], v[190:193], v[222:225], v[64:67]
	s_barrier
; #define PG8_STAGE(bufoff, gbase, voff) do { _Pragma("unroll") for (int _i = 0; _i < 2; ++_i) \
;         __builtin_amdgcn_global_load_lds((const unsigned*)((const char*)(gbase) + (voff)[_i]), (PG8_LAS unsigned*)(lds + (bufoff) + ldsw + _i * 8192), 16, 0, 0); } while (0)
; #define PG8_LDA(dst, b, h) do { _Pragma("unroll") for (int m = 0; m < 4; ++m) _Pragma("unroll") for (int k = 0; k < 2; ++k) dst[m][k] = *(const PG8_LAS bf16x8*)(lds + PG8_SA(b, h) + aoff + m * 2048 + k * 1024); } while (0)
; #define PG8_MMA(ai, bj, At, Bt) do { __builtin_amdgcn_s_setprio(1); _Pragma("unroll") for (int m = 0; m < 4; ++m) _Pragma("unroll") for (int n = 0; n < 2; ++n) _Pragma("unroll") for (int k = 0; k < 2; ++k) \
;         acc[ai][bj][m][n] = __builtin_amdgcn_mfma_f32_16x16x32_bf16(Bt[n][k], At[m][k], acc[ai][bj][m][n], 0, 0, 0); __builtin_amdgcn_s_setprio(0); } while (0)
; #define PG8_WAIT_V(n) asm volatile("s_waitcnt vmcnt(" #n ")" ::: "memory")
; #define PG8_WAIT_L(n) asm volatile("s_waitcnt lgkmcnt(" #n ")" ::: "memory")
; #define PG8_BAR __builtin_amdgcn_s_barrier()
; #define PG8_SCHED __builtin_amdgcn_sched_barrier(0)
; template <class Epi, class Sched, bool ALIGN_EPI = false, bool SP2 = false>
; __device__ __forceinline__ void gemm_phase(PG8_LAS unsigned char* lds, const Gemm g, const Sched& S, const Epi& E) {
;     ...
;             PG8_LDA(At, 1, 1); PG8_STAGE(PG8_SB(1, 0), b3, voffB); PG8_STAGE(PG8_SB(1, 1), b3 + hstep, voffB); PG8_STAGE(PG8_SA(1, 0), a3, voffA);
;             PG8_WAIT_V(8); PG8_WAIT_L(0); PG8_BAR; PG8_MMA(1, 0, At, B0); PG8_MMA(1, 1, At, B1); PG8_BAR; PG8_SCHED;
	s_setprio 0
	s_sleep 2
	s_add_i32 s48, s83, s29
	v_lshl_add_u64 v[180:181], v[180:181], 0, s[6:7]
	s_mov_b32 m0, s48
	ds_read_b128 v[194:197], v155 offset:49152
	ds_read_b128 v[198:201], v155 offset:50176
	ds_read_b128 v[202:205], v155 offset:51200
	ds_read_b128 v[206:209], v155 offset:52224
	ds_read_b128 v[210:213], v155 offset:53248
	ds_read_b128 v[214:217], v155 offset:54272
	ds_read_b128 v[218:221], v155 offset:55296
	ds_read_b128 v[222:225], v155 offset:56320
	global_load_lds_dwordx4 v[180:181], off
	s_add_i32 m0, s48, 0x2000
	s_add_u32 s46, s46, 0x80080
	v_lshl_add_u64 v[180:181], v[188:189], 0, s[6:7]
	s_addc_u32 s47, s47, 0
	s_add_i32 s48, s84, s29
	global_load_lds_dwordx4 v[180:181], off
	v_lshl_add_u64 v[180:181], s[46:47], 0, v[130:131]
	s_mov_b32 m0, s48
	s_nop 0
	global_load_lds_dwordx4 v[180:181], off
	v_lshl_add_u64 v[180:181], s[46:47], 0, v[134:135]
	s_add_i32 m0, s48, 0x2000
	s_nop 0
	global_load_lds_dwordx4 v[180:181], off
	v_lshl_add_u64 v[180:181], v[226:227], 0, s[6:7]
	s_mov_b32 m0, s62
	s_nop 0
	global_load_lds_dwordx4 v[180:181], off
	v_lshl_add_u64 v[180:181], v[228:229], 0, s[6:7]
	s_mov_b32 m0, s63
	s_nop 0
	global_load_lds_dwordx4 v[180:181], off
	s_waitcnt vmcnt(8)
	s_waitcnt lgkmcnt(0)
	s_setprio 1
	s_barrier
	v_mfma_f32_16x16x32_bf16 v[60:63], v[146:149], v[194:197], v[60:63]
	v_mfma_f32_16x16x32_bf16 v[56:59], v[160:163], v[194:197], v[56:59]
	v_mfma_f32_16x16x32_bf16 v[52:55], v[146:149], v[202:205], v[52:55]
	v_mfma_f32_16x16x32_bf16 v[44:47], v[160:163], v[202:205], v[44:47]
	v_mfma_f32_16x16x32_bf16 v[36:39], v[146:149], v[210:213], v[36:39]
	v_mfma_f32_16x16x32_bf16 v[28:31], v[160:163], v[210:213], v[28:31]
	v_mfma_f32_16x16x32_bf16 v[20:23], v[146:149], v[218:221], v[20:23]
	v_mfma_f32_16x16x32_bf16 v[12:15], v[160:163], v[218:221], v[12:15]
	v_mfma_f32_16x16x32_bf16 v[60:63], v[156:159], v[198:201], v[60:63]
	v_mfma_f32_16x16x32_bf16 v[56:59], v[164:167], v[198:201], v[56:59]
	v_mfma_f32_16x16x32_bf16 v[52:55], v[156:159], v[206:209], v[52:55]
	v_mfma_f32_16x16x32_bf16 v[44:47], v[164:167], v[206:209], v[44:47]
	v_mfma_f32_16x16x32_bf16 v[36:39], v[156:159], v[214:217], v[36:39]
	v_mfma_f32_16x16x32_bf16 v[28:31], v[164:167], v[214:217], v[28:31]
	v_mfma_f32_16x16x32_bf16 v[20:23], v[156:159], v[222:225], v[20:23]
	v_mfma_f32_16x16x32_bf16 v[12:15], v[164:167], v[222:225], v[12:15]
	s_setprio 0
	s_setprio 1
	v_mfma_f32_16x16x32_bf16 v[48:51], v[168:171], v[194:197], v[48:51]
	v_mfma_f32_16x16x32_bf16 v[40:43], v[176:179], v[194:197], v[40:43]
	v_mfma_f32_16x16x32_bf16 v[32:35], v[168:171], v[202:205], v[32:35]
	v_mfma_f32_16x16x32_bf16 v[24:27], v[176:179], v[202:205], v[24:27]
	v_mfma_f32_16x16x32_bf16 v[16:19], v[168:171], v[210:213], v[16:19]
	v_mfma_f32_16x16x32_bf16 v[8:11], v[176:179], v[210:213], v[8:11]
	v_mfma_f32_16x16x32_bf16 v[4:7], v[168:171], v[218:221], v[4:7]
	v_mfma_f32_16x16x32_bf16 v[0:3], v[176:179], v[218:221], v[0:3]
	v_mfma_f32_16x16x32_bf16 v[48:51], v[172:175], v[198:201], v[48:51]
	v_mfma_f32_16x16x32_bf16 v[40:43], v[190:193], v[198:201], v[40:43]
	v_mfma_f32_16x16x32_bf16 v[32:35], v[172:175], v[206:209], v[32:35]
	v_mfma_f32_16x16x32_bf16 v[24:27], v[190:193], v[206:209], v[24:27]
	v_mfma_f32_16x16x32_bf16 v[16:19], v[172:175], v[214:217], v[16:19]
	v_mfma_f32_16x16x32_bf16 v[8:11], v[190:193], v[214:217], v[8:11]
	v_mfma_f32_16x16x32_bf16 v[4:7], v[172:175], v[222:225], v[4:7]
	v_mfma_f32_16x16x32_bf16 v[0:3], v[190:193], v[222:225], v[0:3]
	s_barrier
	s_setprio 0
	s_sleep 2
	s_add_i32 s82, s82, 2
	s_add_u32 s44, s44, 0x100
	s_addc_u32 s45, s45, 0
	s_add_u32 s80, s80, 0x100
	s_addc_u32 s81, s81, 0
	s_cmp_gt_u32 s82, 29
	s_cbranch_scc0 .LBB0_251
	s_and_b64 vcc, exec, s[8:9]
	s_cbranch_vccz .LBB0_254
	s_barrier

; #define PG8_STAGE(bufoff, gbase, voff) do { _Pragma("unroll") for (int _i = 0; _i < 2; ++_i) \
;         __builtin_amdgcn_global_load_lds((const unsigned*)((const char*)(gbase) + (voff)[_i]), (PG8_LAS unsigned*)(lds + (bufoff) + ldsw + _i * 8192), 16, 0, 0); } while (0)
; #define PG8_LDA(dst, b, h) do { _Pragma("unroll") for (int m = 0; m < 4; ++m) _Pragma("unroll") for (int k = 0; k < 2; ++k) dst[m][k] = *(const PG8_LAS bf16x8*)(lds + PG8_SA(b, h) + aoff + m * 2048 + k * 1024); } while (0)
; #define PG8_LDB(dst, b, h) do { _Pragma("unroll") for (int n = 0; n < 2; ++n) _Pragma("unroll") for (int k = 0; k < 2; ++k) dst[n][k] = *(const PG8_LAS bf16x8*)(lds + PG8_SB(b, h) + boff + n * 2048 + k * 1024); } while (0)
; #define PG8_MMA(ai, bj, At, Bt) do { __builtin_amdgcn_s_setprio(1); _Pragma("unroll") for (int m = 0; m < 4; ++m) _Pragma("unroll") for (int n = 0; n < 2; ++n) _Pragma("unroll") for (int k = 0; k < 2; ++k) \
;         acc[ai][bj][m][n] = __builtin_amdgcn_mfma_f32_16x16x32_bf16(Bt[n][k], At[m][k], acc[ai][bj][m][n], 0, 0, 0); __builtin_amdgcn_s_setprio(0); } while (0)
; #define PG8_WAIT_V(n) asm volatile("s_waitcnt vmcnt(" #n ")" ::: "memory")
; #define PG8_WAIT_L(n) asm volatile("s_waitcnt lgkmcnt(" #n ")" ::: "memory")
; template <class Epi, class Sched, bool ALIGN_EPI = false, bool SP2 = false>
; __device__ __forceinline__ void gemm_phase(PG8_LAS unsigned char* lds, const Gemm g, const Sched& S, const Epi& E) {
;     ...
;             const bool last = (t == nt - 2);
;             const char* a1 = cA + (size_t)(t + 1) * kstep;
;             const char* a2 = last ? nA : cA + (size_t)(t + 2) * kstep; const char* b2 = last ? nB : cB + (size_t)(t + 2) * kstep;
;             const char* a3 = a2 + kstep; const char* b3 = b2 + kstep;
;             if (last && has_next) S.a_ready(nxt);
;             if constexpr (SP2) {
;             PG8_LDB(B0, 0, 0); PG8_LDB(B1, 0, 1); PG8_SCHED; PG8_LDA(At, 0, 0); PG8_STAGE(PG8_SA(1, 1), a1 + hstep, voffA);
;             PG8_WAIT_V(8); PG8_WAIT_L(0); PG8_BAR; PG8_MMA(0, 0, At, B0); PG8_MMA(0, 1, At, B1); PG8_BAR; PG8_SCHED;
;             PG8_LDA(At, 0, 1); PG8_STAGE(PG8_SB(0, 0), b2, voffB); PG8_STAGE(PG8_SB(0, 1), b2 + hstep, voffB); PG8_STAGE(PG8_SA(0, 0), a2, voffA);
;             PG8_WAIT_V(8); PG8_WAIT_L(0); PG8_BAR; PG8_MMA(1, 0, At, B0); PG8_MMA(1, 1, At, B1); PG8_BAR; PG8_SCHED;
.LBB0_560:
	ds_read_b128 v[174:177], v167
	ds_read_b128 v[178:181], v167 offset:1024
	ds_read_b128 v[190:193], v167 offset:2048
	ds_read_b128 v[194:197], v167 offset:3072
	ds_read_b128 v[198:201], v168
	ds_read_b128 v[202:205], v168 offset:1024
	ds_read_b128 v[206:209], v168 offset:2048
	ds_read_b128 v[210:213], v168 offset:3072
	s_add_u32 s50, s10, 0x100
	s_addc_u32 s51, s11, 0
	s_add_u32 s52, s34, s10
	s_addc_u32 s53, s49, s11
	s_cmp_eq_u32 s67, 28
	s_cselect_b32 s54, s18, s52
	s_cselect_b32 s52, 0, s50
	s_cselect_b32 s55, s19, s53
	s_cselect_b32 s53, 0, s51
	s_add_u32 s52, s16, s52
	s_addc_u32 s53, s17, s53
	v_lshl_add_u64 v[246:247], v[142:143], 0, s[10:11]
	s_add_i32 m0, s15, 0xc000
	ds_read_b128 v[214:217], v169
	ds_read_b128 v[218:221], v169 offset:1024
	ds_read_b128 v[222:225], v169 offset:2048
	ds_read_b128 v[226:229], v169 offset:3072
	ds_read_b128 v[230:233], v169 offset:4096
	ds_read_b128 v[234:237], v169 offset:5120
	ds_read_b128 v[238:241], v169 offset:6144
	ds_read_b128 v[242:245], v169 offset:7168
	global_load_lds_dwordx4 v[246:247], off
	v_lshl_add_u64 v[246:247], v[146:147], 0, s[10:11]
	s_add_i32 m0, s15, 0xe000
	s_nop 0
	global_load_lds_dwordx4 v[246:247], off
	s_waitcnt vmcnt(8)
	s_waitcnt lgkmcnt(0)
	s_setprio 1
	s_barrier
	v_mfma_f32_16x16x32_bf16 v[76:79], v[174:177], v[214:217], v[76:79]
	v_mfma_f32_16x16x32_bf16 v[72:75], v[190:193], v[214:217], v[72:75]
	v_mfma_f32_16x16x32_bf16 v[92:95], v[174:177], v[222:225], v[92:95]
	v_mfma_f32_16x16x32_bf16 v[88:91], v[190:193], v[222:225], v[88:91]
	v_mfma_f32_16x16x32_bf16 v[116:119], v[174:177], v[230:233], v[116:119]
	v_mfma_f32_16x16x32_bf16 v[112:115], v[190:193], v[230:233], v[112:115]
	v_mfma_f32_16x16x32_bf16 v[124:127], v[174:177], v[238:241], v[124:127]
	v_mfma_f32_16x16x32_bf16 v[120:123], v[190:193], v[238:241], v[120:123]
	v_mfma_f32_16x16x32_bf16 v[76:79], v[178:181], v[218:221], v[76:79]
	v_mfma_f32_16x16x32_bf16 v[72:75], v[194:197], v[218:221], v[72:75]
	v_mfma_f32_16x16x32_bf16 v[92:95], v[178:181], v[226:229], v[92:95]
	v_mfma_f32_16x16x32_bf16 v[88:91], v[194:197], v[226:229], v[88:91]
	v_mfma_f32_16x16x32_bf16 v[116:119], v[178:181], v[234:237], v[116:119]
	v_mfma_f32_16x16x32_bf16 v[112:115], v[194:197], v[234:237], v[112:115]
	v_mfma_f32_16x16x32_bf16 v[124:127], v[178:181], v[242:245], v[124:127]
	v_mfma_f32_16x16x32_bf16 v[120:123], v[194:197], v[242:245], v[120:123]
	s_setprio 0
	s_setprio 1
	v_mfma_f32_16x16x32_bf16 v[68:71], v[198:201], v[214:217], v[68:71]
	v_mfma_f32_16x16x32_bf16 v[64:67], v[206:209], v[214:217], v[64:67]
	v_mfma_f32_16x16x32_bf16 v[84:87], v[198:201], v[222:225], v[84:87]
	v_mfma_f32_16x16x32_bf16 v[80:83], v[206:209], v[222:225], v[80:83]
	v_mfma_f32_16x16x32_bf16 v[108:111], v[198:201], v[230:233], v[108:111]
	v_mfma_f32_16x16x32_bf16 v[96:99], v[206:209], v[230:233], v[96:99]
	v_mfma_f32_16x16x32_bf16 v[104:107], v[198:201], v[238:241], v[104:107]
	v_mfma_f32_16x16x32_bf16 v[100:103], v[206:209], v[238:241], v[100:103]
	v_mfma_f32_16x16x32_bf16 v[68:71], v[202:205], v[218:221], v[68:71]
	v_mfma_f32_16x16x32_bf16 v[64:67], v[210:213], v[218:221], v[64:67]
	v_mfma_f32_16x16x32_bf16 v[84:87], v[202:205], v[226:229], v[84:87]
	v_mfma_f32_16x16x32_bf16 v[80:83], v[210:213], v[226:229], v[80:83]
	v_mfma_f32_16x16x32_bf16 v[108:111], v[202:205], v[234:237], v[108:111]
	v_mfma_f32_16x16x32_bf16 v[96:99], v[210:213], v[234:237], v[96:99]
	v_mfma_f32_16x16x32_bf16 v[104:107], v[202:205], v[242:245], v[104:107]
	v_mfma_f32_16x16x32_bf16 v[100:103], v[210:213], v[242:245], v[100:103]
	s_barrier
	s_setprio 0
	s_sleep 2
	s_add_i32 s10, s61, s2
	v_lshl_add_u64 v[246:247], s[52:53], 0, v[128:129]
	s_mov_b32 m0, s10
	ds_read_b128 v[214:217], v169 offset:16384
	ds_read_b128 v[218:221], v169 offset:17408
	ds_read_b128 v[222:225], v169 offset:18432
	ds_read_b128 v[226:229], v169 offset:19456
	ds_read_b128 v[230:233], v169 offset:20480
	ds_read_b128 v[234:237], v169 offset:21504
	ds_read_b128 v[238:241], v169 offset:22528
	ds_read_b128 v[242:245], v169 offset:23552
	global_load_lds_dwordx4 v[246:247], off
	s_add_i32 m0, s10, 0x2000
	s_add_u32 s10, s52, 0x80000
	v_lshl_add_u64 v[248:249], s[52:53], 0, v[130:131]
	s_addc_u32 s11, s53, 0
	s_add_i32 s76, s62, s2
	global_load_lds_dwordx4 v[248:249], off
	v_lshl_add_u64 v[250:251], s[10:11], 0, v[128:129]
	s_mov_b32 m0, s76
	v_lshl_add_u64 v[252:253], s[54:55], 0, v[130:131]
	global_load_lds_dwordx4 v[250:251], off
	v_lshl_add_u64 v[250:251], s[10:11], 0, v[130:131]
	s_add_i32 m0, s76, 0x2000
	s_nop 0
	global_load_lds_dwordx4 v[250:251], off
	v_lshl_add_u64 v[250:251], s[54:55], 0, v[128:129]
	s_mov_b32 m0, s15
	s_nop 0
	global_load_lds_dwordx4 v[250:251], off
	s_mov_b32 m0, s28
	s_nop 0
	global_load_lds_dwordx4 v[252:253], off
	s_waitcnt vmcnt(8)
	s_waitcnt lgkmcnt(0)
	s_setprio 1
	s_barrier
; #define PG8_STAGE(bufoff, gbase, voff) do { _Pragma("unroll") for (int _i = 0; _i < 2; ++_i) \
;         __builtin_amdgcn_global_load_lds((const unsigned*)((const char*)(gbase) + (voff)[_i]), (PG8_LAS unsigned*)(lds + (bufoff) + ldsw + _i * 8192), 16, 0, 0); } while (0)
; #define PG8_LDA(dst, b, h) do { _Pragma("unroll") for (int m = 0; m < 4; ++m) _Pragma("unroll") for (int k = 0; k < 2; ++k) dst[m][k] = *(const PG8_LAS bf16x8*)(lds + PG8_SA(b, h) + aoff + m * 2048 + k * 1024); } while (0)
; #define PG8_LDB(dst, b, h) do { _Pragma("unroll") for (int n = 0; n < 2; ++n) _Pragma("unroll") for (int k = 0; k < 2; ++k) dst[n][k] = *(const PG8_LAS bf16x8*)(lds + PG8_SB(b, h) + boff + n * 2048 + k * 1024); } while (0)
; #define PG8_MMA(ai, bj, At, Bt) do { __builtin_amdgcn_s_setprio(1); _Pragma("unroll") for (int m = 0; m < 4; ++m) _Pragma("unroll") for (int n = 0; n < 2; ++n) _Pragma("unroll") for (int k = 0; k < 2; ++k) \
;         acc[ai][bj][m][n] = __builtin_amdgcn_mfma_f32_16x16x32_bf16(Bt[n][k], At[m][k], acc[ai][bj][m][n], 0, 0, 0); __builtin_amdgcn_s_setprio(0); } while (0)
; #define PG8_WAIT_V(n) asm volatile("s_waitcnt vmcnt(" #n ")" ::: "memory")
; #define PG8_WAIT_L(n) asm volatile("s_waitcnt lgkmcnt(" #n ")" ::: "memory")
; #define PG8_BAR __builtin_amdgcn_s_barrier()
; #define PG8_SCHED __builtin_amdgcn_sched_barrier(0)
; template <class Epi, class Sched, bool ALIGN_EPI = false, bool SP2 = false>
; __device__ __forceinline__ void gemm_phase(PG8_LAS unsigned char* lds, const Gemm g, const Sched& S, const Epi& E) {
;     ...
;             PG8_WAIT_V(8); PG8_WAIT_L(0); PG8_BAR; PG8_MMA(1, 0, At, B0); PG8_MMA(1, 1, At, B1); PG8_BAR; PG8_SCHED;
;             PG8_LDB(B0, 1, 0); PG8_LDB(B1, 1, 1); PG8_SCHED; PG8_LDA(At, 1, 0); PG8_STAGE(PG8_SA(0, 1), a2 + hstep, voffA);
;             PG8_WAIT_V(8); PG8_WAIT_L(0); PG8_BAR; PG8_MMA(0, 0, At, B0); PG8_MMA(0, 1, At, B1); PG8_BAR; PG8_SCHED;
;             PG8_LDA(At, 1, 1); PG8_STAGE(PG8_SB(1, 0), b3, voffB); PG8_STAGE(PG8_SB(1, 1), b3 + hstep, voffB); PG8_STAGE(PG8_SA(1, 0), a3, voffA);
;             PG8_WAIT_V(8); PG8_WAIT_L(0); PG8_BAR; PG8_MMA(1, 0, At, B0); PG8_MMA(1, 1, At, B1); PG8_BAR; PG8_SCHED;
	v_mfma_f32_16x16x32_bf16 v[60:63], v[174:177], v[214:217], v[60:63]
	v_mfma_f32_16x16x32_bf16 v[56:59], v[190:193], v[214:217], v[56:59]
	v_mfma_f32_16x16x32_bf16 v[44:47], v[174:177], v[222:225], v[44:47]
	v_mfma_f32_16x16x32_bf16 v[40:43], v[190:193], v[222:225], v[40:43]
	v_mfma_f32_16x16x32_bf16 v[28:31], v[174:177], v[230:233], v[28:31]
	v_mfma_f32_16x16x32_bf16 v[24:27], v[190:193], v[230:233], v[24:27]
	v_mfma_f32_16x16x32_bf16 v[12:15], v[174:177], v[238:241], v[12:15]
	v_mfma_f32_16x16x32_bf16 v[8:11], v[190:193], v[238:241], v[8:11]
	v_mfma_f32_16x16x32_bf16 v[60:63], v[178:181], v[218:221], v[60:63]
	v_mfma_f32_16x16x32_bf16 v[56:59], v[194:197], v[218:221], v[56:59]
	v_mfma_f32_16x16x32_bf16 v[44:47], v[178:181], v[226:229], v[44:47]
	v_mfma_f32_16x16x32_bf16 v[40:43], v[194:197], v[226:229], v[40:43]
	v_mfma_f32_16x16x32_bf16 v[28:31], v[178:181], v[234:237], v[28:31]
	v_mfma_f32_16x16x32_bf16 v[24:27], v[194:197], v[234:237], v[24:27]
	v_mfma_f32_16x16x32_bf16 v[12:15], v[178:181], v[242:245], v[12:15]
	v_mfma_f32_16x16x32_bf16 v[8:11], v[194:197], v[242:245], v[8:11]
	s_setprio 0
	s_setprio 1
	v_mfma_f32_16x16x32_bf16 v[52:55], v[198:201], v[214:217], v[52:55]
	v_mfma_f32_16x16x32_bf16 v[48:51], v[206:209], v[214:217], v[48:51]
	v_mfma_f32_16x16x32_bf16 v[36:39], v[198:201], v[222:225], v[36:39]
	v_mfma_f32_16x16x32_bf16 v[32:35], v[206:209], v[222:225], v[32:35]
	v_mfma_f32_16x16x32_bf16 v[20:23], v[198:201], v[230:233], v[20:23]
	v_mfma_f32_16x16x32_bf16 v[16:19], v[206:209], v[230:233], v[16:19]
	v_mfma_f32_16x16x32_bf16 v[4:7], v[198:201], v[238:241], v[4:7]
	v_mfma_f32_16x16x32_bf16 v[0:3], v[206:209], v[238:241], v[0:3]
	v_mfma_f32_16x16x32_bf16 v[52:55], v[202:205], v[218:221], v[52:55]
	v_mfma_f32_16x16x32_bf16 v[48:51], v[210:213], v[218:221], v[48:51]
	v_mfma_f32_16x16x32_bf16 v[36:39], v[202:205], v[226:229], v[36:39]
	v_mfma_f32_16x16x32_bf16 v[32:35], v[210:213], v[226:229], v[32:35]
	v_mfma_f32_16x16x32_bf16 v[20:23], v[202:205], v[234:237], v[20:23]
	v_mfma_f32_16x16x32_bf16 v[16:19], v[210:213], v[234:237], v[16:19]
	v_mfma_f32_16x16x32_bf16 v[4:7], v[202:205], v[242:245], v[4:7]
	v_mfma_f32_16x16x32_bf16 v[0:3], v[210:213], v[242:245], v[0:3]
	s_barrier
	s_setprio 0
	s_sleep 2
	s_add_i32 s76, 0, 0x18000
	v_add_u32_e32 v188, s76, v149
	s_add_i32 s77, 0, 0x1c000
	ds_read_b128 v[174:177], v188
	ds_read_b128 v[178:181], v188 offset:1024
	ds_read_b128 v[190:193], v188 offset:2048
	ds_read_b128 v[194:197], v188 offset:3072
	v_add_u32_e32 v188, s77, v149
	ds_read_b128 v[198:201], v188
	ds_read_b128 v[202:205], v188 offset:1024
	ds_read_b128 v[206:209], v188 offset:2048
	ds_read_b128 v[210:213], v188 offset:3072
	s_add_u32 s10, s54, 0x80000
	s_addc_u32 s11, s55, 0
	s_mov_b32 m0, s29
	v_lshl_add_u64 v[188:189], s[10:11], 0, v[128:129]
	ds_read_b128 v[214:217], v169 offset:32768
	ds_read_b128 v[218:221], v169 offset:33792
	ds_read_b128 v[222:225], v169 offset:34816
	ds_read_b128 v[226:229], v169 offset:35840
	ds_read_b128 v[230:233], v169 offset:36864
	ds_read_b128 v[234:237], v169 offset:37888
	ds_read_b128 v[238:241], v169 offset:38912
	ds_read_b128 v[242:245], v169 offset:39936
	global_load_lds_dwordx4 v[188:189], off
	v_lshl_add_u64 v[188:189], s[10:11], 0, v[130:131]
	s_mov_b32 m0, s56
	s_nop 0
	global_load_lds_dwordx4 v[188:189], off
	s_waitcnt vmcnt(8)
	s_waitcnt lgkmcnt(0)
	s_setprio 1
	s_barrier
	v_mfma_f32_16x16x32_bf16 v[76:79], v[174:177], v[214:217], v[76:79]
	v_mfma_f32_16x16x32_bf16 v[72:75], v[190:193], v[214:217], v[72:75]
	v_mfma_f32_16x16x32_bf16 v[92:95], v[174:177], v[222:225], v[92:95]
	v_mfma_f32_16x16x32_bf16 v[88:91], v[190:193], v[222:225], v[88:91]
	v_mfma_f32_16x16x32_bf16 v[116:119], v[174:177], v[230:233], v[116:119]
	v_mfma_f32_16x16x32_bf16 v[112:115], v[190:193], v[230:233], v[112:115]
	v_mfma_f32_16x16x32_bf16 v[124:127], v[174:177], v[238:241], v[124:127]
	v_mfma_f32_16x16x32_bf16 v[120:123], v[190:193], v[238:241], v[120:123]
	v_mfma_f32_16x16x32_bf16 v[76:79], v[178:181], v[218:221], v[76:79]
	v_mfma_f32_16x16x32_bf16 v[72:75], v[194:197], v[218:221], v[72:75]
	v_mfma_f32_16x16x32_bf16 v[92:95], v[178:181], v[226:229], v[92:95]
	v_mfma_f32_16x16x32_bf16 v[88:91], v[194:197], v[226:229], v[88:91]
	v_mfma_f32_16x16x32_bf16 v[116:119], v[178:181], v[234:237], v[116:119]
	v_mfma_f32_16x16x32_bf16 v[112:115], v[194:197], v[234:237], v[112:115]
	v_mfma_f32_16x16x32_bf16 v[124:127], v[178:181], v[242:245], v[124:127]
	v_mfma_f32_16x16x32_bf16 v[120:123], v[194:197], v[242:245], v[120:123]
	s_setprio 0
	s_setprio 1
	v_mfma_f32_16x16x32_bf16 v[68:71], v[198:201], v[214:217], v[68:71]
	v_mfma_f32_16x16x32_bf16 v[64:67], v[206:209], v[214:217], v[64:67]
	v_mfma_f32_16x16x32_bf16 v[84:87], v[198:201], v[222:225], v[84:87]
	v_mfma_f32_16x16x32_bf16 v[80:83], v[206:209], v[222:225], v[80:83]
	v_mfma_f32_16x16x32_bf16 v[108:111], v[198:201], v[230:233], v[108:111]
	v_mfma_f32_16x16x32_bf16 v[96:99], v[206:209], v[230:233], v[96:99]
	v_mfma_f32_16x16x32_bf16 v[104:107], v[198:201], v[238:241], v[104:107]
	v_mfma_f32_16x16x32_bf16 v[100:103], v[206:209], v[238:241], v[100:103]
	v_mfma_f32_16x16x32_bf16 v[68:71], v[202:205], v[218:221], v[68:71]
	v_mfma_f32_16x16x32_bf16 v[64:67], v[210:213], v[218:221], v[64:67]
	v_mfma_f32_16x16x32_bf16 v[84:87], v[202:205], v[226:229], v[84:87]
	v_mfma_f32_16x16x32_bf16 v[80:83], v[210:213], v[226:229], v[80:83]
	v_mfma_f32_16x16x32_bf16 v[108:111], v[202:205], v[234:237], v[108:111]
	v_mfma_f32_16x16x32_bf16 v[96:99], v[210:213], v[234:237], v[96:99]
	v_mfma_f32_16x16x32_bf16 v[104:107], v[202:205], v[242:245], v[104:107]
	v_mfma_f32_16x16x32_bf16 v[100:103], v[210:213], v[242:245], v[100:103]
	s_barrier
; #define PG8_STAGE(bufoff, gbase, voff) do { _Pragma("unroll") for (int _i = 0; _i < 2; ++_i) \
;         __builtin_amdgcn_global_load_lds((const unsigned*)((const char*)(gbase) + (voff)[_i]), (PG8_LAS unsigned*)(lds + (bufoff) + ldsw + _i * 8192), 16, 0, 0); } while (0)
; #define PG8_LDA(dst, b, h) do { _Pragma("unroll") for (int m = 0; m < 4; ++m) _Pragma("unroll") for (int k = 0; k < 2; ++k) dst[m][k] = *(const PG8_LAS bf16x8*)(lds + PG8_SA(b, h) + aoff + m * 2048 + k * 1024); } while (0)
; #define PG8_MMA(ai, bj, At, Bt) do { __builtin_amdgcn_s_setprio(1); _Pragma("unroll") for (int m = 0; m < 4; ++m) _Pragma("unroll") for (int n = 0; n < 2; ++n) _Pragma("unroll") for (int k = 0; k < 2; ++k) \
;         acc[ai][bj][m][n] = __builtin_amdgcn_mfma_f32_16x16x32_bf16(Bt[n][k], At[m][k], acc[ai][bj][m][n], 0, 0, 0); __builtin_amdgcn_s_setprio(0); } while (0)
; #define PG8_WAIT_V(n) asm volatile("s_waitcnt vmcnt(" #n ")" ::: "memory")
; #define PG8_WAIT_L(n) asm volatile("s_waitcnt lgkmcnt(" #n ")" ::: "memory")
; #define PG8_BAR __builtin_amdgcn_s_barrier()
; #define PG8_SCHED __builtin_amdgcn_sched_barrier(0)
; template <class Epi, class Sched, bool ALIGN_EPI = false, bool SP2 = false>
; __device__ __forceinline__ void gemm_phase(PG8_LAS unsigned char* lds, const Gemm g, const Sched& S, const Epi& E) {
;     ...
;             PG8_LDA(At, 1, 1); PG8_STAGE(PG8_SB(1, 0), b3, voffB); PG8_STAGE(PG8_SB(1, 1), b3 + hstep, voffB); PG8_STAGE(PG8_SA(1, 0), a3, voffA);
;             PG8_WAIT_V(8); PG8_WAIT_L(0); PG8_BAR; PG8_MMA(1, 0, At, B0); PG8_MMA(1, 1, At, B1); PG8_BAR; PG8_SCHED;
	s_setprio 0
	s_sleep 2
	s_add_i32 s10, s76, s2
	v_lshl_add_u64 v[188:189], v[246:247], 0, s[38:39]
	s_mov_b32 m0, s10
	ds_read_b128 v[214:217], v169 offset:49152
	ds_read_b128 v[218:221], v169 offset:50176
	ds_read_b128 v[222:225], v169 offset:51200
	ds_read_b128 v[226:229], v169 offset:52224
	ds_read_b128 v[230:233], v169 offset:53248
	ds_read_b128 v[234:237], v169 offset:54272
	ds_read_b128 v[238:241], v169 offset:55296
	ds_read_b128 v[242:245], v169 offset:56320
	global_load_lds_dwordx4 v[188:189], off
	s_add_i32 m0, s10, 0x2000
	s_add_u32 s10, s52, 0x80080
	v_lshl_add_u64 v[188:189], v[248:249], 0, s[38:39]
	s_addc_u32 s11, s53, 0
	s_add_i32 s52, s77, s2
	global_load_lds_dwordx4 v[188:189], off
	v_lshl_add_u64 v[188:189], s[10:11], 0, v[128:129]
	s_mov_b32 m0, s52
	s_nop 0
	global_load_lds_dwordx4 v[188:189], off
	v_lshl_add_u64 v[188:189], s[10:11], 0, v[130:131]
	s_add_i32 m0, s52, 0x2000
	s_nop 0
	global_load_lds_dwordx4 v[188:189], off
	v_lshl_add_u64 v[188:189], v[250:251], 0, s[38:39]
	s_mov_b32 m0, s59
	s_nop 0
	global_load_lds_dwordx4 v[188:189], off
	v_lshl_add_u64 v[188:189], v[252:253], 0, s[38:39]
	s_mov_b32 m0, s60
	s_nop 0
	global_load_lds_dwordx4 v[188:189], off
	s_waitcnt vmcnt(8)
	s_waitcnt lgkmcnt(0)
	s_setprio 1
	s_barrier
	v_mfma_f32_16x16x32_bf16 v[60:63], v[174:177], v[214:217], v[60:63]
	v_mfma_f32_16x16x32_bf16 v[56:59], v[190:193], v[214:217], v[56:59]
	v_mfma_f32_16x16x32_bf16 v[44:47], v[174:177], v[222:225], v[44:47]
	v_mfma_f32_16x16x32_bf16 v[40:43], v[190:193], v[222:225], v[40:43]
	v_mfma_f32_16x16x32_bf16 v[28:31], v[174:177], v[230:233], v[28:31]
	v_mfma_f32_16x16x32_bf16 v[24:27], v[190:193], v[230:233], v[24:27]
	v_mfma_f32_16x16x32_bf16 v[12:15], v[174:177], v[238:241], v[12:15]
	v_mfma_f32_16x16x32_bf16 v[8:11], v[190:193], v[238:241], v[8:11]
	v_mfma_f32_16x16x32_bf16 v[60:63], v[178:181], v[218:221], v[60:63]
	v_mfma_f32_16x16x32_bf16 v[56:59], v[194:197], v[218:221], v[56:59]
	v_mfma_f32_16x16x32_bf16 v[44:47], v[178:181], v[226:229], v[44:47]
	v_mfma_f32_16x16x32_bf16 v[40:43], v[194:197], v[226:229], v[40:43]
	v_mfma_f32_16x16x32_bf16 v[28:31], v[178:181], v[234:237], v[28:31]
	v_mfma_f32_16x16x32_bf16 v[24:27], v[194:197], v[234:237], v[24:27]
	v_mfma_f32_16x16x32_bf16 v[12:15], v[178:181], v[242:245], v[12:15]
	v_mfma_f32_16x16x32_bf16 v[8:11], v[194:197], v[242:245], v[8:11]
	s_setprio 0
	s_setprio 1
	v_mfma_f32_16x16x32_bf16 v[52:55], v[198:201], v[214:217], v[52:55]
	v_mfma_f32_16x16x32_bf16 v[48:51], v[206:209], v[214:217], v[48:51]
	v_mfma_f32_16x16x32_bf16 v[36:39], v[198:201], v[222:225], v[36:39]
	v_mfma_f32_16x16x32_bf16 v[32:35], v[206:209], v[222:225], v[32:35]
	v_mfma_f32_16x16x32_bf16 v[20:23], v[198:201], v[230:233], v[20:23]
	v_mfma_f32_16x16x32_bf16 v[16:19], v[206:209], v[230:233], v[16:19]
	v_mfma_f32_16x16x32_bf16 v[4:7], v[198:201], v[238:241], v[4:7]
	v_mfma_f32_16x16x32_bf16 v[0:3], v[206:209], v[238:241], v[0:3]
	v_mfma_f32_16x16x32_bf16 v[52:55], v[202:205], v[218:221], v[52:55]
	v_mfma_f32_16x16x32_bf16 v[48:51], v[210:213], v[218:221], v[48:51]
	v_mfma_f32_16x16x32_bf16 v[36:39], v[202:205], v[226:229], v[36:39]
	v_mfma_f32_16x16x32_bf16 v[32:35], v[210:213], v[226:229], v[32:35]
	v_mfma_f32_16x16x32_bf16 v[20:23], v[202:205], v[234:237], v[20:23]
	v_mfma_f32_16x16x32_bf16 v[16:19], v[210:213], v[234:237], v[16:19]
	v_mfma_f32_16x16x32_bf16 v[4:7], v[202:205], v[242:245], v[4:7]
	v_mfma_f32_16x16x32_bf16 v[0:3], v[210:213], v[242:245], v[0:3]
	s_barrier
	s_setprio 0
	s_sleep 2
	s_add_i32 s67, s67, 2
	s_cmp_gt_u32 s67, 29
	s_mov_b64 s[10:11], s[50:51]
	s_cbranch_scc0 .LBB0_560
	s_and_b64 vcc, exec, s[40:41]
	s_cbranch_vccz .LBB0_563
	s_barrier

; #define PG8_STAGE(bufoff, gbase, voff) do { _Pragma("unroll") for (int _i = 0; _i < 2; ++_i) \
;         __builtin_amdgcn_global_load_lds((const unsigned*)((const char*)(gbase) + (voff)[_i]), (PG8_LAS unsigned*)(lds + (bufoff) + ldsw + _i * 8192), 16, 0, 0); } while (0)
; #define PG8_LDA(dst, b, h) do { _Pragma("unroll") for (int m = 0; m < 4; ++m) _Pragma("unroll") for (int k = 0; k < 2; ++k) dst[m][k] = *(const PG8_LAS bf16x8*)(lds + PG8_SA(b, h) + aoff + m * 2048 + k * 1024); } while (0)
; #define PG8_LDB(dst, b, h) do { _Pragma("unroll") for (int n = 0; n < 2; ++n) _Pragma("unroll") for (int k = 0; k < 2; ++k) dst[n][k] = *(const PG8_LAS bf16x8*)(lds + PG8_SB(b, h) + boff + n * 2048 + k * 1024); } while (0)
; #define PG8_MMA(ai, bj, At, Bt) do { __builtin_amdgcn_s_setprio(1); _Pragma("unroll") for (int m = 0; m < 4; ++m) _Pragma("unroll") for (int n = 0; n < 2; ++n) _Pragma("unroll") for (int k = 0; k < 2; ++k) \
;         acc[ai][bj][m][n] = __builtin_amdgcn_mfma_f32_16x16x32_bf16(Bt[n][k], At[m][k], acc[ai][bj][m][n], 0, 0, 0); __builtin_amdgcn_s_setprio(0); } while (0)
; #define PG8_WAIT_V(n) asm volatile("s_waitcnt vmcnt(" #n ")" ::: "memory")
; #define PG8_WAIT_L(n) asm volatile("s_waitcnt lgkmcnt(" #n ")" ::: "memory")
; template <class Epi, class Sched, bool ALIGN_EPI = false, bool SP2 = false>
; __device__ __forceinline__ void gemm_phase(PG8_LAS unsigned char* lds, const Gemm g, const Sched& S, const Epi& E) {
;     ...
;             const bool last = (t == nt - 2);
;             const char* a1 = cA + (size_t)(t + 1) * kstep;
;             const char* a2 = last ? nA : cA + (size_t)(t + 2) * kstep; const char* b2 = last ? nB : cB + (size_t)(t + 2) * kstep;
;             const char* a3 = a2 + kstep; const char* b3 = b2 + kstep;
;             if (last && has_next) S.a_ready(nxt);
;             if constexpr (SP2) {
;             PG8_LDB(B0, 0, 0); PG8_LDB(B1, 0, 1); PG8_SCHED; PG8_LDA(At, 0, 0); PG8_STAGE(PG8_SA(1, 1), a1 + hstep, voffA);
;             PG8_WAIT_V(8); PG8_WAIT_L(0); PG8_BAR; PG8_MMA(0, 0, At, B0); PG8_MMA(0, 1, At, B1); PG8_BAR; PG8_SCHED;
;             PG8_LDA(At, 0, 1); PG8_STAGE(PG8_SB(0, 0), b2, voffB); PG8_STAGE(PG8_SB(0, 1), b2 + hstep, voffB); PG8_STAGE(PG8_SA(0, 0), a2, voffA);
;             PG8_WAIT_V(8); PG8_WAIT_L(0); PG8_BAR; PG8_MMA(1, 0, At, B0); PG8_MMA(1, 1, At, B1); PG8_BAR; PG8_SCHED;
.LBB0_621:
	ds_read_b128 v[146:149], v153
	ds_read_b128 v[156:159], v153 offset:1024
	ds_read_b128 v[160:163], v153 offset:2048
	ds_read_b128 v[164:167], v153 offset:3072
	ds_read_b128 v[168:171], v154
	ds_read_b128 v[172:175], v154 offset:1024
	ds_read_b128 v[176:179], v154 offset:2048
	ds_read_b128 v[190:193], v154 offset:3072
	s_add_u32 s34, s30, 0xfff80080
	s_addc_u32 s35, s31, -1
	s_cmp_eq_u32 s50, 28
	s_cselect_b32 s37, s15, s35
	s_cselect_b32 s36, s46, s34
	s_cselect_b32 s35, s13, s49
	s_cselect_b32 s34, s47, s48
	v_lshl_add_u64 v[180:181], s[30:31], 0, v[136:137]
	s_add_i32 m0, s23, 0xc000
	ds_read_b128 v[194:197], v155
	ds_read_b128 v[198:201], v155 offset:1024
	ds_read_b128 v[202:205], v155 offset:2048
	ds_read_b128 v[206:209], v155 offset:3072
	ds_read_b128 v[210:213], v155 offset:4096
	ds_read_b128 v[214:217], v155 offset:5120
	ds_read_b128 v[218:221], v155 offset:6144
	ds_read_b128 v[222:225], v155 offset:7168
	global_load_lds_dwordx4 v[180:181], off
	v_lshl_add_u64 v[180:181], s[30:31], 0, v[138:139]
	s_add_i32 m0, s23, 0xe000
	s_nop 0
	global_load_lds_dwordx4 v[180:181], off
	s_waitcnt vmcnt(8)
	s_waitcnt lgkmcnt(0)
	s_setprio 1
	s_barrier
	v_mfma_f32_16x16x32_bf16 v[124:127], v[146:149], v[194:197], v[124:127]
	v_mfma_f32_16x16x32_bf16 v[120:123], v[160:163], v[194:197], v[120:123]
	v_mfma_f32_16x16x32_bf16 v[108:111], v[146:149], v[202:205], v[108:111]
	v_mfma_f32_16x16x32_bf16 v[104:107], v[160:163], v[202:205], v[104:107]
	v_mfma_f32_16x16x32_bf16 v[92:95], v[146:149], v[210:213], v[92:95]
	v_mfma_f32_16x16x32_bf16 v[88:91], v[160:163], v[210:213], v[88:91]
	v_mfma_f32_16x16x32_bf16 v[76:79], v[146:149], v[218:221], v[76:79]
	v_mfma_f32_16x16x32_bf16 v[72:75], v[160:163], v[218:221], v[72:75]
	v_mfma_f32_16x16x32_bf16 v[124:127], v[156:159], v[198:201], v[124:127]
	v_mfma_f32_16x16x32_bf16 v[120:123], v[164:167], v[198:201], v[120:123]
	v_mfma_f32_16x16x32_bf16 v[108:111], v[156:159], v[206:209], v[108:111]
	v_mfma_f32_16x16x32_bf16 v[104:107], v[164:167], v[206:209], v[104:107]
	v_mfma_f32_16x16x32_bf16 v[92:95], v[156:159], v[214:217], v[92:95]
	v_mfma_f32_16x16x32_bf16 v[88:91], v[164:167], v[214:217], v[88:91]
	v_mfma_f32_16x16x32_bf16 v[76:79], v[156:159], v[222:225], v[76:79]
	v_mfma_f32_16x16x32_bf16 v[72:75], v[164:167], v[222:225], v[72:75]
	s_setprio 0
	s_setprio 1
	v_mfma_f32_16x16x32_bf16 v[116:119], v[168:171], v[194:197], v[116:119]
	v_mfma_f32_16x16x32_bf16 v[112:115], v[176:179], v[194:197], v[112:115]
	v_mfma_f32_16x16x32_bf16 v[100:103], v[168:171], v[202:205], v[100:103]
	v_mfma_f32_16x16x32_bf16 v[96:99], v[176:179], v[202:205], v[96:99]
	v_mfma_f32_16x16x32_bf16 v[84:87], v[168:171], v[210:213], v[84:87]
	v_mfma_f32_16x16x32_bf16 v[80:83], v[176:179], v[210:213], v[80:83]
	v_mfma_f32_16x16x32_bf16 v[68:71], v[168:171], v[218:221], v[68:71]
	v_mfma_f32_16x16x32_bf16 v[64:67], v[176:179], v[218:221], v[64:67]
	v_mfma_f32_16x16x32_bf16 v[116:119], v[172:175], v[198:201], v[116:119]
	v_mfma_f32_16x16x32_bf16 v[112:115], v[190:193], v[198:201], v[112:115]
	v_mfma_f32_16x16x32_bf16 v[100:103], v[172:175], v[206:209], v[100:103]
	v_mfma_f32_16x16x32_bf16 v[96:99], v[190:193], v[206:209], v[96:99]
	v_mfma_f32_16x16x32_bf16 v[84:87], v[172:175], v[214:217], v[84:87]
	v_mfma_f32_16x16x32_bf16 v[80:83], v[190:193], v[214:217], v[80:83]
	v_mfma_f32_16x16x32_bf16 v[68:71], v[172:175], v[222:225], v[68:71]
	v_mfma_f32_16x16x32_bf16 v[64:67], v[190:193], v[222:225], v[64:67]
	s_barrier
	s_setprio 0
	s_sleep 2
	s_add_i32 s51, s42, s2
	v_lshl_add_u64 v[180:181], s[34:35], 0, v[132:133]
	s_mov_b32 m0, s51
	ds_read_b128 v[194:197], v155 offset:16384
	ds_read_b128 v[198:201], v155 offset:17408
	ds_read_b128 v[202:205], v155 offset:18432
	ds_read_b128 v[206:209], v155 offset:19456
	ds_read_b128 v[210:213], v155 offset:20480
	ds_read_b128 v[214:217], v155 offset:21504
	ds_read_b128 v[218:221], v155 offset:22528
	ds_read_b128 v[222:225], v155 offset:23552
	global_load_lds_dwordx4 v[180:181], off
	s_add_i32 m0, s51, 0x2000
	s_add_u32 s52, s34, 0x80000
	v_lshl_add_u64 v[188:189], s[34:35], 0, v[128:129]
	s_addc_u32 s53, s35, 0
	s_add_i32 s51, s43, s2
	global_load_lds_dwordx4 v[188:189], off
	v_lshl_add_u64 v[226:227], s[52:53], 0, v[132:133]
	s_mov_b32 m0, s51
	v_lshl_add_u64 v[228:229], s[36:37], 0, v[130:131]
	global_load_lds_dwordx4 v[226:227], off
	v_lshl_add_u64 v[226:227], s[52:53], 0, v[128:129]
	s_add_i32 m0, s51, 0x2000
	s_nop 0
	global_load_lds_dwordx4 v[226:227], off
	v_lshl_add_u64 v[226:227], s[36:37], 0, v[134:135]
	s_mov_b32 m0, s23
	s_nop 0
	global_load_lds_dwordx4 v[226:227], off
	s_mov_b32 m0, s28
	s_nop 0
	global_load_lds_dwordx4 v[228:229], off
	s_waitcnt vmcnt(8)
	s_waitcnt lgkmcnt(0)
	s_setprio 1
	s_barrier
; #define PG8_STAGE(bufoff, gbase, voff) do { _Pragma("unroll") for (int _i = 0; _i < 2; ++_i) \
;         __builtin_amdgcn_global_load_lds((const unsigned*)((const char*)(gbase) + (voff)[_i]), (PG8_LAS unsigned*)(lds + (bufoff) + ldsw + _i * 8192), 16, 0, 0); } while (0)
; #define PG8_LDA(dst, b, h) do { _Pragma("unroll") for (int m = 0; m < 4; ++m) _Pragma("unroll") for (int k = 0; k < 2; ++k) dst[m][k] = *(const PG8_LAS bf16x8*)(lds + PG8_SA(b, h) + aoff + m * 2048 + k * 1024); } while (0)
; #define PG8_LDB(dst, b, h) do { _Pragma("unroll") for (int n = 0; n < 2; ++n) _Pragma("unroll") for (int k = 0; k < 2; ++k) dst[n][k] = *(const PG8_LAS bf16x8*)(lds + PG8_SB(b, h) + boff + n * 2048 + k * 1024); } while (0)
; #define PG8_MMA(ai, bj, At, Bt) do { __builtin_amdgcn_s_setprio(1); _Pragma("unroll") for (int m = 0; m < 4; ++m) _Pragma("unroll") for (int n = 0; n < 2; ++n) _Pragma("unroll") for (int k = 0; k < 2; ++k) \
;         acc[ai][bj][m][n] = __builtin_amdgcn_mfma_f32_16x16x32_bf16(Bt[n][k], At[m][k], acc[ai][bj][m][n], 0, 0, 0); __builtin_amdgcn_s_setprio(0); } while (0)
; #define PG8_WAIT_V(n) asm volatile("s_waitcnt vmcnt(" #n ")" ::: "memory")
; #define PG8_WAIT_L(n) asm volatile("s_waitcnt lgkmcnt(" #n ")" ::: "memory")
; #define PG8_BAR __builtin_amdgcn_s_barrier()
; #define PG8_SCHED __builtin_amdgcn_sched_barrier(0)
; template <class Epi, class Sched, bool ALIGN_EPI = false, bool SP2 = false>
; __device__ __forceinline__ void gemm_phase(PG8_LAS unsigned char* lds, const Gemm g, const Sched& S, const Epi& E) {
;     ...
;             PG8_WAIT_V(8); PG8_WAIT_L(0); PG8_BAR; PG8_MMA(1, 0, At, B0); PG8_MMA(1, 1, At, B1); PG8_BAR; PG8_SCHED;
;             PG8_LDB(B0, 1, 0); PG8_LDB(B1, 1, 1); PG8_SCHED; PG8_LDA(At, 1, 0); PG8_STAGE(PG8_SA(0, 1), a2 + hstep, voffA);
;             PG8_WAIT_V(8); PG8_WAIT_L(0); PG8_BAR; PG8_MMA(0, 0, At, B0); PG8_MMA(0, 1, At, B1); PG8_BAR; PG8_SCHED;
;             PG8_LDA(At, 1, 1); PG8_STAGE(PG8_SB(1, 0), b3, voffB); PG8_STAGE(PG8_SB(1, 1), b3 + hstep, voffB); PG8_STAGE(PG8_SA(1, 0), a3, voffA);
;             PG8_WAIT_V(8); PG8_WAIT_L(0); PG8_BAR; PG8_MMA(1, 0, At, B0); PG8_MMA(1, 1, At, B1); PG8_BAR; PG8_SCHED;
	v_mfma_f32_16x16x32_bf16 v[60:63], v[146:149], v[194:197], v[60:63]
	v_mfma_f32_16x16x32_bf16 v[56:59], v[160:163], v[194:197], v[56:59]
	v_mfma_f32_16x16x32_bf16 v[44:47], v[146:149], v[202:205], v[44:47]
	v_mfma_f32_16x16x32_bf16 v[40:43], v[160:163], v[202:205], v[40:43]
	v_mfma_f32_16x16x32_bf16 v[28:31], v[146:149], v[210:213], v[28:31]
	v_mfma_f32_16x16x32_bf16 v[24:27], v[160:163], v[210:213], v[24:27]
	v_mfma_f32_16x16x32_bf16 v[12:15], v[146:149], v[218:221], v[12:15]
	v_mfma_f32_16x16x32_bf16 v[8:11], v[160:163], v[218:221], v[8:11]
	v_mfma_f32_16x16x32_bf16 v[60:63], v[156:159], v[198:201], v[60:63]
	v_mfma_f32_16x16x32_bf16 v[56:59], v[164:167], v[198:201], v[56:59]
	v_mfma_f32_16x16x32_bf16 v[44:47], v[156:159], v[206:209], v[44:47]
	v_mfma_f32_16x16x32_bf16 v[40:43], v[164:167], v[206:209], v[40:43]
	v_mfma_f32_16x16x32_bf16 v[28:31], v[156:159], v[214:217], v[28:31]
	v_mfma_f32_16x16x32_bf16 v[24:27], v[164:167], v[214:217], v[24:27]
	v_mfma_f32_16x16x32_bf16 v[12:15], v[156:159], v[222:225], v[12:15]
	v_mfma_f32_16x16x32_bf16 v[8:11], v[164:167], v[222:225], v[8:11]
	s_setprio 0
	s_setprio 1
	v_mfma_f32_16x16x32_bf16 v[52:55], v[168:171], v[194:197], v[52:55]
	v_mfma_f32_16x16x32_bf16 v[48:51], v[176:179], v[194:197], v[48:51]
	v_mfma_f32_16x16x32_bf16 v[36:39], v[168:171], v[202:205], v[36:39]
	v_mfma_f32_16x16x32_bf16 v[32:35], v[176:179], v[202:205], v[32:35]
	v_mfma_f32_16x16x32_bf16 v[20:23], v[168:171], v[210:213], v[20:23]
	v_mfma_f32_16x16x32_bf16 v[16:19], v[176:179], v[210:213], v[16:19]
	v_mfma_f32_16x16x32_bf16 v[4:7], v[168:171], v[218:221], v[4:7]
	v_mfma_f32_16x16x32_bf16 v[0:3], v[176:179], v[218:221], v[0:3]
	v_mfma_f32_16x16x32_bf16 v[52:55], v[172:175], v[198:201], v[52:55]
	v_mfma_f32_16x16x32_bf16 v[48:51], v[190:193], v[198:201], v[48:51]
	v_mfma_f32_16x16x32_bf16 v[36:39], v[172:175], v[206:209], v[36:39]
	v_mfma_f32_16x16x32_bf16 v[32:35], v[190:193], v[206:209], v[32:35]
	v_mfma_f32_16x16x32_bf16 v[20:23], v[172:175], v[214:217], v[20:23]
	v_mfma_f32_16x16x32_bf16 v[16:19], v[190:193], v[214:217], v[16:19]
	v_mfma_f32_16x16x32_bf16 v[4:7], v[172:175], v[222:225], v[4:7]
	v_mfma_f32_16x16x32_bf16 v[0:3], v[190:193], v[222:225], v[0:3]
	s_barrier
	s_setprio 0
	s_sleep 2
	s_add_i32 s51, 0, 0x18000
	s_add_i32 s52, 0, 0x1c000
	v_add_u32_e32 v164, s51, v151
	v_add_u32_e32 v190, s52, v151
	ds_read_b128 v[146:149], v164
	ds_read_b128 v[156:159], v164 offset:1024
	ds_read_b128 v[160:163], v164 offset:2048
	ds_read_b128 v[164:167], v164 offset:3072
	ds_read_b128 v[168:171], v190
	ds_read_b128 v[172:175], v190 offset:1024
	ds_read_b128 v[176:179], v190 offset:2048
	ds_read_b128 v[190:193], v190 offset:3072
	s_add_u32 s36, s36, 0x80000
	s_addc_u32 s37, s37, 0
	s_mov_b32 m0, s29
	v_lshl_add_u64 v[230:231], s[36:37], 0, v[134:135]
	ds_read_b128 v[194:197], v155 offset:32768
	ds_read_b128 v[198:201], v155 offset:33792
	ds_read_b128 v[202:205], v155 offset:34816
	ds_read_b128 v[206:209], v155 offset:35840
	ds_read_b128 v[210:213], v155 offset:36864
	ds_read_b128 v[214:217], v155 offset:37888
	ds_read_b128 v[218:221], v155 offset:38912
	ds_read_b128 v[222:225], v155 offset:39936
	global_load_lds_dwordx4 v[230:231], off
	v_lshl_add_u64 v[230:231], s[36:37], 0, v[130:131]
	s_mov_b32 m0, s38
	s_nop 0
	global_load_lds_dwordx4 v[230:231], off
	s_waitcnt vmcnt(8)
	s_waitcnt lgkmcnt(0)
	s_setprio 1
	s_barrier
	v_mfma_f32_16x16x32_bf16 v[124:127], v[146:149], v[194:197], v[124:127]
	v_mfma_f32_16x16x32_bf16 v[120:123], v[160:163], v[194:197], v[120:123]
	v_mfma_f32_16x16x32_bf16 v[108:111], v[146:149], v[202:205], v[108:111]
	v_mfma_f32_16x16x32_bf16 v[104:107], v[160:163], v[202:205], v[104:107]
	v_mfma_f32_16x16x32_bf16 v[92:95], v[146:149], v[210:213], v[92:95]
	v_mfma_f32_16x16x32_bf16 v[88:91], v[160:163], v[210:213], v[88:91]
	v_mfma_f32_16x16x32_bf16 v[76:79], v[146:149], v[218:221], v[76:79]
	v_mfma_f32_16x16x32_bf16 v[72:75], v[160:163], v[218:221], v[72:75]
	v_mfma_f32_16x16x32_bf16 v[124:127], v[156:159], v[198:201], v[124:127]
	v_mfma_f32_16x16x32_bf16 v[120:123], v[164:167], v[198:201], v[120:123]
	v_mfma_f32_16x16x32_bf16 v[108:111], v[156:159], v[206:209], v[108:111]
	v_mfma_f32_16x16x32_bf16 v[104:107], v[164:167], v[206:209], v[104:107]
	v_mfma_f32_16x16x32_bf16 v[92:95], v[156:159], v[214:217], v[92:95]
	v_mfma_f32_16x16x32_bf16 v[88:91], v[164:167], v[214:217], v[88:91]
	v_mfma_f32_16x16x32_bf16 v[76:79], v[156:159], v[222:225], v[76:79]
	v_mfma_f32_16x16x32_bf16 v[72:75], v[164:167], v[222:225], v[72:75]
	s_setprio 0
	s_setprio 1
	v_mfma_f32_16x16x32_bf16 v[116:119], v[168:171], v[194:197], v[116:119]
	v_mfma_f32_16x16x32_bf16 v[112:115], v[176:179], v[194:197], v[112:115]
	v_mfma_f32_16x16x32_bf16 v[100:103], v[168:171], v[202:205], v[100:103]
	v_mfma_f32_16x16x32_bf16 v[96:99], v[176:179], v[202:205], v[96:99]
	v_mfma_f32_16x16x32_bf16 v[84:87], v[168:171], v[210:213], v[84:87]
	v_mfma_f32_16x16x32_bf16 v[80:83], v[176:179], v[210:213], v[80:83]
	v_mfma_f32_16x16x32_bf16 v[68:71], v[168:171], v[218:221], v[68:71]
	v_mfma_f32_16x16x32_bf16 v[64:67], v[176:179], v[218:221], v[64:67]
	v_mfma_f32_16x16x32_bf16 v[116:119], v[172:175], v[198:201], v[116:119]
	v_mfma_f32_16x16x32_bf16 v[112:115], v[190:193], v[198:201], v[112:115]
	v_mfma_f32_16x16x32_bf16 v[100:103], v[172:175], v[206:209], v[100:103]
	v_mfma_f32_16x16x32_bf16 v[96:99], v[190:193], v[206:209], v[96:99]
	v_mfma_f32_16x16x32_bf16 v[84:87], v[172:175], v[214:217], v[84:87]
	v_mfma_f32_16x16x32_bf16 v[80:83], v[190:193], v[214:217], v[80:83]
	v_mfma_f32_16x16x32_bf16 v[68:71], v[172:175], v[222:225], v[68:71]
	v_mfma_f32_16x16x32_bf16 v[64:67], v[190:193], v[222:225], v[64:67]
	s_barrier
; #define PG8_STAGE(bufoff, gbase, voff) do { _Pragma("unroll") for (int _i = 0; _i < 2; ++_i) \
;         __builtin_amdgcn_global_load_lds((const unsigned*)((const char*)(gbase) + (voff)[_i]), (PG8_LAS unsigned*)(lds + (bufoff) + ldsw + _i * 8192), 16, 0, 0); } while (0)
; #define PG8_LDA(dst, b, h) do { _Pragma("unroll") for (int m = 0; m < 4; ++m) _Pragma("unroll") for (int k = 0; k < 2; ++k) dst[m][k] = *(const PG8_LAS bf16x8*)(lds + PG8_SA(b, h) + aoff + m * 2048 + k * 1024); } while (0)
; #define PG8_MMA(ai, bj, At, Bt) do { __builtin_amdgcn_s_setprio(1); _Pragma("unroll") for (int m = 0; m < 4; ++m) _Pragma("unroll") for (int n = 0; n < 2; ++n) _Pragma("unroll") for (int k = 0; k < 2; ++k) \
;         acc[ai][bj][m][n] = __builtin_amdgcn_mfma_f32_16x16x32_bf16(Bt[n][k], At[m][k], acc[ai][bj][m][n], 0, 0, 0); __builtin_amdgcn_s_setprio(0); } while (0)
; #define PG8_WAIT_V(n) asm volatile("s_waitcnt vmcnt(" #n ")" ::: "memory")
; #define PG8_WAIT_L(n) asm volatile("s_waitcnt lgkmcnt(" #n ")" ::: "memory")
; #define PG8_BAR __builtin_amdgcn_s_barrier()
; #define PG8_SCHED __builtin_amdgcn_sched_barrier(0)
; template <class Epi, class Sched, bool ALIGN_EPI = false, bool SP2 = false>
; __device__ __forceinline__ void gemm_phase(PG8_LAS unsigned char* lds, const Gemm g, const Sched& S, const Epi& E) {
;     ...
;             PG8_LDA(At, 1, 1); PG8_STAGE(PG8_SB(1, 0), b3, voffB); PG8_STAGE(PG8_SB(1, 1), b3 + hstep, voffB); PG8_STAGE(PG8_SA(1, 0), a3, voffA);
;             PG8_WAIT_V(8); PG8_WAIT_L(0); PG8_BAR; PG8_MMA(1, 0, At, B0); PG8_MMA(1, 1, At, B1); PG8_BAR; PG8_SCHED;
	s_setprio 0
	s_sleep 2
	s_add_i32 s36, s51, s2
	v_lshl_add_u64 v[180:181], v[180:181], 0, s[8:9]
	s_mov_b32 m0, s36
	ds_read_b128 v[194:197], v155 offset:49152
	ds_read_b128 v[198:201], v155 offset:50176
	ds_read_b128 v[202:205], v155 offset:51200
	ds_read_b128 v[206:209], v155 offset:52224
	ds_read_b128 v[210:213], v155 offset:53248
	ds_read_b128 v[214:217], v155 offset:54272
	ds_read_b128 v[218:221], v155 offset:55296
	ds_read_b128 v[222:225], v155 offset:56320
	global_load_lds_dwordx4 v[180:181], off
	s_add_i32 m0, s36, 0x2000
	s_add_u32 s34, s34, 0x80080
	v_lshl_add_u64 v[180:181], v[188:189], 0, s[8:9]
	s_addc_u32 s35, s35, 0
	s_add_i32 s36, s52, s2
	global_load_lds_dwordx4 v[180:181], off
	v_lshl_add_u64 v[180:181], s[34:35], 0, v[132:133]
	s_mov_b32 m0, s36
	s_nop 0
	global_load_lds_dwordx4 v[180:181], off
	v_lshl_add_u64 v[180:181], s[34:35], 0, v[128:129]
	s_add_i32 m0, s36, 0x2000
	s_nop 0
	global_load_lds_dwordx4 v[180:181], off
	v_lshl_add_u64 v[180:181], v[226:227], 0, s[8:9]
	s_mov_b32 m0, s40
	s_nop 0
	global_load_lds_dwordx4 v[180:181], off
	v_lshl_add_u64 v[180:181], v[228:229], 0, s[8:9]
	s_mov_b32 m0, s41
	s_nop 0
	global_load_lds_dwordx4 v[180:181], off
	s_waitcnt vmcnt(8)
	s_waitcnt lgkmcnt(0)
	s_setprio 1
	s_barrier
	v_mfma_f32_16x16x32_bf16 v[60:63], v[146:149], v[194:197], v[60:63]
	v_mfma_f32_16x16x32_bf16 v[56:59], v[160:163], v[194:197], v[56:59]
	v_mfma_f32_16x16x32_bf16 v[44:47], v[146:149], v[202:205], v[44:47]
	v_mfma_f32_16x16x32_bf16 v[40:43], v[160:163], v[202:205], v[40:43]
	v_mfma_f32_16x16x32_bf16 v[28:31], v[146:149], v[210:213], v[28:31]
	v_mfma_f32_16x16x32_bf16 v[24:27], v[160:163], v[210:213], v[24:27]
	v_mfma_f32_16x16x32_bf16 v[12:15], v[146:149], v[218:221], v[12:15]
	v_mfma_f32_16x16x32_bf16 v[8:11], v[160:163], v[218:221], v[8:11]
	v_mfma_f32_16x16x32_bf16 v[60:63], v[156:159], v[198:201], v[60:63]
	v_mfma_f32_16x16x32_bf16 v[56:59], v[164:167], v[198:201], v[56:59]
	v_mfma_f32_16x16x32_bf16 v[44:47], v[156:159], v[206:209], v[44:47]
	v_mfma_f32_16x16x32_bf16 v[40:43], v[164:167], v[206:209], v[40:43]
	v_mfma_f32_16x16x32_bf16 v[28:31], v[156:159], v[214:217], v[28:31]
	v_mfma_f32_16x16x32_bf16 v[24:27], v[164:167], v[214:217], v[24:27]
	v_mfma_f32_16x16x32_bf16 v[12:15], v[156:159], v[222:225], v[12:15]
	v_mfma_f32_16x16x32_bf16 v[8:11], v[164:167], v[222:225], v[8:11]
	s_setprio 0
	s_setprio 1
	v_mfma_f32_16x16x32_bf16 v[52:55], v[168:171], v[194:197], v[52:55]
	v_mfma_f32_16x16x32_bf16 v[48:51], v[176:179], v[194:197], v[48:51]
	v_mfma_f32_16x16x32_bf16 v[36:39], v[168:171], v[202:205], v[36:39]
	v_mfma_f32_16x16x32_bf16 v[32:35], v[176:179], v[202:205], v[32:35]
	v_mfma_f32_16x16x32_bf16 v[20:23], v[168:171], v[210:213], v[20:23]
	v_mfma_f32_16x16x32_bf16 v[16:19], v[176:179], v[210:213], v[16:19]
	v_mfma_f32_16x16x32_bf16 v[4:7], v[168:171], v[218:221], v[4:7]
	v_mfma_f32_16x16x32_bf16 v[0:3], v[176:179], v[218:221], v[0:3]
	v_mfma_f32_16x16x32_bf16 v[52:55], v[172:175], v[198:201], v[52:55]
	v_mfma_f32_16x16x32_bf16 v[48:51], v[190:193], v[198:201], v[48:51]
	v_mfma_f32_16x16x32_bf16 v[36:39], v[172:175], v[206:209], v[36:39]
	v_mfma_f32_16x16x32_bf16 v[32:35], v[190:193], v[206:209], v[32:35]
	v_mfma_f32_16x16x32_bf16 v[20:23], v[172:175], v[214:217], v[20:23]
	v_mfma_f32_16x16x32_bf16 v[16:19], v[190:193], v[214:217], v[16:19]
	v_mfma_f32_16x16x32_bf16 v[4:7], v[172:175], v[222:225], v[4:7]
	v_mfma_f32_16x16x32_bf16 v[0:3], v[190:193], v[222:225], v[0:3]
	s_barrier
	s_setprio 0
	s_sleep 2
	s_add_i32 s50, s50, 2
	s_add_u32 s30, s30, 0x100
	s_addc_u32 s31, s31, 0
	s_add_u32 s48, s48, 0x100
	s_addc_u32 s49, s49, 0
	s_cmp_gt_u32 s50, 29
	s_cbranch_scc0 .LBB0_621
	s_and_b64 vcc, exec, s[10:11]
	s_cbranch_vccz .LBB0_624
	s_barrier

; #define PG8_STAGE(bufoff, gbase, voff) do { _Pragma("unroll") for (int _i = 0; _i < 2; ++_i) \
;         __builtin_amdgcn_global_load_lds((const unsigned*)((const char*)(gbase) + (voff)[_i]), (PG8_LAS unsigned*)(lds + (bufoff) + ldsw + _i * 8192), 16, 0, 0); } while (0)
; #define PG8_LDA(dst, b, h) do { _Pragma("unroll") for (int m = 0; m < 4; ++m) _Pragma("unroll") for (int k = 0; k < 2; ++k) dst[m][k] = *(const PG8_LAS bf16x8*)(lds + PG8_SA(b, h) + aoff + m * 2048 + k * 1024); } while (0)
; #define PG8_LDB(dst, b, h) do { _Pragma("unroll") for (int n = 0; n < 2; ++n) _Pragma("unroll") for (int k = 0; k < 2; ++k) dst[n][k] = *(const PG8_LAS bf16x8*)(lds + PG8_SB(b, h) + boff + n * 2048 + k * 1024); } while (0)
; #define PG8_MMA(ai, bj, At, Bt) do { __builtin_amdgcn_s_setprio(1); _Pragma("unroll") for (int m = 0; m < 4; ++m) _Pragma("unroll") for (int n = 0; n < 2; ++n) _Pragma("unroll") for (int k = 0; k < 2; ++k) \
;         acc[ai][bj][m][n] = __builtin_amdgcn_mfma_f32_16x16x32_bf16(Bt[n][k], At[m][k], acc[ai][bj][m][n], 0, 0, 0); __builtin_amdgcn_s_setprio(0); } while (0)
; #define PG8_WAIT_V(n) asm volatile("s_waitcnt vmcnt(" #n ")" ::: "memory")
; #define PG8_WAIT_L(n) asm volatile("s_waitcnt lgkmcnt(" #n ")" ::: "memory")
; template <class Epi, class Sched, bool ALIGN_EPI = false, bool SP2 = false>
; __device__ __forceinline__ void gemm_phase(PG8_LAS unsigned char* lds, const Gemm g, const Sched& S, const Epi& E) {
;     ...
;             const bool last = (t == nt - 2);
;             const char* a1 = cA + (size_t)(t + 1) * kstep;
;             const char* a2 = last ? nA : cA + (size_t)(t + 2) * kstep; const char* b2 = last ? nB : cB + (size_t)(t + 2) * kstep;
;             const char* a3 = a2 + kstep; const char* b3 = b2 + kstep;
;             if (last && has_next) S.a_ready(nxt);
;             if constexpr (SP2) {
;             PG8_LDB(B0, 0, 0); PG8_LDB(B1, 0, 1); PG8_SCHED; PG8_LDA(At, 0, 0); PG8_STAGE(PG8_SA(1, 1), a1 + hstep, voffA);
;             PG8_WAIT_V(8); PG8_WAIT_L(0); PG8_BAR; PG8_MMA(0, 0, At, B0); PG8_MMA(0, 1, At, B1); PG8_BAR; PG8_SCHED;
;             PG8_LDA(At, 0, 1); PG8_STAGE(PG8_SB(0, 0), b2, voffB); PG8_STAGE(PG8_SB(0, 1), b2 + hstep, voffB); PG8_STAGE(PG8_SA(0, 0), a2, voffA);
;             PG8_WAIT_V(8); PG8_WAIT_L(0); PG8_BAR; PG8_MMA(1, 0, At, B0); PG8_MMA(1, 1, At, B1); PG8_BAR; PG8_SCHED;
.LBB0_649:
	ds_read_b128 v[140:143], v165
	ds_read_b128 v[176:179], v165 offset:1024
	ds_read_b128 v[180:183], v165 offset:2048
	ds_read_b128 v[184:187], v165 offset:3072
	ds_read_b128 v[188:191], v166
	ds_read_b128 v[192:195], v166 offset:1024
	ds_read_b128 v[196:199], v166 offset:2048
	ds_read_b128 v[200:203], v166 offset:3072
	s_add_u32 s40, s8, 0xffea0080
	s_addc_u32 s41, s9, -1
	s_cmpk_eq_i32 s65, 0x54
	s_cselect_b32 s43, s37, s41
	s_cselect_b32 s42, s36, s40
	s_cselect_b32 s41, s11, s39
	s_cselect_b32 s40, s10, s38
	s_mov_b32 m0, s54
	v_lshl_add_u64 v[144:145], s[8:9], 0, v[136:137]
	ds_read_b128 v[204:207], v167
	ds_read_b128 v[208:211], v167 offset:1024
	ds_read_b128 v[212:215], v167 offset:2048
	ds_read_b128 v[216:219], v167 offset:3072
	ds_read_b128 v[220:223], v167 offset:4096
	ds_read_b128 v[224:227], v167 offset:5120
	ds_read_b128 v[228:231], v167 offset:6144
	ds_read_b128 v[232:235], v167 offset:7168
	global_load_lds_dwordx4 v[144:145], off
	v_lshl_add_u64 v[144:145], s[8:9], 0, v[138:139]
	s_mov_b32 m0, s55
	s_nop 0
	global_load_lds_dwordx4 v[144:145], off
	s_waitcnt vmcnt(8)
	s_waitcnt lgkmcnt(0)
	s_setprio 1
	s_barrier
	v_mfma_f32_16x16x32_bf16 v[124:127], v[140:143], v[204:207], v[124:127]
	v_mfma_f32_16x16x32_bf16 v[120:123], v[180:183], v[204:207], v[120:123]
	v_mfma_f32_16x16x32_bf16 v[108:111], v[140:143], v[212:215], v[108:111]
	v_mfma_f32_16x16x32_bf16 v[104:107], v[180:183], v[212:215], v[104:107]
	v_mfma_f32_16x16x32_bf16 v[92:95], v[140:143], v[220:223], v[92:95]
	v_mfma_f32_16x16x32_bf16 v[88:91], v[180:183], v[220:223], v[88:91]
	v_mfma_f32_16x16x32_bf16 v[76:79], v[140:143], v[228:231], v[76:79]
	v_mfma_f32_16x16x32_bf16 v[72:75], v[180:183], v[228:231], v[72:75]
	v_mfma_f32_16x16x32_bf16 v[124:127], v[176:179], v[208:211], v[124:127]
	v_mfma_f32_16x16x32_bf16 v[120:123], v[184:187], v[208:211], v[120:123]
	v_mfma_f32_16x16x32_bf16 v[108:111], v[176:179], v[216:219], v[108:111]
	v_mfma_f32_16x16x32_bf16 v[104:107], v[184:187], v[216:219], v[104:107]
	v_mfma_f32_16x16x32_bf16 v[92:95], v[176:179], v[224:227], v[92:95]
	v_mfma_f32_16x16x32_bf16 v[88:91], v[184:187], v[224:227], v[88:91]
	v_mfma_f32_16x16x32_bf16 v[76:79], v[176:179], v[232:235], v[76:79]
	v_mfma_f32_16x16x32_bf16 v[72:75], v[184:187], v[232:235], v[72:75]
	s_setprio 0
	s_setprio 1
	v_mfma_f32_16x16x32_bf16 v[116:119], v[188:191], v[204:207], v[116:119]
	v_mfma_f32_16x16x32_bf16 v[112:115], v[196:199], v[204:207], v[112:115]
	v_mfma_f32_16x16x32_bf16 v[100:103], v[188:191], v[212:215], v[100:103]
	v_mfma_f32_16x16x32_bf16 v[96:99], v[196:199], v[212:215], v[96:99]
	v_mfma_f32_16x16x32_bf16 v[84:87], v[188:191], v[220:223], v[84:87]
	v_mfma_f32_16x16x32_bf16 v[80:83], v[196:199], v[220:223], v[80:83]
	v_mfma_f32_16x16x32_bf16 v[68:71], v[188:191], v[228:231], v[68:71]
	v_mfma_f32_16x16x32_bf16 v[64:67], v[196:199], v[228:231], v[64:67]
	v_mfma_f32_16x16x32_bf16 v[116:119], v[192:195], v[208:211], v[116:119]
	v_mfma_f32_16x16x32_bf16 v[112:115], v[200:203], v[208:211], v[112:115]
	v_mfma_f32_16x16x32_bf16 v[100:103], v[192:195], v[216:219], v[100:103]
	v_mfma_f32_16x16x32_bf16 v[96:99], v[200:203], v[216:219], v[96:99]
	v_mfma_f32_16x16x32_bf16 v[84:87], v[192:195], v[224:227], v[84:87]
	v_mfma_f32_16x16x32_bf16 v[80:83], v[200:203], v[224:227], v[80:83]
	v_mfma_f32_16x16x32_bf16 v[68:71], v[192:195], v[232:235], v[68:71]
	v_mfma_f32_16x16x32_bf16 v[64:67], v[200:203], v[232:235], v[64:67]
	s_barrier
	s_setprio 0
	s_sleep 2
	s_mov_b32 m0, s56
	v_lshl_add_u64 v[144:145], s[40:41], 0, v[128:129]
	s_add_u32 s66, s40, 0x160000
	ds_read_b128 v[204:207], v167 offset:16384
	ds_read_b128 v[208:211], v167 offset:17408
	ds_read_b128 v[212:215], v167 offset:18432
	ds_read_b128 v[216:219], v167 offset:19456
	ds_read_b128 v[220:223], v167 offset:20480
	ds_read_b128 v[224:227], v167 offset:21504
	ds_read_b128 v[228:231], v167 offset:22528
	ds_read_b128 v[232:235], v167 offset:23552
	global_load_lds_dwordx4 v[144:145], off
	v_lshl_add_u64 v[236:237], s[40:41], 0, v[130:131]
	s_mov_b32 m0, s57
	s_addc_u32 s67, s41, 0
	global_load_lds_dwordx4 v[236:237], off
	v_lshl_add_u64 v[238:239], s[66:67], 0, v[128:129]
	s_mov_b32 m0, s58
	v_lshl_add_u64 v[240:241], s[42:43], 0, v[130:131]
	global_load_lds_dwordx4 v[238:239], off
	v_lshl_add_u64 v[238:239], s[66:67], 0, v[130:131]
	s_mov_b32 m0, s59
	s_nop 0
	global_load_lds_dwordx4 v[238:239], off
	v_lshl_add_u64 v[238:239], s[42:43], 0, v[128:129]
	s_mov_b32 m0, s33
	s_nop 0
	global_load_lds_dwordx4 v[238:239], off
	s_mov_b32 m0, s46
	s_nop 0
	global_load_lds_dwordx4 v[240:241], off
	s_waitcnt vmcnt(8)
	s_waitcnt lgkmcnt(0)
	s_setprio 1
	s_barrier
; #define PG8_STAGE(bufoff, gbase, voff) do { _Pragma("unroll") for (int _i = 0; _i < 2; ++_i) \
;         __builtin_amdgcn_global_load_lds((const unsigned*)((const char*)(gbase) + (voff)[_i]), (PG8_LAS unsigned*)(lds + (bufoff) + ldsw + _i * 8192), 16, 0, 0); } while (0)
; #define PG8_LDA(dst, b, h) do { _Pragma("unroll") for (int m = 0; m < 4; ++m) _Pragma("unroll") for (int k = 0; k < 2; ++k) dst[m][k] = *(const PG8_LAS bf16x8*)(lds + PG8_SA(b, h) + aoff + m * 2048 + k * 1024); } while (0)
; #define PG8_LDB(dst, b, h) do { _Pragma("unroll") for (int n = 0; n < 2; ++n) _Pragma("unroll") for (int k = 0; k < 2; ++k) dst[n][k] = *(const PG8_LAS bf16x8*)(lds + PG8_SB(b, h) + boff + n * 2048 + k * 1024); } while (0)
; #define PG8_MMA(ai, bj, At, Bt) do { __builtin_amdgcn_s_setprio(1); _Pragma("unroll") for (int m = 0; m < 4; ++m) _Pragma("unroll") for (int n = 0; n < 2; ++n) _Pragma("unroll") for (int k = 0; k < 2; ++k) \
;         acc[ai][bj][m][n] = __builtin_amdgcn_mfma_f32_16x16x32_bf16(Bt[n][k], At[m][k], acc[ai][bj][m][n], 0, 0, 0); __builtin_amdgcn_s_setprio(0); } while (0)
; #define PG8_WAIT_V(n) asm volatile("s_waitcnt vmcnt(" #n ")" ::: "memory")
; #define PG8_WAIT_L(n) asm volatile("s_waitcnt lgkmcnt(" #n ")" ::: "memory")
; #define PG8_BAR __builtin_amdgcn_s_barrier()
; #define PG8_SCHED __builtin_amdgcn_sched_barrier(0)
; template <class Epi, class Sched, bool ALIGN_EPI = false, bool SP2 = false>
; __device__ __forceinline__ void gemm_phase(PG8_LAS unsigned char* lds, const Gemm g, const Sched& S, const Epi& E) {
;     ...
;             PG8_WAIT_V(8); PG8_WAIT_L(0); PG8_BAR; PG8_MMA(1, 0, At, B0); PG8_MMA(1, 1, At, B1); PG8_BAR; PG8_SCHED;
;             PG8_LDB(B0, 1, 0); PG8_LDB(B1, 1, 1); PG8_SCHED; PG8_LDA(At, 1, 0); PG8_STAGE(PG8_SA(0, 1), a2 + hstep, voffA);
;             PG8_WAIT_V(8); PG8_WAIT_L(0); PG8_BAR; PG8_MMA(0, 0, At, B0); PG8_MMA(0, 1, At, B1); PG8_BAR; PG8_SCHED;
;             PG8_LDA(At, 1, 1); PG8_STAGE(PG8_SB(1, 0), b3, voffB); PG8_STAGE(PG8_SB(1, 1), b3 + hstep, voffB); PG8_STAGE(PG8_SA(1, 0), a3, voffA);
;             PG8_WAIT_V(8); PG8_WAIT_L(0); PG8_BAR; PG8_MMA(1, 0, At, B0); PG8_MMA(1, 1, At, B1); PG8_BAR; PG8_SCHED;
	v_mfma_f32_16x16x32_bf16 v[60:63], v[140:143], v[204:207], v[60:63]
	v_mfma_f32_16x16x32_bf16 v[56:59], v[180:183], v[204:207], v[56:59]
	v_mfma_f32_16x16x32_bf16 v[44:47], v[140:143], v[212:215], v[44:47]
	v_mfma_f32_16x16x32_bf16 v[40:43], v[180:183], v[212:215], v[40:43]
	v_mfma_f32_16x16x32_bf16 v[28:31], v[140:143], v[220:223], v[28:31]
	v_mfma_f32_16x16x32_bf16 v[24:27], v[180:183], v[220:223], v[24:27]
	v_mfma_f32_16x16x32_bf16 v[12:15], v[140:143], v[228:231], v[12:15]
	v_mfma_f32_16x16x32_bf16 v[8:11], v[180:183], v[228:231], v[8:11]
	v_mfma_f32_16x16x32_bf16 v[60:63], v[176:179], v[208:211], v[60:63]
	v_mfma_f32_16x16x32_bf16 v[56:59], v[184:187], v[208:211], v[56:59]
	v_mfma_f32_16x16x32_bf16 v[44:47], v[176:179], v[216:219], v[44:47]
	v_mfma_f32_16x16x32_bf16 v[40:43], v[184:187], v[216:219], v[40:43]
	v_mfma_f32_16x16x32_bf16 v[28:31], v[176:179], v[224:227], v[28:31]
	v_mfma_f32_16x16x32_bf16 v[24:27], v[184:187], v[224:227], v[24:27]
	v_mfma_f32_16x16x32_bf16 v[12:15], v[176:179], v[232:235], v[12:15]
	v_mfma_f32_16x16x32_bf16 v[8:11], v[184:187], v[232:235], v[8:11]
	s_setprio 0
	s_setprio 1
	v_mfma_f32_16x16x32_bf16 v[52:55], v[188:191], v[204:207], v[52:55]
	v_mfma_f32_16x16x32_bf16 v[48:51], v[196:199], v[204:207], v[48:51]
	v_mfma_f32_16x16x32_bf16 v[36:39], v[188:191], v[212:215], v[36:39]
	v_mfma_f32_16x16x32_bf16 v[32:35], v[196:199], v[212:215], v[32:35]
	v_mfma_f32_16x16x32_bf16 v[20:23], v[188:191], v[220:223], v[20:23]
	v_mfma_f32_16x16x32_bf16 v[16:19], v[196:199], v[220:223], v[16:19]
	v_mfma_f32_16x16x32_bf16 v[4:7], v[188:191], v[228:231], v[4:7]
	v_mfma_f32_16x16x32_bf16 v[0:3], v[196:199], v[228:231], v[0:3]
	v_mfma_f32_16x16x32_bf16 v[52:55], v[192:195], v[208:211], v[52:55]
	v_mfma_f32_16x16x32_bf16 v[48:51], v[200:203], v[208:211], v[48:51]
	v_mfma_f32_16x16x32_bf16 v[36:39], v[192:195], v[216:219], v[36:39]
	v_mfma_f32_16x16x32_bf16 v[32:35], v[200:203], v[216:219], v[32:35]
	v_mfma_f32_16x16x32_bf16 v[20:23], v[192:195], v[224:227], v[20:23]
	v_mfma_f32_16x16x32_bf16 v[16:19], v[200:203], v[224:227], v[16:19]
	v_mfma_f32_16x16x32_bf16 v[4:7], v[192:195], v[232:235], v[4:7]
	v_mfma_f32_16x16x32_bf16 v[0:3], v[200:203], v[232:235], v[0:3]
	s_barrier
	s_setprio 0
	s_sleep 2
	s_add_i32 s66, 0, 0x1c000
	v_add_u32_e32 v175, s66, v147
	ds_read_b128 v[140:143], v173
	ds_read_b128 v[176:179], v173 offset:1024
	ds_read_b128 v[180:183], v173 offset:2048
	ds_read_b128 v[184:187], v173 offset:3072
	ds_read_b128 v[188:191], v175
	ds_read_b128 v[192:195], v175 offset:1024
	ds_read_b128 v[196:199], v175 offset:2048
	ds_read_b128 v[200:203], v175 offset:3072
	s_add_u32 s42, s42, 0x160000
	s_addc_u32 s43, s43, 0
	s_mov_b32 m0, s47
	v_lshl_add_u64 v[242:243], s[42:43], 0, v[128:129]
	ds_read_b128 v[204:207], v167 offset:32768
	ds_read_b128 v[208:211], v167 offset:33792
	ds_read_b128 v[212:215], v167 offset:34816
	ds_read_b128 v[216:219], v167 offset:35840
	ds_read_b128 v[220:223], v167 offset:36864
	ds_read_b128 v[224:227], v167 offset:37888
	ds_read_b128 v[228:231], v167 offset:38912
	ds_read_b128 v[232:235], v167 offset:39936
	global_load_lds_dwordx4 v[242:243], off
	v_lshl_add_u64 v[242:243], s[42:43], 0, v[130:131]
	s_mov_b32 m0, s48
	s_nop 0
	global_load_lds_dwordx4 v[242:243], off
	s_waitcnt vmcnt(8)
	s_waitcnt lgkmcnt(0)
	s_setprio 1
	s_barrier
	v_mfma_f32_16x16x32_bf16 v[124:127], v[140:143], v[204:207], v[124:127]
	v_mfma_f32_16x16x32_bf16 v[120:123], v[180:183], v[204:207], v[120:123]
	v_mfma_f32_16x16x32_bf16 v[108:111], v[140:143], v[212:215], v[108:111]
	v_mfma_f32_16x16x32_bf16 v[104:107], v[180:183], v[212:215], v[104:107]
	v_mfma_f32_16x16x32_bf16 v[92:95], v[140:143], v[220:223], v[92:95]
	v_mfma_f32_16x16x32_bf16 v[88:91], v[180:183], v[220:223], v[88:91]
	v_mfma_f32_16x16x32_bf16 v[76:79], v[140:143], v[228:231], v[76:79]
	v_mfma_f32_16x16x32_bf16 v[72:75], v[180:183], v[228:231], v[72:75]
	v_mfma_f32_16x16x32_bf16 v[124:127], v[176:179], v[208:211], v[124:127]
	v_mfma_f32_16x16x32_bf16 v[120:123], v[184:187], v[208:211], v[120:123]
	v_mfma_f32_16x16x32_bf16 v[108:111], v[176:179], v[216:219], v[108:111]
	v_mfma_f32_16x16x32_bf16 v[104:107], v[184:187], v[216:219], v[104:107]
	v_mfma_f32_16x16x32_bf16 v[92:95], v[176:179], v[224:227], v[92:95]
	v_mfma_f32_16x16x32_bf16 v[88:91], v[184:187], v[224:227], v[88:91]
	v_mfma_f32_16x16x32_bf16 v[76:79], v[176:179], v[232:235], v[76:79]
	v_mfma_f32_16x16x32_bf16 v[72:75], v[184:187], v[232:235], v[72:75]
	s_setprio 0
	s_setprio 1
	v_mfma_f32_16x16x32_bf16 v[116:119], v[188:191], v[204:207], v[116:119]
	v_mfma_f32_16x16x32_bf16 v[112:115], v[196:199], v[204:207], v[112:115]
	v_mfma_f32_16x16x32_bf16 v[100:103], v[188:191], v[212:215], v[100:103]
	v_mfma_f32_16x16x32_bf16 v[96:99], v[196:199], v[212:215], v[96:99]
	v_mfma_f32_16x16x32_bf16 v[84:87], v[188:191], v[220:223], v[84:87]
	v_mfma_f32_16x16x32_bf16 v[80:83], v[196:199], v[220:223], v[80:83]
	v_mfma_f32_16x16x32_bf16 v[68:71], v[188:191], v[228:231], v[68:71]
	v_mfma_f32_16x16x32_bf16 v[64:67], v[196:199], v[228:231], v[64:67]
	v_mfma_f32_16x16x32_bf16 v[116:119], v[192:195], v[208:211], v[116:119]
	v_mfma_f32_16x16x32_bf16 v[112:115], v[200:203], v[208:211], v[112:115]
	v_mfma_f32_16x16x32_bf16 v[100:103], v[192:195], v[216:219], v[100:103]
	v_mfma_f32_16x16x32_bf16 v[96:99], v[200:203], v[216:219], v[96:99]
	v_mfma_f32_16x16x32_bf16 v[84:87], v[192:195], v[224:227], v[84:87]
	v_mfma_f32_16x16x32_bf16 v[80:83], v[200:203], v[224:227], v[80:83]
	v_mfma_f32_16x16x32_bf16 v[68:71], v[192:195], v[232:235], v[68:71]
	v_mfma_f32_16x16x32_bf16 v[64:67], v[200:203], v[232:235], v[64:67]
	s_barrier
; #define PG8_STAGE(bufoff, gbase, voff) do { _Pragma("unroll") for (int _i = 0; _i < 2; ++_i) \
;         __builtin_amdgcn_global_load_lds((const unsigned*)((const char*)(gbase) + (voff)[_i]), (PG8_LAS unsigned*)(lds + (bufoff) + ldsw + _i * 8192), 16, 0, 0); } while (0)
; #define PG8_LDA(dst, b, h) do { _Pragma("unroll") for (int m = 0; m < 4; ++m) _Pragma("unroll") for (int k = 0; k < 2; ++k) dst[m][k] = *(const PG8_LAS bf16x8*)(lds + PG8_SA(b, h) + aoff + m * 2048 + k * 1024); } while (0)
; #define PG8_MMA(ai, bj, At, Bt) do { __builtin_amdgcn_s_setprio(1); _Pragma("unroll") for (int m = 0; m < 4; ++m) _Pragma("unroll") for (int n = 0; n < 2; ++n) _Pragma("unroll") for (int k = 0; k < 2; ++k) \
;         acc[ai][bj][m][n] = __builtin_amdgcn_mfma_f32_16x16x32_bf16(Bt[n][k], At[m][k], acc[ai][bj][m][n], 0, 0, 0); __builtin_amdgcn_s_setprio(0); } while (0)
; #define PG8_WAIT_V(n) asm volatile("s_waitcnt vmcnt(" #n ")" ::: "memory")
; #define PG8_WAIT_L(n) asm volatile("s_waitcnt lgkmcnt(" #n ")" ::: "memory")
; #define PG8_BAR __builtin_amdgcn_s_barrier()
; #define PG8_SCHED __builtin_amdgcn_sched_barrier(0)
; template <class Epi, class Sched, bool ALIGN_EPI = false, bool SP2 = false>
; __device__ __forceinline__ void gemm_phase(PG8_LAS unsigned char* lds, const Gemm g, const Sched& S, const Epi& E) {
;     ...
;         for (int t = 0; t < nt; t += 2) {
;     ...
;             PG8_LDA(At, 1, 1); PG8_STAGE(PG8_SB(1, 0), b3, voffB); PG8_STAGE(PG8_SB(1, 1), b3 + hstep, voffB); PG8_STAGE(PG8_SA(1, 0), a3, voffA);
;             PG8_WAIT_V(8); PG8_WAIT_L(0); PG8_BAR; PG8_MMA(1, 0, At, B0); PG8_MMA(1, 1, At, B1); PG8_BAR; PG8_SCHED;
	s_setprio 0
	s_sleep 2
	s_add_i32 s42, s60, s45
	v_lshl_add_u64 v[144:145], v[144:145], 0, s[18:19]
	s_mov_b32 m0, s42
	ds_read_b128 v[204:207], v167 offset:49152
	ds_read_b128 v[208:211], v167 offset:50176
	ds_read_b128 v[212:215], v167 offset:51200
	ds_read_b128 v[216:219], v167 offset:52224
	ds_read_b128 v[220:223], v167 offset:53248
	ds_read_b128 v[224:227], v167 offset:54272
	ds_read_b128 v[228:231], v167 offset:55296
	ds_read_b128 v[232:235], v167 offset:56320
	global_load_lds_dwordx4 v[144:145], off
	s_add_i32 m0, s42, 0x2000
	s_add_u32 s40, s40, 0x160080
	v_lshl_add_u64 v[144:145], v[236:237], 0, s[18:19]
	s_addc_u32 s41, s41, 0
	s_add_i32 s42, s66, s45
	global_load_lds_dwordx4 v[144:145], off
	v_lshl_add_u64 v[144:145], s[40:41], 0, v[128:129]
	s_mov_b32 m0, s42
	s_nop 0
	global_load_lds_dwordx4 v[144:145], off
	v_lshl_add_u64 v[144:145], s[40:41], 0, v[130:131]
	s_add_i32 m0, s42, 0x2000
	s_nop 0
	global_load_lds_dwordx4 v[144:145], off
	v_lshl_add_u64 v[144:145], v[238:239], 0, s[18:19]
	s_mov_b32 m0, s51
	s_nop 0
	global_load_lds_dwordx4 v[144:145], off
	v_lshl_add_u64 v[144:145], v[240:241], 0, s[18:19]
	s_mov_b32 m0, s52
	s_nop 0
	global_load_lds_dwordx4 v[144:145], off
	s_waitcnt vmcnt(8)
	s_waitcnt lgkmcnt(0)
	s_setprio 1
	s_barrier
	v_mfma_f32_16x16x32_bf16 v[60:63], v[140:143], v[204:207], v[60:63]
	v_mfma_f32_16x16x32_bf16 v[56:59], v[180:183], v[204:207], v[56:59]
	v_mfma_f32_16x16x32_bf16 v[44:47], v[140:143], v[212:215], v[44:47]
	v_mfma_f32_16x16x32_bf16 v[40:43], v[180:183], v[212:215], v[40:43]
	v_mfma_f32_16x16x32_bf16 v[28:31], v[140:143], v[220:223], v[28:31]
	v_mfma_f32_16x16x32_bf16 v[24:27], v[180:183], v[220:223], v[24:27]
	v_mfma_f32_16x16x32_bf16 v[12:15], v[140:143], v[228:231], v[12:15]
	v_mfma_f32_16x16x32_bf16 v[8:11], v[180:183], v[228:231], v[8:11]
	v_mfma_f32_16x16x32_bf16 v[60:63], v[176:179], v[208:211], v[60:63]
	v_mfma_f32_16x16x32_bf16 v[56:59], v[184:187], v[208:211], v[56:59]
	v_mfma_f32_16x16x32_bf16 v[44:47], v[176:179], v[216:219], v[44:47]
	v_mfma_f32_16x16x32_bf16 v[40:43], v[184:187], v[216:219], v[40:43]
	v_mfma_f32_16x16x32_bf16 v[28:31], v[176:179], v[224:227], v[28:31]
	v_mfma_f32_16x16x32_bf16 v[24:27], v[184:187], v[224:227], v[24:27]
	v_mfma_f32_16x16x32_bf16 v[12:15], v[176:179], v[232:235], v[12:15]
	v_mfma_f32_16x16x32_bf16 v[8:11], v[184:187], v[232:235], v[8:11]
	s_setprio 0
	s_setprio 1
	v_mfma_f32_16x16x32_bf16 v[52:55], v[188:191], v[204:207], v[52:55]
	v_mfma_f32_16x16x32_bf16 v[48:51], v[196:199], v[204:207], v[48:51]
	v_mfma_f32_16x16x32_bf16 v[36:39], v[188:191], v[212:215], v[36:39]
	v_mfma_f32_16x16x32_bf16 v[32:35], v[196:199], v[212:215], v[32:35]
	v_mfma_f32_16x16x32_bf16 v[20:23], v[188:191], v[220:223], v[20:23]
	v_mfma_f32_16x16x32_bf16 v[16:19], v[196:199], v[220:223], v[16:19]
	v_mfma_f32_16x16x32_bf16 v[4:7], v[188:191], v[228:231], v[4:7]
	v_mfma_f32_16x16x32_bf16 v[0:3], v[196:199], v[228:231], v[0:3]
	v_mfma_f32_16x16x32_bf16 v[52:55], v[192:195], v[208:211], v[52:55]
	v_mfma_f32_16x16x32_bf16 v[48:51], v[200:203], v[208:211], v[48:51]
	v_mfma_f32_16x16x32_bf16 v[36:39], v[192:195], v[216:219], v[36:39]
	v_mfma_f32_16x16x32_bf16 v[32:35], v[200:203], v[216:219], v[32:35]
	v_mfma_f32_16x16x32_bf16 v[20:23], v[192:195], v[224:227], v[20:23]
	v_mfma_f32_16x16x32_bf16 v[16:19], v[200:203], v[224:227], v[16:19]
	v_mfma_f32_16x16x32_bf16 v[4:7], v[192:195], v[232:235], v[4:7]
	v_mfma_f32_16x16x32_bf16 v[0:3], v[200:203], v[232:235], v[0:3]
	s_barrier
	s_setprio 0
	s_sleep 2
	s_add_i32 s65, s65, 2
	s_add_u32 s8, s8, 0x100
	s_addc_u32 s9, s9, 0
	s_add_u32 s38, s38, 0x100
	s_addc_u32 s39, s39, 0
	s_cmpk_gt_u32 s65, 0x55
	s_cbranch_scc0 .LBB0_649
	s_and_b64 vcc, exec, s[22:23]
	s_cbranch_vccz .LBB0_652
	s_barrier
